# weight conversions moved into idle workgroup time: w_in and w_out from P0 into the FFN1 GEMM tail, FFN2 weights from P10 into the scan-phase tail (hand-written conversion block), RWKV scan v2
# speedup vs baseline: 1.0208x; 1.0208x over previous
; __device__ __forceinline__ TDesc tconv_desc(const float* wg, const float* wu, const float* wd, const float* win, const float* wout, unsigned char* ws, int i) {
;     ...
;     if (i < 704) { d.W = wg; d.Bt = (bf16_t*)(ws + WS_WGU); d.K = 1024; d.N = DFF; mode = 1; }
;     else if (i < 1408) { d.W = wu; d.Bt = (bf16_t*)(ws + WS_WGU); d.K = 1024; d.N = DFF; mode = 2; tile = i - 704; }
;     else if (i < 2112) { d.W = wd; d.Bt = (bf16_t*)(ws + WS_WD); d.K = DFF; d.N = 1024; tile = i - 1408; }
;     else if (i < 3072) { d.W = win; d.Bt = (bf16_t*)(ws + WS_WIN); d.K = 1024; d.N = NCOLS; tile = i - 2112; }
;     else { d.W = wout; d.Bt = (bf16_t*)(ws + WS_WOUT); d.K = 1024; d.N = 1024; tile = i - 3072; }
; __device__ __forceinline__ void tconv_list(const float* wg, const float* wu, const float* wd, const float* win, const float* wout, unsigned char* ws, const int ntiles, LAS float* t, const int wv) {
;     ...
;     for (; i < ntiles; i += G) {
;         const TDesc d = tconv_desc(wg, wu, wd, win, wout, ws, i);
;         { const TDesc dn = tconv_desc(wg, wu, wd, win, wout, ws, i + G < ntiles ? i + G : i);
; #pragma unroll
;             for (int e = 0; e < 8; ++e) { const int idx = e * 512 + tid, r = idx >> 6, c = idx & 63; nxt[e] = __builtin_nontemporal_load(dn.W + (size_t)(dn.k0 + r) * dn.N + dn.n0 + c); } }
.LBB0_72:
	s_add_i32 s4, s7, s50
	s_cmpk_gt_i32 s4, 0x83f
	s_cselect_b64 s[30:31], -1, 0
	s_cmpk_lt_i32 s4, 0x840
	s_cselect_b32 s7, s4, s7
	s_cmpk_lt_i32 s7, 0x2c0
	s_cbranch_scc1 .LBB0_77
	s_cmpk_gt_u32 s7, 0x57f
	s_cbranch_scc0 .LBB0_78
	s_cmpk_gt_u32 s7, 0x83f
	s_cbranch_scc0 .LBB0_79
	s_cmpk_gt_u32 s7, 0xbff
	s_cbranch_scc0 .LBB0_80
	s_add_i32 s44, s7, 0xfffff400
	s_mov_b64 s[38:39], s[18:19]
	s_mov_b64 s[36:37], 0x400
	s_cbranch_execz .LBB0_81
	s_branch .LBB0_82

; __device__ __forceinline__ int fresh_tid(int wv) { int l; asm volatile("v_mbcnt_lo_u32_b32 %0, -1, 0\n\tv_mbcnt_hi_u32_b32 %0, -1, %0" : "=v"(l)); return wv * 64 + l; }
; #define LAS __attribute__((address_space(3)))
; __device__ __forceinline__ TDesc tconv_desc(const float* wg, const float* wu, const float* wd, const float* win, const float* wout, unsigned char* ws, int i) {
;     TDesc d; int mode = 0, tile = i;
;     if (i < 704) { d.W = wg; d.Bt = (bf16_t*)(ws + WS_WGU); d.K = 1024; d.N = DFF; mode = 1; }
;     else if (i < 1408) { d.W = wu; d.Bt = (bf16_t*)(ws + WS_WGU); d.K = 1024; d.N = DFF; mode = 2; tile = i - 704; }
;     else if (i < 2112) { d.W = wd; d.Bt = (bf16_t*)(ws + WS_WD); d.K = DFF; d.N = 1024; tile = i - 1408; }
;     else if (i < 3072) { d.W = win; d.Bt = (bf16_t*)(ws + WS_WIN); d.K = 1024; d.N = NCOLS; tile = i - 2112; }
;     else { d.W = wout; d.Bt = (bf16_t*)(ws + WS_WOUT); d.K = 1024; d.N = 1024; tile = i - 3072; }
;     const int nkt = d.K / 64; const int kt = tile % nkt, nt = tile / nkt; d.k0 = kt * 64; d.n0 = nt * 64;
;     d.brow0 = mode == 0 ? d.n0 : ((d.n0 >> 7) * 256 + (d.n0 & 127) + (mode == 2 ? 128 : 0));
;     return d;
; }
; __device__ __forceinline__ void tconv_list(const float* wg, const float* wu, const float* wd, const float* win, const float* wout, unsigned char* ws, const int ntiles, LAS float* t, const int wv) {
;     const int tid = fresh_tid(wv); const int G = gridDim.x;
;     float cur[8], nxt[8];
;     int i = blockIdx.x;
;     if (i < ntiles) { const TDesc d = tconv_desc(wg, wu, wd, win, wout, ws, i);
; #pragma unroll
;         for (int e = 0; e < 8; ++e) { const int idx = e * 512 + tid, r = idx >> 6, c = idx & 63; cur[e] = __builtin_nontemporal_load(d.W + (size_t)(d.k0 + r) * d.N + d.n0 + c); } }
;     for (; i < ntiles; i += G) {
;         const TDesc d = tconv_desc(wg, wu, wd, win, wout, ws, i);
;         { const TDesc dn = tconv_desc(wg, wu, wd, win, wout, ws, i + G < ntiles ? i + G : i);
; #pragma unroll
;             for (int e = 0; e < 8; ++e) { const int idx = e * 512 + tid, r = idx >> 6, c = idx & 63; nxt[e] = __builtin_nontemporal_load(dn.W + (size_t)(dn.k0 + r) * dn.N + dn.n0 + c); } }
.LBB0_163:
	s_cmp_lt_u32 s2, 172
	s_cbranch_scc1 .Ltc1_skip
	v_writelane_b32 v40, s4, 4
	v_writelane_b32 v40, s5, 5
	v_writelane_b32 v40, s6, 6
	v_writelane_b32 v40, s7, 7
	v_writelane_b32 v40, s8, 8
	v_writelane_b32 v40, s9, 9
	v_writelane_b32 v40, s10, 10
	v_writelane_b32 v40, s11, 11
	v_writelane_b32 v40, s12, 12
	v_writelane_b32 v40, s13, 13
	v_writelane_b32 v40, s14, 14
	v_writelane_b32 v40, s15, 15
	v_writelane_b32 v40, s16, 16
	v_writelane_b32 v40, s17, 17
	v_writelane_b32 v40, s18, 18
	v_writelane_b32 v40, s19, 19
	v_writelane_b32 v40, s20, 20
	v_writelane_b32 v40, s21, 21
	v_writelane_b32 v40, s22, 22
	v_writelane_b32 v40, s23, 23
	v_writelane_b32 v40, s24, 24
	v_writelane_b32 v40, s25, 25
	v_writelane_b32 v40, s26, 26
	v_writelane_b32 v40, s27, 27
	v_writelane_b32 v40, s28, 28
	v_writelane_b32 v40, s29, 29
	v_writelane_b32 v40, s30, 30
	v_writelane_b32 v40, s31, 31
	s_load_dwordx2 s[24:25], s[0:1], 0xd8
	s_load_dwordx2 s[26:27], s[0:1], 0xd0
	s_load_dwordx2 s[18:19], s[0:1], 0x48
	s_load_dwordx2 s[20:21], s[0:1], 0xb0
	v_mbcnt_lo_u32_b32 v0, -1, 0
	v_mbcnt_hi_u32_b32 v0, -1, v0
	s_lshr_b32 s28, s33, 6
	v_lshlrev_b32_e32 v1, 2, v0
	v_lshrrev_b32_e32 v2, 5, v0
	v_and_b32_e32 v3, 31, v0
	s_mul_i32 s7, s28, 260
	v_add_u32_e32 v5, s7, v1
	v_mul_u32_u24_e32 v6, 0x208, v3
	s_lshl_b32 s7, s28, 3
	v_lshl_add_u32 v6, v2, 2, v6
	v_add_u32_e32 v6, s7, v6
	v_lshlrev_b32_e32 v3, 2, v3
	s_sub_u32 s4, s2, 172
	s_waitcnt lgkmcnt(0)
	s_cmp_lt_u32 s4, 960
	s_cbranch_scc0 .Ltc1_seg1_0
	s_mov_b32 s7, s4
	s_and_b32 s8, s7, 15
	s_lshr_b32 s9, s7, 4
	s_mul_i32 s7, s8, 983040
	s_lshl_b32 s29, s9, 8
	s_add_u32 s7, s7, s29
	s_mul_i32 s29, s28, 15360
	s_add_u32 s7, s7, s29
	s_add_u32 s10, s18, s7
	s_addc_u32 s11, s19, 0
	s_lshl_b32 s7, s9, 6
	s_mul_i32 s7, s7, 2048
	s_lshl_b32 s29, s8, 7
	s_add_u32 s7, s7, s29
	s_mul_i32 s29, s28, 4096
	s_add_u32 s7, s7, s29
	s_add_u32 s12, s24, 0x3c4800
	s_addc_u32 s13, s25, 0
	s_add_u32 s12, s12, s7
	s_addc_u32 s13, s13, 0
	s_mov_b32 s14, 122880
	s_mov_b32 s15, 32768
	s_movk_i32 s16, 2048
	s_branch .Ltc1_segend_0
.Ltc1_seg1_0:
	s_sub_u32 s7, s4, 960
	s_and_b32 s8, s7, 15
	s_lshr_b32 s9, s7, 4
	s_mul_i32 s7, s8, 262144
	s_lshl_b32 s29, s9, 8
	s_add_u32 s7, s7, s29
	s_mul_i32 s29, s28, 4096
	s_add_u32 s7, s7, s29
	s_add_u32 s10, s20, s7
	s_addc_u32 s11, s21, 0
	s_lshl_b32 s7, s9, 6
	s_mul_i32 s7, s7, 2048
	s_lshl_b32 s29, s8, 7
	s_add_u32 s7, s7, s29
	s_mul_i32 s29, s28, 4096
	s_add_u32 s7, s7, s29
	s_add_u32 s12, s24, 0x1c4800
	s_addc_u32 s13, s25, 0
	s_add_u32 s12, s12, s7
	s_addc_u32 s13, s13, 0
	s_mov_b32 s14, 32768
	s_mov_b32 s15, 32768
	s_movk_i32 s16, 2048
.Ltc1_segend_0:
	s_mov_b32 s17, s15
	s_mov_b32 s30, s16
	s_mov_b64 s[8:9], s[12:13]
	global_load_dword v8, v1, s[10:11] nt
	s_add_u32 s10, s10, s14
	s_addc_u32 s11, s11, 0
	global_load_dword v9, v1, s[10:11] nt
	s_add_u32 s10, s10, s14
	s_addc_u32 s11, s11, 0
	global_load_dword v10, v1, s[10:11] nt
	s_add_u32 s10, s10, s14
	s_addc_u32 s11, s11, 0
	global_load_dword v11, v1, s[10:11] nt
	s_add_u32 s10, s10, s14
	s_addc_u32 s11, s11, 0
	global_load_dword v12, v1, s[10:11] nt
	s_add_u32 s10, s10, s14
	s_addc_u32 s11, s11, 0
	global_load_dword v13, v1, s[10:11] nt
	s_add_u32 s10, s10, s14
	s_addc_u32 s11, s11, 0
	global_load_dword v14, v1, s[10:11] nt
	s_add_u32 s10, s10, s14
	s_addc_u32 s11, s11, 0
	global_load_dword v15, v1, s[10:11] nt
.Ltc1_loop:
	s_add_u32 s4, s4, 84
	s_cmp_lt_u32 s4, 1216
	s_cselect_b32 s31, 1, 0
	s_cbranch_scc0 .Ltc1_nonexta
	v_writelane_b32 v40, s8, 32
	v_writelane_b32 v40, s9, 33
	s_cmp_lt_u32 s4, 960
	s_cbranch_scc0 .Ltc1_seg1_1
	s_mov_b32 s7, s4
	s_and_b32 s8, s7, 15
	s_lshr_b32 s9, s7, 4
	s_mul_i32 s7, s8, 983040
	s_lshl_b32 s29, s9, 8
	s_add_u32 s7, s7, s29
	s_mul_i32 s29, s28, 15360
	s_add_u32 s7, s7, s29
	s_add_u32 s10, s18, s7
	s_addc_u32 s11, s19, 0
	s_lshl_b32 s7, s9, 6
	s_mul_i32 s7, s7, 2048
	s_lshl_b32 s29, s8, 7
	s_add_u32 s7, s7, s29
	s_mul_i32 s29, s28, 4096
	s_add_u32 s7, s7, s29
	s_add_u32 s12, s24, 0x3c4800
	s_addc_u32 s13, s25, 0
	s_add_u32 s12, s12, s7
	s_addc_u32 s13, s13, 0
	s_mov_b32 s14, 122880
	s_mov_b32 s15, 32768
	s_movk_i32 s16, 2048
	s_branch .Ltc1_segend_1

; __device__ __forceinline__ void tconv_list(const float* wg, const float* wu, const float* wd, const float* win, const float* wout, unsigned char* ws, const int ntiles, LAS float* t, const int wv) {
;     ...
;         { const TDesc dn = tconv_desc(wg, wu, wd, win, wout, ws, i + G < ntiles ? i + G : i);
; #pragma unroll
;             for (int e = 0; e < 8; ++e) { const int idx = e * 512 + tid, r = idx >> 6, c = idx & 63; nxt[e] = __builtin_nontemporal_load(dn.W + (size_t)(dn.k0 + r) * dn.N + dn.n0 + c); } }
.Ltc1_segend_1:
	v_readlane_b32 s8, v40, 32
	v_readlane_b32 s9, v40, 33
	global_load_dword v16, v1, s[10:11] nt
	s_add_u32 s10, s10, s14
	s_addc_u32 s11, s11, 0
	global_load_dword v17, v1, s[10:11] nt
	s_add_u32 s10, s10, s14
	s_addc_u32 s11, s11, 0
	global_load_dword v18, v1, s[10:11] nt
	s_add_u32 s10, s10, s14
	s_addc_u32 s11, s11, 0
	global_load_dword v19, v1, s[10:11] nt
	s_add_u32 s10, s10, s14
	s_addc_u32 s11, s11, 0
	global_load_dword v20, v1, s[10:11] nt
	s_add_u32 s10, s10, s14
	s_addc_u32 s11, s11, 0
	global_load_dword v21, v1, s[10:11] nt
	s_add_u32 s10, s10, s14
	s_addc_u32 s11, s11, 0
	global_load_dword v22, v1, s[10:11] nt
	s_add_u32 s10, s10, s14
	s_addc_u32 s11, s11, 0
	global_load_dword v23, v1, s[10:11] nt
	s_waitcnt vmcnt(8)
	s_branch .Ltc1_havea

; __device__ __forceinline__ unsigned cvt_pk_bf16(float lo, float hi) { const f32x2_t v = {lo, hi}; const bf16x2_t b = __builtin_convertvector(v, bf16x2_t); return __builtin_bit_cast(unsigned, b); }
; __device__ __forceinline__ void tconv_list(const float* wg, const float* wu, const float* wd, const float* win, const float* wout, unsigned char* ws, const int ntiles, LAS float* t, const int wv) {
;     ...
; #pragma unroll
;         for (int e = 0; e < 8; ++e) { const int idx = e * 512 + tid, r = idx >> 6, c = idx & 63; t[r * 65 + c] = cur[e]; }
;         __syncthreads();
; #pragma unroll
;         for (int e = 0; e < 4; ++e) { const int idx = e * 512 + tid, n = idx >> 5, kp = idx & 31;
;             const unsigned w = pg8::cvt_pk_bf16(t[(2 * kp) * 65 + n], t[(2 * kp + 1) * 65 + n]);
;             *(unsigned*)(d.Bt + (size_t)(d.brow0 + n) * d.K + d.k0 + 2 * kp) = w; }
;         __syncthreads();
; #pragma unroll
;         for (int e = 0; e < 8; ++e) cur[e] = nxt[e];
.Ltc1_havea:
	ds_write_b32 v5, v8 offset:0
	ds_write_b32 v5, v9 offset:2080
	ds_write_b32 v5, v10 offset:4160
	ds_write_b32 v5, v11 offset:6240
	ds_write_b32 v5, v12 offset:8320
	ds_write_b32 v5, v13 offset:10400
	ds_write_b32 v5, v14 offset:12480
	ds_write_b32 v5, v15 offset:14560
	v_mad_u32_u24 v4, v2, s30, v3
	s_waitcnt lgkmcnt(0)
	s_barrier
	ds_read2_b32 v[24:25], v6 offset0:0 offset1:65
	ds_read2_b32 v[26:27], v6 offset0:16 offset1:81
	ds_read2_b32 v[28:29], v6 offset0:32 offset1:97
	ds_read2_b32 v[30:31], v6 offset0:48 offset1:113
	s_waitcnt lgkmcnt(3)
	v_cvt_pk_bf16_f32 v32, v24, v25
	s_waitcnt lgkmcnt(2)
	v_cvt_pk_bf16_f32 v33, v26, v27
	s_waitcnt lgkmcnt(1)
	v_cvt_pk_bf16_f32 v34, v28, v29
	s_waitcnt lgkmcnt(0)
	v_cvt_pk_bf16_f32 v35, v30, v31
	global_store_dword v4, v32, s[8:9]
	s_add_u32 s8, s8, s17
	s_addc_u32 s9, s9, 0
	global_store_dword v4, v33, s[8:9]
	s_add_u32 s8, s8, s17
	s_addc_u32 s9, s9, 0
	global_store_dword v4, v34, s[8:9]
	s_add_u32 s8, s8, s17
	s_addc_u32 s9, s9, 0
	global_store_dword v4, v35, s[8:9]
	s_barrier
	s_cmp_eq_u32 s31, 0
	s_cbranch_scc1 .Ltc1_done
	s_mov_b32 s17, s15
	s_mov_b32 s30, s16
	s_mov_b64 s[8:9], s[12:13]
	s_add_u32 s4, s4, 84
	s_cmp_lt_u32 s4, 1216
	s_cselect_b32 s31, 1, 0
	s_cbranch_scc0 .Ltc1_nonextb
	v_writelane_b32 v40, s8, 32
	v_writelane_b32 v40, s9, 33
	s_cmp_lt_u32 s4, 960
	s_cbranch_scc0 .Ltc1_seg1_2
	s_mov_b32 s7, s4
	s_and_b32 s8, s7, 15
	s_lshr_b32 s9, s7, 4
	s_mul_i32 s7, s8, 983040
	s_lshl_b32 s29, s9, 8
	s_add_u32 s7, s7, s29
	s_mul_i32 s29, s28, 15360
	s_add_u32 s7, s7, s29
	s_add_u32 s10, s18, s7
	s_addc_u32 s11, s19, 0
	s_lshl_b32 s7, s9, 6
	s_mul_i32 s7, s7, 2048
	s_lshl_b32 s29, s8, 7
	s_add_u32 s7, s7, s29
	s_mul_i32 s29, s28, 4096
	s_add_u32 s7, s7, s29
	s_add_u32 s12, s24, 0x3c4800
	s_addc_u32 s13, s25, 0
	s_add_u32 s12, s12, s7
	s_addc_u32 s13, s13, 0
	s_mov_b32 s14, 122880
	s_mov_b32 s15, 32768
	s_movk_i32 s16, 2048
	s_branch .Ltc1_segend_2

; __device__ __forceinline__ void tconv_list(const float* wg, const float* wu, const float* wd, const float* win, const float* wout, unsigned char* ws, const int ntiles, LAS float* t, const int wv) {
;     ...
;         { const TDesc dn = tconv_desc(wg, wu, wd, win, wout, ws, i + G < ntiles ? i + G : i);
; #pragma unroll
;             for (int e = 0; e < 8; ++e) { const int idx = e * 512 + tid, r = idx >> 6, c = idx & 63; nxt[e] = __builtin_nontemporal_load(dn.W + (size_t)(dn.k0 + r) * dn.N + dn.n0 + c); } }
.Ltc1_segend_2:
	v_readlane_b32 s8, v40, 32
	v_readlane_b32 s9, v40, 33
	global_load_dword v8, v1, s[10:11] nt
	s_add_u32 s10, s10, s14
	s_addc_u32 s11, s11, 0
	global_load_dword v9, v1, s[10:11] nt
	s_add_u32 s10, s10, s14
	s_addc_u32 s11, s11, 0
	global_load_dword v10, v1, s[10:11] nt
	s_add_u32 s10, s10, s14
	s_addc_u32 s11, s11, 0
	global_load_dword v11, v1, s[10:11] nt
	s_add_u32 s10, s10, s14
	s_addc_u32 s11, s11, 0
	global_load_dword v12, v1, s[10:11] nt
	s_add_u32 s10, s10, s14
	s_addc_u32 s11, s11, 0
	global_load_dword v13, v1, s[10:11] nt
	s_add_u32 s10, s10, s14
	s_addc_u32 s11, s11, 0
	global_load_dword v14, v1, s[10:11] nt
	s_add_u32 s10, s10, s14
	s_addc_u32 s11, s11, 0
	global_load_dword v15, v1, s[10:11] nt
	s_waitcnt vmcnt(8)
	s_branch .Ltc1_haveb

; __device__ __forceinline__ unsigned cvt_pk_bf16(float lo, float hi) { const f32x2_t v = {lo, hi}; const bf16x2_t b = __builtin_convertvector(v, bf16x2_t); return __builtin_bit_cast(unsigned, b); }
; __device__ __forceinline__ void tconv_list(const float* wg, const float* wu, const float* wd, const float* win, const float* wout, unsigned char* ws, const int ntiles, LAS float* t, const int wv) {
;     ...
; #pragma unroll
;         for (int e = 0; e < 8; ++e) { const int idx = e * 512 + tid, r = idx >> 6, c = idx & 63; t[r * 65 + c] = cur[e]; }
;         __syncthreads();
; #pragma unroll
;         for (int e = 0; e < 4; ++e) { const int idx = e * 512 + tid, n = idx >> 5, kp = idx & 31;
;             const unsigned w = pg8::cvt_pk_bf16(t[(2 * kp) * 65 + n], t[(2 * kp + 1) * 65 + n]);
;             *(unsigned*)(d.Bt + (size_t)(d.brow0 + n) * d.K + d.k0 + 2 * kp) = w; }
;         __syncthreads();
; #pragma unroll
;         for (int e = 0; e < 8; ++e) cur[e] = nxt[e];
;     }
; }
.Ltc1_haveb:
	ds_write_b32 v5, v16 offset:0
	ds_write_b32 v5, v17 offset:2080
	ds_write_b32 v5, v18 offset:4160
	ds_write_b32 v5, v19 offset:6240
	ds_write_b32 v5, v20 offset:8320
	ds_write_b32 v5, v21 offset:10400
	ds_write_b32 v5, v22 offset:12480
	ds_write_b32 v5, v23 offset:14560
	v_mad_u32_u24 v4, v2, s30, v3
	s_waitcnt lgkmcnt(0)
	s_barrier
	ds_read2_b32 v[24:25], v6 offset0:0 offset1:65
	ds_read2_b32 v[26:27], v6 offset0:16 offset1:81
	ds_read2_b32 v[28:29], v6 offset0:32 offset1:97
	ds_read2_b32 v[30:31], v6 offset0:48 offset1:113
	s_waitcnt lgkmcnt(3)
	v_cvt_pk_bf16_f32 v32, v24, v25
	s_waitcnt lgkmcnt(2)
	v_cvt_pk_bf16_f32 v33, v26, v27
	s_waitcnt lgkmcnt(1)
	v_cvt_pk_bf16_f32 v34, v28, v29
	s_waitcnt lgkmcnt(0)
	v_cvt_pk_bf16_f32 v35, v30, v31
	global_store_dword v4, v32, s[8:9]
	s_add_u32 s8, s8, s17
	s_addc_u32 s9, s9, 0
	global_store_dword v4, v33, s[8:9]
	s_add_u32 s8, s8, s17
	s_addc_u32 s9, s9, 0
	global_store_dword v4, v34, s[8:9]
	s_add_u32 s8, s8, s17
	s_addc_u32 s9, s9, 0
	global_store_dword v4, v35, s[8:9]
	s_barrier
	s_cmp_eq_u32 s31, 0
	s_cbranch_scc1 .Ltc1_done
	s_mov_b32 s17, s15
	s_mov_b32 s30, s16
	s_mov_b64 s[8:9], s[12:13]
	s_branch .Ltc1_loop
.Ltc1_done:
	v_readlane_b32 s4, v40, 4
	v_readlane_b32 s5, v40, 5
	v_readlane_b32 s6, v40, 6
	v_readlane_b32 s7, v40, 7
	v_readlane_b32 s8, v40, 8
	v_readlane_b32 s9, v40, 9
	v_readlane_b32 s10, v40, 10
	v_readlane_b32 s11, v40, 11
	v_readlane_b32 s12, v40, 12
	v_readlane_b32 s13, v40, 13
	v_readlane_b32 s14, v40, 14
	v_readlane_b32 s15, v40, 15
	v_readlane_b32 s16, v40, 16
	v_readlane_b32 s17, v40, 17
	v_readlane_b32 s18, v40, 18
	v_readlane_b32 s19, v40, 19
	v_readlane_b32 s20, v40, 20
	v_readlane_b32 s21, v40, 21
	v_readlane_b32 s22, v40, 22
	v_readlane_b32 s23, v40, 23
	v_readlane_b32 s24, v40, 24
	v_readlane_b32 s25, v40, 25
	v_readlane_b32 s26, v40, 26
	v_readlane_b32 s27, v40, 27
	v_readlane_b32 s28, v40, 28
	v_readlane_b32 s29, v40, 29
	v_readlane_b32 s30, v40, 30
	v_readlane_b32 s31, v40, 31
	s_nop 4

; __device__ __forceinline__ int fresh_tid(int wv) { int l; asm volatile("v_mbcnt_lo_u32_b32 %0, -1, 0\n\tv_mbcnt_hi_u32_b32 %0, -1, %0" : "=v"(l)); return wv * 64 + l; }
; #define LAS __attribute__((address_space(3)))
; __device__ __forceinline__ TDesc tconv_desc(const float* wg, const float* wu, const float* wd, const float* win, const float* wout, unsigned char* ws, int i) {
;     TDesc d; int mode = 0, tile = i;
;     if (i < 704) { d.W = wg; d.Bt = (bf16_t*)(ws + WS_WGU); d.K = 1024; d.N = DFF; mode = 1; }
;     else if (i < 1408) { d.W = wu; d.Bt = (bf16_t*)(ws + WS_WGU); d.K = 1024; d.N = DFF; mode = 2; tile = i - 704; }
;     else if (i < 2112) { d.W = wd; d.Bt = (bf16_t*)(ws + WS_WD); d.K = DFF; d.N = 1024; tile = i - 1408; }
;     else if (i < 3072) { d.W = win; d.Bt = (bf16_t*)(ws + WS_WIN); d.K = 1024; d.N = NCOLS; tile = i - 2112; }
;     else { d.W = wout; d.Bt = (bf16_t*)(ws + WS_WOUT); d.K = 1024; d.N = 1024; tile = i - 3072; }
;     const int nkt = d.K / 64; const int kt = tile % nkt, nt = tile / nkt; d.k0 = kt * 64; d.n0 = nt * 64;
;     d.brow0 = mode == 0 ? d.n0 : ((d.n0 >> 7) * 256 + (d.n0 & 127) + (mode == 2 ? 128 : 0));
;     return d;
; }
; __device__ __forceinline__ void tconv_list(const float* wg, const float* wu, const float* wd, const float* win, const float* wout, unsigned char* ws, const int ntiles, LAS float* t, const int wv) {
;     const int tid = fresh_tid(wv); const int G = gridDim.x;
;     float cur[8], nxt[8];
;     int i = blockIdx.x;
;     if (i < ntiles) { const TDesc d = tconv_desc(wg, wu, wd, win, wout, ws, i);
; #pragma unroll
;         for (int e = 0; e < 8; ++e) { const int idx = e * 512 + tid, r = idx >> 6, c = idx & 63; cur[e] = __builtin_nontemporal_load(d.W + (size_t)(d.k0 + r) * d.N + d.n0 + c); } }
;     for (; i < ntiles; i += G) {
;         const TDesc d = tconv_desc(wg, wu, wd, win, wout, ws, i);
;         { const TDesc dn = tconv_desc(wg, wu, wd, win, wout, ws, i + G < ntiles ? i + G : i);
; #pragma unroll
;             for (int e = 0; e < 8; ++e) { const int idx = e * 512 + tid, r = idx >> 6, c = idx & 63; nxt[e] = __builtin_nontemporal_load(dn.W + (size_t)(dn.k0 + r) * dn.N + dn.n0 + c); } }
.LBB0_689:
	s_cmp_lt_u32 s2, 128
	s_cbranch_scc1 .Ltc2_skip
	v_writelane_b32 v40, s4, 4
	v_writelane_b32 v40, s5, 5
	v_writelane_b32 v40, s6, 6
	v_writelane_b32 v40, s7, 7
	v_writelane_b32 v40, s8, 8
	v_writelane_b32 v40, s9, 9
	v_writelane_b32 v40, s10, 10
	v_writelane_b32 v40, s11, 11
	v_writelane_b32 v40, s12, 12
	v_writelane_b32 v40, s13, 13
	v_writelane_b32 v40, s14, 14
	v_writelane_b32 v40, s15, 15
	v_writelane_b32 v40, s16, 16
	v_writelane_b32 v40, s17, 17
	v_writelane_b32 v40, s18, 18
	v_writelane_b32 v40, s19, 19
	v_writelane_b32 v40, s20, 20
	v_writelane_b32 v40, s21, 21
	v_writelane_b32 v40, s22, 22
	v_writelane_b32 v40, s23, 23
	v_writelane_b32 v40, s24, 24
	v_writelane_b32 v40, s25, 25
	v_writelane_b32 v40, s26, 26
	v_writelane_b32 v40, s27, 27
	v_writelane_b32 v40, s28, 28
	v_writelane_b32 v40, s29, 29
	v_writelane_b32 v40, s30, 30
	v_writelane_b32 v40, s31, 31
	s_load_dwordx2 s[24:25], s[38:39], 0xd8
	s_load_dwordx2 s[26:27], s[38:39], 0xd0
	s_load_dwordx2 s[18:19], s[38:39], 0xb8
	s_load_dwordx2 s[20:21], s[38:39], 0xc0
	s_load_dwordx2 s[22:23], s[38:39], 0xc8
	v_mbcnt_lo_u32_b32 v0, -1, 0
	v_mbcnt_hi_u32_b32 v0, -1, v0
	s_lshr_b32 s28, s33, 6
	v_lshlrev_b32_e32 v1, 2, v0
	v_lshrrev_b32_e32 v2, 5, v0
	v_and_b32_e32 v3, 31, v0
	s_mul_i32 s7, s28, 260
	v_add_u32_e32 v5, s7, v1
	v_mul_u32_u24_e32 v6, 0x208, v3
	s_lshl_b32 s7, s28, 3
	v_lshl_add_u32 v6, v2, 2, v6
	v_add_u32_e32 v6, s7, v6
	v_lshlrev_b32_e32 v3, 2, v3
	s_sub_u32 s4, s2, 128
	s_waitcnt lgkmcnt(0)
	s_cmp_lt_u32 s4, 704
	s_cbranch_scc0 .Ltc2_seg1_0
	s_mov_b32 s7, s4
	s_and_b32 s8, s7, 15
	s_lshr_b32 s9, s7, 4
	s_mul_i32 s7, s8, 720896
	s_lshl_b32 s29, s9, 8
	s_add_u32 s7, s7, s29
	s_mul_i32 s29, s28, 11264
	s_add_u32 s7, s7, s29
	s_add_u32 s10, s18, s7
	s_addc_u32 s11, s19, 0
	s_lshr_b32 s7, s9, 1
	s_lshl_b32 s7, s7, 8
	s_and_b32 s29, s9, 1
	s_lshl_b32 s29, s29, 6
	s_add_u32 s7, s7, s29
	s_mul_i32 s7, s7, 2048
	s_lshl_b32 s29, s8, 7
	s_add_u32 s7, s7, s29
	s_mul_i32 s29, s28, 4096
	s_add_u32 s7, s7, s29
	s_add_u32 s12, s26, 0x2100000
	s_addc_u32 s13, s27, 0
	s_add_u32 s12, s12, s7
	s_addc_u32 s13, s13, 0
	s_mov_b32 s14, 90112
	s_mov_b32 s15, 32768
	s_movk_i32 s16, 2048
	s_branch .Ltc2_segend_0
.Ltc2_seg1_0:
	s_cmp_lt_u32 s4, 1408
	s_cbranch_scc0 .Ltc2_seg2_0
	s_sub_u32 s7, s4, 704
	s_and_b32 s8, s7, 15
	s_lshr_b32 s9, s7, 4
	s_mul_i32 s7, s8, 720896
	s_lshl_b32 s29, s9, 8
	s_add_u32 s7, s7, s29
	s_mul_i32 s29, s28, 11264
	s_add_u32 s7, s7, s29
	s_add_u32 s10, s20, s7
	s_addc_u32 s11, s21, 0
	s_lshr_b32 s7, s9, 1
	s_lshl_b32 s7, s7, 8
	s_and_b32 s29, s9, 1
	s_lshl_b32 s29, s29, 6
	s_add_u32 s7, s7, s29
	s_add_u32 s7, s7, 128
	s_mul_i32 s7, s7, 2048
	s_lshl_b32 s29, s8, 7
	s_add_u32 s7, s7, s29
	s_mul_i32 s29, s28, 4096
	s_add_u32 s7, s7, s29
	s_add_u32 s12, s26, 0x2100000
	s_addc_u32 s13, s27, 0
	s_add_u32 s12, s12, s7
	s_addc_u32 s13, s13, 0
	s_mov_b32 s14, 90112
	s_mov_b32 s15, 32768
	s_movk_i32 s16, 2048
	s_branch .Ltc2_segend_0
.Ltc2_seg2_0:
	s_sub_u32 s7, s4, 1408
	s_mul_i32 s9, s7, 1490
	s_lshr_b32 s9, s9, 16
	s_mul_i32 s8, s9, 44
	s_sub_u32 s8, s7, s8
	s_mul_i32 s7, s8, 262144
	s_lshl_b32 s29, s9, 8
	s_add_u32 s7, s7, s29
	s_mul_i32 s29, s28, 4096
	s_add_u32 s7, s7, s29
	s_add_u32 s10, s22, s7
	s_addc_u32 s11, s23, 0
	s_lshl_b32 s7, s9, 6
	s_mul_i32 s7, s7, 5632
	s_lshl_b32 s29, s8, 7
	s_add_u32 s7, s7, s29
	s_mul_i32 s29, s28, 11264
	s_add_u32 s7, s7, s29
	s_add_u32 s12, s24, 0x1644800
	s_addc_u32 s13, s25, 0
	s_add_u32 s12, s12, s7
	s_addc_u32 s13, s13, 0
	s_mov_b32 s14, 32768
	s_mov_b32 s15, 90112
	s_movk_i32 s16, 5632

; __device__ __forceinline__ TDesc tconv_desc(const float* wg, const float* wu, const float* wd, const float* win, const float* wout, unsigned char* ws, int i) {
;     ...
;     if (i < 704) { d.W = wg; d.Bt = (bf16_t*)(ws + WS_WGU); d.K = 1024; d.N = DFF; mode = 1; }
;     else if (i < 1408) { d.W = wu; d.Bt = (bf16_t*)(ws + WS_WGU); d.K = 1024; d.N = DFF; mode = 2; tile = i - 704; }
;     else if (i < 2112) { d.W = wd; d.Bt = (bf16_t*)(ws + WS_WD); d.K = DFF; d.N = 1024; tile = i - 1408; }
;     else if (i < 3072) { d.W = win; d.Bt = (bf16_t*)(ws + WS_WIN); d.K = 1024; d.N = NCOLS; tile = i - 2112; }
;     else { d.W = wout; d.Bt = (bf16_t*)(ws + WS_WOUT); d.K = 1024; d.N = 1024; tile = i - 3072; }
;     const int nkt = d.K / 64; const int kt = tile % nkt, nt = tile / nkt; d.k0 = kt * 64; d.n0 = nt * 64;
;     d.brow0 = mode == 0 ? d.n0 : ((d.n0 >> 7) * 256 + (d.n0 & 127) + (mode == 2 ? 128 : 0));
; __device__ __forceinline__ void tconv_list(const float* wg, const float* wu, const float* wd, const float* win, const float* wout, unsigned char* ws, const int ntiles, LAS float* t, const int wv) {
;     ...
;     for (; i < ntiles; i += G) {
;         const TDesc d = tconv_desc(wg, wu, wd, win, wout, ws, i);
;         { const TDesc dn = tconv_desc(wg, wu, wd, win, wout, ws, i + G < ntiles ? i + G : i);
; #pragma unroll
;             for (int e = 0; e < 8; ++e) { const int idx = e * 512 + tid, r = idx >> 6, c = idx & 63; nxt[e] = __builtin_nontemporal_load(dn.W + (size_t)(dn.k0 + r) * dn.N + dn.n0 + c); } }
.Ltc2_loop:
	s_add_u32 s4, s4, 128
	s_cmp_lt_u32 s4, 2112
	s_cselect_b32 s31, 1, 0
	s_cbranch_scc0 .Ltc2_nonexta
	v_writelane_b32 v40, s8, 32
	v_writelane_b32 v40, s9, 33
	s_cmp_lt_u32 s4, 704
	s_cbranch_scc0 .Ltc2_seg1_1
	s_mov_b32 s7, s4
	s_and_b32 s8, s7, 15
	s_lshr_b32 s9, s7, 4
	s_mul_i32 s7, s8, 720896
	s_lshl_b32 s29, s9, 8
	s_add_u32 s7, s7, s29
	s_mul_i32 s29, s28, 11264
	s_add_u32 s7, s7, s29
	s_add_u32 s10, s18, s7
	s_addc_u32 s11, s19, 0
	s_lshr_b32 s7, s9, 1
	s_lshl_b32 s7, s7, 8
	s_and_b32 s29, s9, 1
	s_lshl_b32 s29, s29, 6
	s_add_u32 s7, s7, s29
	s_mul_i32 s7, s7, 2048
	s_lshl_b32 s29, s8, 7
	s_add_u32 s7, s7, s29
	s_mul_i32 s29, s28, 4096
	s_add_u32 s7, s7, s29
	s_add_u32 s12, s26, 0x2100000
	s_addc_u32 s13, s27, 0
	s_add_u32 s12, s12, s7
	s_addc_u32 s13, s13, 0
	s_mov_b32 s14, 90112
	s_mov_b32 s15, 32768
	s_movk_i32 s16, 2048
	s_branch .Ltc2_segend_1

; __device__ __forceinline__ unsigned cvt_pk_bf16(float lo, float hi) { const f32x2_t v = {lo, hi}; const bf16x2_t b = __builtin_convertvector(v, bf16x2_t); return __builtin_bit_cast(unsigned, b); }
; __device__ __forceinline__ void tconv_list(const float* wg, const float* wu, const float* wd, const float* win, const float* wout, unsigned char* ws, const int ntiles, LAS float* t, const int wv) {
;     ...
;         { const TDesc dn = tconv_desc(wg, wu, wd, win, wout, ws, i + G < ntiles ? i + G : i);
; #pragma unroll
;             for (int e = 0; e < 8; ++e) { const int idx = e * 512 + tid, r = idx >> 6, c = idx & 63; nxt[e] = __builtin_nontemporal_load(dn.W + (size_t)(dn.k0 + r) * dn.N + dn.n0 + c); } }
; #pragma unroll
;         for (int e = 0; e < 8; ++e) { const int idx = e * 512 + tid, r = idx >> 6, c = idx & 63; t[r * 65 + c] = cur[e]; }
;         __syncthreads();
; #pragma unroll
;         for (int e = 0; e < 4; ++e) { const int idx = e * 512 + tid, n = idx >> 5, kp = idx & 31;
;             const unsigned w = pg8::cvt_pk_bf16(t[(2 * kp) * 65 + n], t[(2 * kp + 1) * 65 + n]);
;             *(unsigned*)(d.Bt + (size_t)(d.brow0 + n) * d.K + d.k0 + 2 * kp) = w; }
;         __syncthreads();
; #pragma unroll
;         for (int e = 0; e < 8; ++e) cur[e] = nxt[e];
.Ltc2_havea:
	ds_write_b32 v5, v8 offset:0
	ds_write_b32 v5, v9 offset:2080
	ds_write_b32 v5, v10 offset:4160
	ds_write_b32 v5, v11 offset:6240
	ds_write_b32 v5, v12 offset:8320
	ds_write_b32 v5, v13 offset:10400
	ds_write_b32 v5, v14 offset:12480
	ds_write_b32 v5, v15 offset:14560
	v_mad_u32_u24 v4, v2, s30, v3
	s_waitcnt lgkmcnt(0)
	s_barrier
	ds_read2_b32 v[24:25], v6 offset0:0 offset1:65
	ds_read2_b32 v[26:27], v6 offset0:16 offset1:81
	ds_read2_b32 v[28:29], v6 offset0:32 offset1:97
	ds_read2_b32 v[30:31], v6 offset0:48 offset1:113
	s_waitcnt lgkmcnt(3)
	v_cvt_pk_bf16_f32 v32, v24, v25
	s_waitcnt lgkmcnt(2)
	v_cvt_pk_bf16_f32 v33, v26, v27
	s_waitcnt lgkmcnt(1)
	v_cvt_pk_bf16_f32 v34, v28, v29
	s_waitcnt lgkmcnt(0)
	v_cvt_pk_bf16_f32 v35, v30, v31
	global_store_dword v4, v32, s[8:9]
	s_add_u32 s8, s8, s17
	s_addc_u32 s9, s9, 0
	global_store_dword v4, v33, s[8:9]
	s_add_u32 s8, s8, s17
	s_addc_u32 s9, s9, 0
	global_store_dword v4, v34, s[8:9]
	s_add_u32 s8, s8, s17
	s_addc_u32 s9, s9, 0
	global_store_dword v4, v35, s[8:9]
	s_barrier
	s_cmp_eq_u32 s31, 0
	s_cbranch_scc1 .Ltc2_done
	s_mov_b32 s17, s15
	s_mov_b32 s30, s16
	s_mov_b64 s[8:9], s[12:13]
	s_add_u32 s4, s4, 128
	s_cmp_lt_u32 s4, 2112
	s_cselect_b32 s31, 1, 0
	s_cbranch_scc0 .Ltc2_nonextb
	v_writelane_b32 v40, s8, 32
	v_writelane_b32 v40, s9, 33
	s_cmp_lt_u32 s4, 704
	s_cbranch_scc0 .Ltc2_seg1_2
	s_mov_b32 s7, s4
	s_and_b32 s8, s7, 15
	s_lshr_b32 s9, s7, 4
	s_mul_i32 s7, s8, 720896
	s_lshl_b32 s29, s9, 8
	s_add_u32 s7, s7, s29
	s_mul_i32 s29, s28, 11264
	s_add_u32 s7, s7, s29
	s_add_u32 s10, s18, s7
	s_addc_u32 s11, s19, 0
	s_lshr_b32 s7, s9, 1
	s_lshl_b32 s7, s7, 8
	s_and_b32 s29, s9, 1
	s_lshl_b32 s29, s29, 6
	s_add_u32 s7, s7, s29
	s_mul_i32 s7, s7, 2048
	s_lshl_b32 s29, s8, 7
	s_add_u32 s7, s7, s29
	s_mul_i32 s29, s28, 4096
	s_add_u32 s7, s7, s29
	s_add_u32 s12, s26, 0x2100000
	s_addc_u32 s13, s27, 0
	s_add_u32 s12, s12, s7
	s_addc_u32 s13, s13, 0
	s_mov_b32 s14, 90112
	s_mov_b32 s15, 32768
	s_movk_i32 s16, 2048
	s_branch .Ltc2_segend_2

; #define LAS __attribute__((address_space(3)))
; #define RW_LOAD(c) do { RW_LOAD1(c, 0); RW_LOAD1(c, 1); } while (0)
; template <bool SAMPLE>
; __device__ __forceinline__ void rwkv_unit(PR P, LAS float* lds, const int b, const int h, const int half, const int wv) {
;     ...
;     for (int c = 0; c < NCH; ++c) {
;         LAS float* cur = (c & 1) ? buf1 : buf0; LAS float* nxt = (c & 1) ? buf0 : buf1;
;         if (c + 1 < NCH) RW_LOAD(c + 1);
.LBB0_705:
	s_cmp_lt_u32 s33, 0x100
	s_cbranch_scc1 .Lrw_scan_chunk
	s_add_i32 s56, s71, 1
	s_cmp_lg_u32 s71, 63
	s_cselect_b64 s[46:47], -1, 0
	s_cmp_eq_u32 s71, 63
	s_cbranch_scc1 .LBB0_715
	v_lshl_add_u32 v72, s56, 5, v55
	s_and_saveexec_b64 s[66:67], s[62:63]
	s_cbranch_execz .LBB0_710
	s_waitcnt vmcnt(1)
	v_add_u32_e32 v34, s6, v72
	v_mad_i64_i32 v[26:27], s[60:61], v34, s49, v[58:59]
	global_load_dwordx2 v[22:23], v[26:27], off
	global_load_dwordx2 v[24:25], v[26:27], off offset:1024
	s_nop 0
	global_load_dwordx2 v[26:27], v[26:27], off offset:2048
	v_mov_b32_e32 v57, v56
	v_ashrrev_i32_e32 v35, 31, v34
	v_cmp_lt_i32_e32 vcc, 0, v72
	v_mov_b64_e32 v[30:31], v[56:57]
	v_mov_b64_e32 v[32:33], v[56:57]
	v_mov_b64_e32 v[28:29], v[56:57]
	s_and_saveexec_b64 s[68:69], vcc
	s_cbranch_execz .LBB0_709
	v_add_u32_e32 v28, -1, v34
	v_mad_i64_i32 v[30:31], s[60:61], v28, s49, v[58:59]
	global_load_dwordx2 v[28:29], v[30:31], off
	global_load_dwordx2 v[32:33], v[30:31], off offset:1024
	s_nop 0
	global_load_dwordx2 v[30:31], v[30:31], off offset:2048

; __device__ __forceinline__ unsigned cvt_pk_bf16(float lo, float hi) { const f32x2_t v = {lo, hi}; const bf16x2_t b = __builtin_convertvector(v, bf16x2_t); return __builtin_bit_cast(unsigned, b); }
; #define LAS __attribute__((address_space(3)))
; #define ROW16_SUM2(x, y) do { DPP2(x, y, "quad_perm:[1,0,3,2]", "s_nop 1"); DPP2(x, y, "quad_perm:[2,3,0,1]", "s_nop 0"); DPP2(x, y, "row_half_mirror", "s_nop 0"); DPP2(x, y, "row_mirror", "s_nop 0"); } while (0)
; #define RW_LOAD(c) do { RW_LOAD1(c, 0); RW_LOAD1(c, 1); } while (0)
; template <bool SAMPLE>
; __device__ __forceinline__ void rwkv_unit(PR P, LAS float* lds, const int b, const int h, const int half, const int wv) {
;     ...
;         LAS float* cur = (c & 1) ? buf1 : buf0; LAS float* nxt = (c & 1) ? buf0 : buf1;
;         if (c + 1 < NCH) RW_LOAD(c + 1);
;         if (wid < 4) {
;             constexpr int GS = SAMPLE ? 4 : 16;
;             for (int g = 0; g < TC / GS; ++g) {
;                 float yk0 = 0.f, yk1 = 0.f;
;                 const LAS float* q0 = cur + (g * GS) * 384;
;                 f32x4 r4 = *(const LAS f32x4*)(q0 + j0), o4 = *(const LAS f32x4*)(q0 + 64 + j0), k4 = *(const LAS f32x4*)(q0 + 128 + j0), a4 = *(const LAS f32x4*)(q0 + 192 + j0), b4 = *(const LAS f32x4*)(q0 + 256 + j0);
;                 f32x2 v2 = *(const LAS f32x2*)(q0 + 320 + row0);
;     ...
;                 ROW16_SUM2(py0, py1); yk0 = cgl == GS - 1 ? py0 : yk0; yk1 = cgl == GS - 1 ? py1 : yk1;
;                 if (cgl < GS) *(unsigned*)(YS + (size_t)(row_base + c * TC + g * GS + cgl) * 512 + h * 64 + row0) = pg8::cvt_pk_bf16(yk0, yk1);
.Lrw_scan_chunk:
	s_add_i32 s56, s71, 1
	s_bitcmp0_b32 s71, 0
	s_cselect_b32 s57, 0, s55
	v_lshl_add_u32 v57, s71, 5, v77
	v_lshl_add_u32 v152, v76, 2, s57
	v_lshl_add_u32 v153, v54, 2, s57
	v_add_u32_e32 v153, 0x100, v153
	ds_read_b128 v[172:175], v152 offset:768
	ds_read_b128 v[164:167], v152 offset:256
	ds_read2st64_b64 v[240:243], v153 offset0:2 offset1:5
	ds_read_b128 v[168:171], v152 offset:512
	ds_read_b128 v[192:195], v152 offset:2304
	ds_read_b128 v[184:187], v152 offset:1792
	ds_read_b128 v[176:179], v152 offset:1024
	ds_read_b128 v[188:191], v152 offset:2048
	ds_read_b128 v[196:199], v152 offset:2560
	ds_read_b128 v[160:163], v152 offset:0
	ds_read_b128 v[180:183], v152 offset:1536
	s_cmp_eq_u32 s71, 0
	s_cbranch_scc1 .Lrw_first_chunk
	v_add_f32_dpp v110, v110, v110 row_ror:8 row_mask:0xf bank_mask:0x3 bound_ctrl:1
	v_add_f32_dpp v110, v126, v126 row_ror:8 row_mask:0xf bank_mask:0xc bound_ctrl:1
	v_add_f32_dpp v112, v112, v112 row_ror:8 row_mask:0xf bank_mask:0x3 bound_ctrl:1
	v_add_f32_dpp v112, v128, v128 row_ror:8 row_mask:0xf bank_mask:0xc bound_ctrl:1
	v_add_f32_dpp v114, v114, v114 row_ror:8 row_mask:0xf bank_mask:0x3 bound_ctrl:1
	v_add_f32_dpp v114, v130, v130 row_ror:8 row_mask:0xf bank_mask:0xc bound_ctrl:1
	v_add_f32_dpp v116, v116, v116 row_ror:8 row_mask:0xf bank_mask:0x3 bound_ctrl:1
	v_add_f32_dpp v116, v132, v132 row_ror:8 row_mask:0xf bank_mask:0xc bound_ctrl:1
	v_add_f32_dpp v118, v118, v118 row_ror:8 row_mask:0xf bank_mask:0x3 bound_ctrl:1
	v_add_f32_dpp v118, v134, v134 row_ror:8 row_mask:0xf bank_mask:0xc bound_ctrl:1
	v_add_f32_dpp v120, v120, v120 row_ror:8 row_mask:0xf bank_mask:0x3 bound_ctrl:1
	v_add_f32_dpp v120, v136, v136 row_ror:8 row_mask:0xf bank_mask:0xc bound_ctrl:1
	v_add_f32_dpp v122, v122, v122 row_ror:8 row_mask:0xf bank_mask:0x3 bound_ctrl:1
	v_add_f32_dpp v122, v138, v138 row_ror:8 row_mask:0xf bank_mask:0xc bound_ctrl:1
	v_add_f32_dpp v124, v124, v124 row_ror:8 row_mask:0xf bank_mask:0x3 bound_ctrl:1
	v_add_f32_dpp v124, v140, v140 row_ror:8 row_mask:0xf bank_mask:0xc bound_ctrl:1
	v_add_f32_dpp v111, v111, v111 row_ror:8 row_mask:0xf bank_mask:0x3 bound_ctrl:1
	v_add_f32_dpp v111, v127, v127 row_ror:8 row_mask:0xf bank_mask:0xc bound_ctrl:1
	v_add_f32_dpp v113, v113, v113 row_ror:8 row_mask:0xf bank_mask:0x3 bound_ctrl:1
	v_add_f32_dpp v113, v129, v129 row_ror:8 row_mask:0xf bank_mask:0xc bound_ctrl:1
	v_add_f32_dpp v115, v115, v115 row_ror:8 row_mask:0xf bank_mask:0x3 bound_ctrl:1
	v_add_f32_dpp v115, v131, v131 row_ror:8 row_mask:0xf bank_mask:0xc bound_ctrl:1
	v_add_f32_dpp v117, v117, v117 row_ror:8 row_mask:0xf bank_mask:0x3 bound_ctrl:1
	v_add_f32_dpp v117, v133, v133 row_ror:8 row_mask:0xf bank_mask:0xc bound_ctrl:1
	v_add_f32_dpp v119, v119, v119 row_ror:8 row_mask:0xf bank_mask:0x3 bound_ctrl:1
	v_add_f32_dpp v119, v135, v135 row_ror:8 row_mask:0xf bank_mask:0xc bound_ctrl:1
	v_add_f32_dpp v121, v121, v121 row_ror:8 row_mask:0xf bank_mask:0x3 bound_ctrl:1
	v_add_f32_dpp v121, v137, v137 row_ror:8 row_mask:0xf bank_mask:0xc bound_ctrl:1
	v_add_f32_dpp v123, v123, v123 row_ror:8 row_mask:0xf bank_mask:0x3 bound_ctrl:1
	v_add_f32_dpp v123, v139, v139 row_ror:8 row_mask:0xf bank_mask:0xc bound_ctrl:1
	v_add_f32_dpp v125, v125, v125 row_ror:8 row_mask:0xf bank_mask:0x3 bound_ctrl:1
	v_add_f32_dpp v125, v141, v141 row_ror:8 row_mask:0xf bank_mask:0xc bound_ctrl:1
	v_add_f32_dpp v110, v110, v110 row_shl:4 row_mask:0xf bank_mask:0x5 bound_ctrl:1
	v_add_f32_dpp v110, v118, v118 row_shr:4 row_mask:0xf bank_mask:0xa bound_ctrl:1
	v_add_f32_dpp v112, v112, v112 row_shl:4 row_mask:0xf bank_mask:0x5 bound_ctrl:1
	v_add_f32_dpp v112, v120, v120 row_shr:4 row_mask:0xf bank_mask:0xa bound_ctrl:1
	v_add_f32_dpp v114, v114, v114 row_shl:4 row_mask:0xf bank_mask:0x5 bound_ctrl:1
	v_add_f32_dpp v114, v122, v122 row_shr:4 row_mask:0xf bank_mask:0xa bound_ctrl:1
	v_add_f32_dpp v116, v116, v116 row_shl:4 row_mask:0xf bank_mask:0x5 bound_ctrl:1
	v_add_f32_dpp v116, v124, v124 row_shr:4 row_mask:0xf bank_mask:0xa bound_ctrl:1
	v_add_f32_dpp v111, v111, v111 row_shl:4 row_mask:0xf bank_mask:0x5 bound_ctrl:1
	v_add_f32_dpp v111, v119, v119 row_shr:4 row_mask:0xf bank_mask:0xa bound_ctrl:1
	v_add_f32_dpp v113, v113, v113 row_shl:4 row_mask:0xf bank_mask:0x5 bound_ctrl:1
	v_add_f32_dpp v113, v121, v121 row_shr:4 row_mask:0xf bank_mask:0xa bound_ctrl:1
	v_add_f32_dpp v115, v115, v115 row_shl:4 row_mask:0xf bank_mask:0x5 bound_ctrl:1
	v_add_f32_dpp v115, v123, v123 row_shr:4 row_mask:0xf bank_mask:0xa bound_ctrl:1
	v_add_f32_dpp v117, v117, v117 row_shl:4 row_mask:0xf bank_mask:0x5 bound_ctrl:1
	v_add_f32_dpp v117, v125, v125 row_shr:4 row_mask:0xf bank_mask:0xa bound_ctrl:1
	v_add_f32_dpp v110, v110, v110 quad_perm:[1,0,3,2] row_mask:0xf bank_mask:0xf bound_ctrl:1
	v_add_f32_dpp v112, v112, v112 quad_perm:[1,0,3,2] row_mask:0xf bank_mask:0xf bound_ctrl:1
	v_add_f32_dpp v114, v114, v114 quad_perm:[1,0,3,2] row_mask:0xf bank_mask:0xf bound_ctrl:1
	v_add_f32_dpp v116, v116, v116 quad_perm:[1,0,3,2] row_mask:0xf bank_mask:0xf bound_ctrl:1
	v_add_f32_dpp v111, v111, v111 quad_perm:[1,0,3,2] row_mask:0xf bank_mask:0xf bound_ctrl:1
	v_add_f32_dpp v113, v113, v113 quad_perm:[1,0,3,2] row_mask:0xf bank_mask:0xf bound_ctrl:1
	v_add_f32_dpp v115, v115, v115 quad_perm:[1,0,3,2] row_mask:0xf bank_mask:0xf bound_ctrl:1
	v_add_f32_dpp v117, v117, v117 quad_perm:[1,0,3,2] row_mask:0xf bank_mask:0xf bound_ctrl:1
	v_add_f32_dpp v110, v110, v110 quad_perm:[2,3,0,1] row_mask:0xf bank_mask:0xf bound_ctrl:1
	v_add_f32_dpp v112, v112, v112 quad_perm:[2,3,0,1] row_mask:0xf bank_mask:0xf bound_ctrl:1
	v_add_f32_dpp v114, v114, v114 quad_perm:[2,3,0,1] row_mask:0xf bank_mask:0xf bound_ctrl:1
	v_add_f32_dpp v116, v116, v116 quad_perm:[2,3,0,1] row_mask:0xf bank_mask:0xf bound_ctrl:1
	v_add_f32_dpp v111, v111, v111 quad_perm:[2,3,0,1] row_mask:0xf bank_mask:0xf bound_ctrl:1
	v_add_f32_dpp v113, v113, v113 quad_perm:[2,3,0,1] row_mask:0xf bank_mask:0xf bound_ctrl:1
	v_add_f32_dpp v115, v115, v115 quad_perm:[2,3,0,1] row_mask:0xf bank_mask:0xf bound_ctrl:1
	v_add_f32_dpp v117, v117, v117 quad_perm:[2,3,0,1] row_mask:0xf bank_mask:0xf bound_ctrl:1
	v_subrev_u32_e32 v72, 16, v57
	v_ashrrev_i32_e32 v73, 31, v72
	v_lshlrev_b64 v[72:73], 10, v[72:73]
	v_lshl_add_u64 v[72:73], v[64:65], 0, v[72:73]
	v_cndmask_b32_e64 v154, v116, v114, s[16:17]
	v_cndmask_b32_e64 v155, v117, v115, s[16:17]
	v_cndmask_b32_e64 v154, v154, v112, s[14:15]
	v_cndmask_b32_e64 v155, v155, v113, s[14:15]
	v_cndmask_b32_e64 v154, v154, v110, s[12:13]
	v_cndmask_b32_e64 v155, v155, v111, s[12:13]
	v_cvt_pk_bf16_f32 v154, v154, v155
	global_store_dword v[72:73], v154, off
; #define LAS __attribute__((address_space(3)))
; #define ROW16_SUM4(x, y, z, w) do { DPP4(x, y, z, w, "quad_perm:[1,0,3,2]", "s_nop 1"); DPP4(x, y, z, w, "quad_perm:[2,3,0,1]", ""); DPP4(x, y, z, w, "row_half_mirror", ""); DPP4(x, y, z, w, "row_mirror", ""); } while (0)
; template <bool SAMPLE>
; __device__ __forceinline__ void rwkv_unit(PR P, LAS float* lds, const int b, const int h, const int half, const int wv) {
;     ...
;                 f32x4 r4 = *(const LAS f32x4*)(q0 + j0), o4 = *(const LAS f32x4*)(q0 + 64 + j0), k4 = *(const LAS f32x4*)(q0 + 128 + j0), a4 = *(const LAS f32x4*)(q0 + 192 + j0), b4 = *(const LAS f32x4*)(q0 + 256 + j0);
;                 f32x2 v2 = *(const LAS f32x2*)(q0 + 320 + row0);
;                 float py0 = 0.f, py1 = 0.f;
; #pragma unroll
;                 for (int tt = 0; tt < GS; ++tt) {
;                     const LAS float* qn = q0 + (tt + 1 < GS ? tt + 1 : tt) * 384;
;                     const f32x4 nr4 = *(const LAS f32x4*)(qn + j0), no4 = *(const LAS f32x4*)(qn + 64 + j0), nk4 = *(const LAS f32x4*)(qn + 128 + j0), na4 = *(const LAS f32x4*)(qn + 192 + j0), nb4 = *(const LAS f32x4*)(qn + 256 + j0);
;                     const f32x2 nv2 = *(const LAS f32x2*)(qn + 320 + row0);
;                     f32x2 sa = (S[0] * a4[0] + S[1] * a4[1]) + (S[2] * a4[2] + S[3] * a4[3]);
;                     float sx = sa.x, sy = sa.y; ROW16_SUM4(sx, sy, py0, py1); sa = (f32x2){sx, sy};
;                     if (tt > 0) { yk0 = cgl == tt - 1 ? py0 : yk0; yk1 = cgl == tt - 1 ? py1 : yk1; }
; #pragma unroll
;                     for (int c = 0; c < 4; ++c) { f32x2 t = S[c] - S[c] * o4[c]; t = t + sa * b4[c]; S[c] = t + v2 * k4[c]; }
;                     const f32x2 y = (S[0] * r4[0] + S[1] * r4[1]) + (S[2] * r4[2] + S[3] * r4[3]);
;                     py0 = y.x; py1 = y.y;
;                     r4 = nr4; o4 = no4; k4 = nk4; a4 = na4; b4 = nb4; v2 = nv2;
.Lrw_first_chunk:
	s_waitcnt lgkmcnt(0)
	v_pk_mul_f32 v[150:151], v[66:67], v[172:173] op_sel_hi:[1,0]
	v_pk_fma_f32 v[142:143], v[66:67], v[164:165], v[66:67] op_sel_hi:[1,0,1] neg_lo:[1,0,0] neg_hi:[1,0,0]
	ds_read_b128 v[212:215], v152 offset:3840
	v_pk_fma_f32 v[150:151], v[20:21], v[172:173], v[150:151] op_sel:[0,1,0]
	v_pk_fma_f32 v[144:145], v[20:21], v[164:165], v[20:21] op_sel:[0,1,0] neg_lo:[1,0,0] neg_hi:[1,0,0]
	ds_read_b128 v[204:207], v152 offset:3328
	v_pk_fma_f32 v[150:151], v[68:69], v[174:175], v[150:151] op_sel_hi:[1,0,1]
	v_pk_fma_f32 v[146:147], v[68:69], v[166:167], v[68:69] op_sel_hi:[1,0,1] neg_lo:[1,0,0] neg_hi:[1,0,0]
	ds_read2st64_b64 v[244:247], v153 offset0:8 offset1:11
	v_pk_fma_f32 v[150:151], v[70:71], v[174:175], v[150:151] op_sel:[0,1,0]
	v_pk_fma_f32 v[148:149], v[70:71], v[166:167], v[70:71] op_sel:[0,1,0] neg_lo:[1,0,0] neg_hi:[1,0,0]
	ds_read_b128 v[208:211], v152 offset:3584
	v_pk_fma_f32 v[142:143], v[240:241], v[168:169], v[142:143] op_sel_hi:[1,0,1]
	v_pk_fma_f32 v[144:145], v[240:241], v[168:169], v[144:145] op_sel:[0,1,0]
	v_add_f32_dpp v150, v150, v150 quad_perm:[1,0,3,2] row_mask:0xf bank_mask:0xf bound_ctrl:1
	v_add_f32_dpp v151, v151, v151 quad_perm:[1,0,3,2] row_mask:0xf bank_mask:0xf bound_ctrl:1
	v_pk_fma_f32 v[146:147], v[240:241], v[170:171], v[146:147] op_sel_hi:[1,0,1]
	v_add_f32_dpp v150, v150, v150 quad_perm:[2,3,0,1] row_mask:0xf bank_mask:0xf bound_ctrl:1
	v_add_f32_dpp v151, v151, v151 quad_perm:[2,3,0,1] row_mask:0xf bank_mask:0xf bound_ctrl:1
	v_pk_fma_f32 v[148:149], v[240:241], v[170:171], v[148:149] op_sel:[0,1,0]
	v_add_f32_dpp v150, v150, v150 row_half_mirror row_mask:0xf bank_mask:0xf bound_ctrl:1
	v_add_f32_dpp v151, v151, v151 row_half_mirror row_mask:0xf bank_mask:0xf bound_ctrl:1
	ds_read_b128 v[232:235], v152 offset:5376
	v_add_f32_dpp v150, v150, v150 row_mirror row_mask:0xf bank_mask:0xf bound_ctrl:1
	v_add_f32_dpp v151, v151, v151 row_mirror row_mask:0xf bank_mask:0xf bound_ctrl:1
	ds_read_b128 v[224:227], v152 offset:4864
	ds_read_b128 v[216:219], v152 offset:4096
	ds_read_b128 v[228:231], v152 offset:5120
	ds_read_b128 v[236:239], v152 offset:5632
	ds_read_b128 v[200:203], v152 offset:3072
	ds_read_b128 v[220:223], v152 offset:4608
	v_pk_fma_f32 v[66:67], v[150:151], v[176:177], v[142:143] op_sel_hi:[1,0,1]
	v_pk_fma_f32 v[20:21], v[150:151], v[176:177], v[144:145] op_sel:[0,1,0]
	v_pk_fma_f32 v[68:69], v[150:151], v[178:179], v[146:147] op_sel_hi:[1,0,1]
	v_pk_fma_f32 v[70:71], v[150:151], v[178:179], v[148:149] op_sel:[0,1,0]
	v_pk_mul_f32 v[78:79], v[66:67], v[160:161] op_sel_hi:[1,0]
	v_pk_mul_f32 v[150:151], v[66:67], v[192:193] op_sel_hi:[1,0]
	v_pk_fma_f32 v[142:143], v[66:67], v[184:185], v[66:67] op_sel_hi:[1,0,1] neg_lo:[1,0,0] neg_hi:[1,0,0]
	v_pk_fma_f32 v[78:79], v[20:21], v[160:161], v[78:79] op_sel:[0,1,0]
	v_pk_fma_f32 v[150:151], v[20:21], v[192:193], v[150:151] op_sel:[0,1,0]
	v_pk_fma_f32 v[144:145], v[20:21], v[184:185], v[20:21] op_sel:[0,1,0] neg_lo:[1,0,0] neg_hi:[1,0,0]
	v_pk_fma_f32 v[78:79], v[68:69], v[162:163], v[78:79] op_sel_hi:[1,0,1]
	v_pk_fma_f32 v[150:151], v[68:69], v[194:195], v[150:151] op_sel_hi:[1,0,1]
	v_pk_fma_f32 v[146:147], v[68:69], v[186:187], v[68:69] op_sel_hi:[1,0,1] neg_lo:[1,0,0] neg_hi:[1,0,0]
	v_pk_fma_f32 v[78:79], v[70:71], v[162:163], v[78:79] op_sel:[0,1,0]
	v_pk_fma_f32 v[150:151], v[70:71], v[194:195], v[150:151] op_sel:[0,1,0]
	v_pk_fma_f32 v[148:149], v[70:71], v[186:187], v[70:71] op_sel:[0,1,0] neg_lo:[1,0,0] neg_hi:[1,0,0]
	v_pk_fma_f32 v[142:143], v[242:243], v[188:189], v[142:143] op_sel_hi:[1,0,1]
	v_pk_fma_f32 v[144:145], v[242:243], v[188:189], v[144:145] op_sel:[0,1,0]
	v_add_f32_dpp v150, v150, v150 quad_perm:[1,0,3,2] row_mask:0xf bank_mask:0xf bound_ctrl:1
	v_add_f32_dpp v151, v151, v151 quad_perm:[1,0,3,2] row_mask:0xf bank_mask:0xf bound_ctrl:1
	v_pk_fma_f32 v[146:147], v[242:243], v[190:191], v[146:147] op_sel_hi:[1,0,1]
	v_add_f32_dpp v150, v150, v150 quad_perm:[2,3,0,1] row_mask:0xf bank_mask:0xf bound_ctrl:1
	v_add_f32_dpp v151, v151, v151 quad_perm:[2,3,0,1] row_mask:0xf bank_mask:0xf bound_ctrl:1
	v_pk_fma_f32 v[148:149], v[242:243], v[190:191], v[148:149] op_sel:[0,1,0]
	v_add_f32_dpp v150, v150, v150 row_half_mirror row_mask:0xf bank_mask:0xf bound_ctrl:1
	v_add_f32_dpp v151, v151, v151 row_half_mirror row_mask:0xf bank_mask:0xf bound_ctrl:1
	s_nop 0
	v_add_f32_dpp v150, v150, v150 row_mirror row_mask:0xf bank_mask:0xf bound_ctrl:1
	v_add_f32_dpp v151, v151, v151 row_mirror row_mask:0xf bank_mask:0xf bound_ctrl:1
	s_waitcnt lgkmcnt(0)
; #define LAS __attribute__((address_space(3)))
; #define ROW16_SUM4(x, y, z, w) do { DPP4(x, y, z, w, "quad_perm:[1,0,3,2]", "s_nop 1"); DPP4(x, y, z, w, "quad_perm:[2,3,0,1]", ""); DPP4(x, y, z, w, "row_half_mirror", ""); DPP4(x, y, z, w, "row_mirror", ""); } while (0)
; template <bool SAMPLE>
; __device__ __forceinline__ void rwkv_unit(PR P, LAS float* lds, const int b, const int h, const int half, const int wv) {
;     ...
;                 for (int tt = 0; tt < GS; ++tt) {
;                     const LAS float* qn = q0 + (tt + 1 < GS ? tt + 1 : tt) * 384;
;                     const f32x4 nr4 = *(const LAS f32x4*)(qn + j0), no4 = *(const LAS f32x4*)(qn + 64 + j0), nk4 = *(const LAS f32x4*)(qn + 128 + j0), na4 = *(const LAS f32x4*)(qn + 192 + j0), nb4 = *(const LAS f32x4*)(qn + 256 + j0);
;                     const f32x2 nv2 = *(const LAS f32x2*)(qn + 320 + row0);
;                     f32x2 sa = (S[0] * a4[0] + S[1] * a4[1]) + (S[2] * a4[2] + S[3] * a4[3]);
;                     float sx = sa.x, sy = sa.y; ROW16_SUM4(sx, sy, py0, py1); sa = (f32x2){sx, sy};
;                     if (tt > 0) { yk0 = cgl == tt - 1 ? py0 : yk0; yk1 = cgl == tt - 1 ? py1 : yk1; }
; #pragma unroll
;                     for (int c = 0; c < 4; ++c) { f32x2 t = S[c] - S[c] * o4[c]; t = t + sa * b4[c]; S[c] = t + v2 * k4[c]; }
;                     const f32x2 y = (S[0] * r4[0] + S[1] * r4[1]) + (S[2] * r4[2] + S[3] * r4[3]);
;                     py0 = y.x; py1 = y.y;
;                     r4 = nr4; o4 = no4; k4 = nk4; a4 = na4; b4 = nb4; v2 = nv2;
	v_pk_fma_f32 v[66:67], v[150:151], v[196:197], v[142:143] op_sel_hi:[1,0,1]
	v_pk_fma_f32 v[20:21], v[150:151], v[196:197], v[144:145] op_sel:[0,1,0]
	v_pk_fma_f32 v[68:69], v[150:151], v[198:199], v[146:147] op_sel_hi:[1,0,1]
	v_pk_fma_f32 v[70:71], v[150:151], v[198:199], v[148:149] op_sel:[0,1,0]
	v_pk_mul_f32 v[80:81], v[66:67], v[180:181] op_sel_hi:[1,0]
	v_pk_mul_f32 v[150:151], v[66:67], v[212:213] op_sel_hi:[1,0]
	v_pk_fma_f32 v[142:143], v[66:67], v[204:205], v[66:67] op_sel_hi:[1,0,1] neg_lo:[1,0,0] neg_hi:[1,0,0]
	ds_read_b128 v[172:175], v152 offset:6912
	v_pk_fma_f32 v[80:81], v[20:21], v[180:181], v[80:81] op_sel:[0,1,0]
	v_pk_fma_f32 v[150:151], v[20:21], v[212:213], v[150:151] op_sel:[0,1,0]
	v_pk_fma_f32 v[144:145], v[20:21], v[204:205], v[20:21] op_sel:[0,1,0] neg_lo:[1,0,0] neg_hi:[1,0,0]
	ds_read_b128 v[164:167], v152 offset:6400
	v_pk_fma_f32 v[80:81], v[68:69], v[182:183], v[80:81] op_sel_hi:[1,0,1]
	v_pk_fma_f32 v[150:151], v[68:69], v[214:215], v[150:151] op_sel_hi:[1,0,1]
	v_pk_fma_f32 v[146:147], v[68:69], v[206:207], v[68:69] op_sel_hi:[1,0,1] neg_lo:[1,0,0] neg_hi:[1,0,0]
	ds_read2st64_b64 v[248:251], v153 offset0:14 offset1:17
	v_pk_fma_f32 v[80:81], v[70:71], v[182:183], v[80:81] op_sel:[0,1,0]
	v_pk_fma_f32 v[150:151], v[70:71], v[214:215], v[150:151] op_sel:[0,1,0]
	v_pk_fma_f32 v[148:149], v[70:71], v[206:207], v[70:71] op_sel:[0,1,0] neg_lo:[1,0,0] neg_hi:[1,0,0]
	ds_read_b128 v[168:171], v152 offset:6656
	v_pk_fma_f32 v[142:143], v[244:245], v[208:209], v[142:143] op_sel_hi:[1,0,1]
	v_pk_fma_f32 v[144:145], v[244:245], v[208:209], v[144:145] op_sel:[0,1,0]
	v_add_f32_dpp v150, v150, v150 quad_perm:[1,0,3,2] row_mask:0xf bank_mask:0xf bound_ctrl:1
	v_add_f32_dpp v151, v151, v151 quad_perm:[1,0,3,2] row_mask:0xf bank_mask:0xf bound_ctrl:1
	v_pk_fma_f32 v[146:147], v[244:245], v[210:211], v[146:147] op_sel_hi:[1,0,1]
	v_add_f32_dpp v150, v150, v150 quad_perm:[2,3,0,1] row_mask:0xf bank_mask:0xf bound_ctrl:1
	v_add_f32_dpp v151, v151, v151 quad_perm:[2,3,0,1] row_mask:0xf bank_mask:0xf bound_ctrl:1
	v_pk_fma_f32 v[148:149], v[244:245], v[210:211], v[148:149] op_sel:[0,1,0]
	v_add_f32_dpp v150, v150, v150 row_half_mirror row_mask:0xf bank_mask:0xf bound_ctrl:1
	v_add_f32_dpp v151, v151, v151 row_half_mirror row_mask:0xf bank_mask:0xf bound_ctrl:1
	ds_read_b128 v[192:195], v152 offset:8448
	v_add_f32_dpp v150, v150, v150 row_mirror row_mask:0xf bank_mask:0xf bound_ctrl:1
	v_add_f32_dpp v151, v151, v151 row_mirror row_mask:0xf bank_mask:0xf bound_ctrl:1
	ds_read_b128 v[184:187], v152 offset:7936
	ds_read_b128 v[176:179], v152 offset:7168
	ds_read_b128 v[188:191], v152 offset:8192
	ds_read_b128 v[196:199], v152 offset:8704
	ds_read_b128 v[160:163], v152 offset:6144
	ds_read_b128 v[180:183], v152 offset:7680
	v_pk_fma_f32 v[66:67], v[150:151], v[216:217], v[142:143] op_sel_hi:[1,0,1]
	v_pk_fma_f32 v[20:21], v[150:151], v[216:217], v[144:145] op_sel:[0,1,0]
	v_pk_fma_f32 v[68:69], v[150:151], v[218:219], v[146:147] op_sel_hi:[1,0,1]
	v_pk_fma_f32 v[70:71], v[150:151], v[218:219], v[148:149] op_sel:[0,1,0]
	v_pk_mul_f32 v[82:83], v[66:67], v[200:201] op_sel_hi:[1,0]
	v_pk_mul_f32 v[150:151], v[66:67], v[232:233] op_sel_hi:[1,0]
	v_pk_fma_f32 v[142:143], v[66:67], v[224:225], v[66:67] op_sel_hi:[1,0,1] neg_lo:[1,0,0] neg_hi:[1,0,0]
	v_pk_fma_f32 v[82:83], v[20:21], v[200:201], v[82:83] op_sel:[0,1,0]
	v_pk_fma_f32 v[150:151], v[20:21], v[232:233], v[150:151] op_sel:[0,1,0]
	v_pk_fma_f32 v[144:145], v[20:21], v[224:225], v[20:21] op_sel:[0,1,0] neg_lo:[1,0,0] neg_hi:[1,0,0]
	v_pk_fma_f32 v[82:83], v[68:69], v[202:203], v[82:83] op_sel_hi:[1,0,1]
	v_pk_fma_f32 v[150:151], v[68:69], v[234:235], v[150:151] op_sel_hi:[1,0,1]
	v_pk_fma_f32 v[146:147], v[68:69], v[226:227], v[68:69] op_sel_hi:[1,0,1] neg_lo:[1,0,0] neg_hi:[1,0,0]
	v_pk_fma_f32 v[82:83], v[70:71], v[202:203], v[82:83] op_sel:[0,1,0]
	v_pk_fma_f32 v[150:151], v[70:71], v[234:235], v[150:151] op_sel:[0,1,0]
	v_pk_fma_f32 v[148:149], v[70:71], v[226:227], v[70:71] op_sel:[0,1,0] neg_lo:[1,0,0] neg_hi:[1,0,0]
	v_pk_fma_f32 v[142:143], v[246:247], v[228:229], v[142:143] op_sel_hi:[1,0,1]
	v_pk_fma_f32 v[144:145], v[246:247], v[228:229], v[144:145] op_sel:[0,1,0]
	v_add_f32_dpp v150, v150, v150 quad_perm:[1,0,3,2] row_mask:0xf bank_mask:0xf bound_ctrl:1
	v_add_f32_dpp v151, v151, v151 quad_perm:[1,0,3,2] row_mask:0xf bank_mask:0xf bound_ctrl:1
	v_pk_fma_f32 v[146:147], v[246:247], v[230:231], v[146:147] op_sel_hi:[1,0,1]
	v_add_f32_dpp v150, v150, v150 quad_perm:[2,3,0,1] row_mask:0xf bank_mask:0xf bound_ctrl:1
	v_add_f32_dpp v151, v151, v151 quad_perm:[2,3,0,1] row_mask:0xf bank_mask:0xf bound_ctrl:1
	v_pk_fma_f32 v[148:149], v[246:247], v[230:231], v[148:149] op_sel:[0,1,0]
	v_add_f32_dpp v150, v150, v150 row_half_mirror row_mask:0xf bank_mask:0xf bound_ctrl:1
	v_add_f32_dpp v151, v151, v151 row_half_mirror row_mask:0xf bank_mask:0xf bound_ctrl:1
	s_nop 0
	v_add_f32_dpp v150, v150, v150 row_mirror row_mask:0xf bank_mask:0xf bound_ctrl:1
	v_add_f32_dpp v151, v151, v151 row_mirror row_mask:0xf bank_mask:0xf bound_ctrl:1
	s_waitcnt lgkmcnt(0)
; #define LAS __attribute__((address_space(3)))
; #define ROW16_SUM4(x, y, z, w) do { DPP4(x, y, z, w, "quad_perm:[1,0,3,2]", "s_nop 1"); DPP4(x, y, z, w, "quad_perm:[2,3,0,1]", ""); DPP4(x, y, z, w, "row_half_mirror", ""); DPP4(x, y, z, w, "row_mirror", ""); } while (0)
; template <bool SAMPLE>
; __device__ __forceinline__ void rwkv_unit(PR P, LAS float* lds, const int b, const int h, const int half, const int wv) {
;     ...
;                 for (int tt = 0; tt < GS; ++tt) {
;                     const LAS float* qn = q0 + (tt + 1 < GS ? tt + 1 : tt) * 384;
;                     const f32x4 nr4 = *(const LAS f32x4*)(qn + j0), no4 = *(const LAS f32x4*)(qn + 64 + j0), nk4 = *(const LAS f32x4*)(qn + 128 + j0), na4 = *(const LAS f32x4*)(qn + 192 + j0), nb4 = *(const LAS f32x4*)(qn + 256 + j0);
;                     const f32x2 nv2 = *(const LAS f32x2*)(qn + 320 + row0);
;                     f32x2 sa = (S[0] * a4[0] + S[1] * a4[1]) + (S[2] * a4[2] + S[3] * a4[3]);
;                     float sx = sa.x, sy = sa.y; ROW16_SUM4(sx, sy, py0, py1); sa = (f32x2){sx, sy};
;                     if (tt > 0) { yk0 = cgl == tt - 1 ? py0 : yk0; yk1 = cgl == tt - 1 ? py1 : yk1; }
; #pragma unroll
;                     for (int c = 0; c < 4; ++c) { f32x2 t = S[c] - S[c] * o4[c]; t = t + sa * b4[c]; S[c] = t + v2 * k4[c]; }
;                     const f32x2 y = (S[0] * r4[0] + S[1] * r4[1]) + (S[2] * r4[2] + S[3] * r4[3]);
;                     py0 = y.x; py1 = y.y;
;                     r4 = nr4; o4 = no4; k4 = nk4; a4 = na4; b4 = nb4; v2 = nv2;
	v_pk_fma_f32 v[66:67], v[150:151], v[236:237], v[142:143] op_sel_hi:[1,0,1]
	v_pk_fma_f32 v[20:21], v[150:151], v[236:237], v[144:145] op_sel:[0,1,0]
	v_pk_fma_f32 v[68:69], v[150:151], v[238:239], v[146:147] op_sel_hi:[1,0,1]
	v_pk_fma_f32 v[70:71], v[150:151], v[238:239], v[148:149] op_sel:[0,1,0]
	v_pk_mul_f32 v[84:85], v[66:67], v[220:221] op_sel_hi:[1,0]
	v_pk_mul_f32 v[150:151], v[66:67], v[172:173] op_sel_hi:[1,0]
	v_pk_fma_f32 v[142:143], v[66:67], v[164:165], v[66:67] op_sel_hi:[1,0,1] neg_lo:[1,0,0] neg_hi:[1,0,0]
	ds_read_b128 v[212:215], v152 offset:9984
	v_pk_fma_f32 v[84:85], v[20:21], v[220:221], v[84:85] op_sel:[0,1,0]
	v_pk_fma_f32 v[150:151], v[20:21], v[172:173], v[150:151] op_sel:[0,1,0]
	v_pk_fma_f32 v[144:145], v[20:21], v[164:165], v[20:21] op_sel:[0,1,0] neg_lo:[1,0,0] neg_hi:[1,0,0]
	ds_read_b128 v[204:207], v152 offset:9472
	v_pk_fma_f32 v[84:85], v[68:69], v[222:223], v[84:85] op_sel_hi:[1,0,1]
	v_pk_fma_f32 v[150:151], v[68:69], v[174:175], v[150:151] op_sel_hi:[1,0,1]
	v_pk_fma_f32 v[146:147], v[68:69], v[166:167], v[68:69] op_sel_hi:[1,0,1] neg_lo:[1,0,0] neg_hi:[1,0,0]
	ds_read2st64_b64 v[240:243], v153 offset0:20 offset1:23
	v_pk_fma_f32 v[84:85], v[70:71], v[222:223], v[84:85] op_sel:[0,1,0]
	v_pk_fma_f32 v[150:151], v[70:71], v[174:175], v[150:151] op_sel:[0,1,0]
	v_pk_fma_f32 v[148:149], v[70:71], v[166:167], v[70:71] op_sel:[0,1,0] neg_lo:[1,0,0] neg_hi:[1,0,0]
	ds_read_b128 v[208:211], v152 offset:9728
	v_pk_fma_f32 v[142:143], v[248:249], v[168:169], v[142:143] op_sel_hi:[1,0,1]
	v_pk_fma_f32 v[144:145], v[248:249], v[168:169], v[144:145] op_sel:[0,1,0]
	v_add_f32_dpp v150, v150, v150 quad_perm:[1,0,3,2] row_mask:0xf bank_mask:0xf bound_ctrl:1
	v_add_f32_dpp v151, v151, v151 quad_perm:[1,0,3,2] row_mask:0xf bank_mask:0xf bound_ctrl:1
	v_pk_fma_f32 v[146:147], v[248:249], v[170:171], v[146:147] op_sel_hi:[1,0,1]
	v_add_f32_dpp v150, v150, v150 quad_perm:[2,3,0,1] row_mask:0xf bank_mask:0xf bound_ctrl:1
	v_add_f32_dpp v151, v151, v151 quad_perm:[2,3,0,1] row_mask:0xf bank_mask:0xf bound_ctrl:1
	v_pk_fma_f32 v[148:149], v[248:249], v[170:171], v[148:149] op_sel:[0,1,0]
	v_add_f32_dpp v150, v150, v150 row_half_mirror row_mask:0xf bank_mask:0xf bound_ctrl:1
	v_add_f32_dpp v151, v151, v151 row_half_mirror row_mask:0xf bank_mask:0xf bound_ctrl:1
	ds_read_b128 v[232:235], v152 offset:11520
	v_add_f32_dpp v150, v150, v150 row_mirror row_mask:0xf bank_mask:0xf bound_ctrl:1
	v_add_f32_dpp v151, v151, v151 row_mirror row_mask:0xf bank_mask:0xf bound_ctrl:1
	ds_read_b128 v[224:227], v152 offset:11008
	ds_read_b128 v[216:219], v152 offset:10240
	ds_read_b128 v[228:231], v152 offset:11264
	ds_read_b128 v[236:239], v152 offset:11776
	ds_read_b128 v[200:203], v152 offset:9216
	ds_read_b128 v[220:223], v152 offset:10752
	v_pk_fma_f32 v[66:67], v[150:151], v[176:177], v[142:143] op_sel_hi:[1,0,1]
	v_pk_fma_f32 v[20:21], v[150:151], v[176:177], v[144:145] op_sel:[0,1,0]
	v_pk_fma_f32 v[68:69], v[150:151], v[178:179], v[146:147] op_sel_hi:[1,0,1]
	v_pk_fma_f32 v[70:71], v[150:151], v[178:179], v[148:149] op_sel:[0,1,0]
	v_pk_mul_f32 v[86:87], v[66:67], v[160:161] op_sel_hi:[1,0]
	v_pk_mul_f32 v[150:151], v[66:67], v[192:193] op_sel_hi:[1,0]
	v_pk_fma_f32 v[142:143], v[66:67], v[184:185], v[66:67] op_sel_hi:[1,0,1] neg_lo:[1,0,0] neg_hi:[1,0,0]
	v_pk_fma_f32 v[86:87], v[20:21], v[160:161], v[86:87] op_sel:[0,1,0]
	v_pk_fma_f32 v[150:151], v[20:21], v[192:193], v[150:151] op_sel:[0,1,0]
	v_pk_fma_f32 v[144:145], v[20:21], v[184:185], v[20:21] op_sel:[0,1,0] neg_lo:[1,0,0] neg_hi:[1,0,0]
	v_pk_fma_f32 v[86:87], v[68:69], v[162:163], v[86:87] op_sel_hi:[1,0,1]
	v_pk_fma_f32 v[150:151], v[68:69], v[194:195], v[150:151] op_sel_hi:[1,0,1]
	v_pk_fma_f32 v[146:147], v[68:69], v[186:187], v[68:69] op_sel_hi:[1,0,1] neg_lo:[1,0,0] neg_hi:[1,0,0]
	v_pk_fma_f32 v[86:87], v[70:71], v[162:163], v[86:87] op_sel:[0,1,0]
	v_pk_fma_f32 v[150:151], v[70:71], v[194:195], v[150:151] op_sel:[0,1,0]
	v_pk_fma_f32 v[148:149], v[70:71], v[186:187], v[70:71] op_sel:[0,1,0] neg_lo:[1,0,0] neg_hi:[1,0,0]
	v_pk_fma_f32 v[142:143], v[250:251], v[188:189], v[142:143] op_sel_hi:[1,0,1]
	v_pk_fma_f32 v[144:145], v[250:251], v[188:189], v[144:145] op_sel:[0,1,0]
	v_add_f32_dpp v150, v150, v150 quad_perm:[1,0,3,2] row_mask:0xf bank_mask:0xf bound_ctrl:1
	v_add_f32_dpp v151, v151, v151 quad_perm:[1,0,3,2] row_mask:0xf bank_mask:0xf bound_ctrl:1
	v_pk_fma_f32 v[146:147], v[250:251], v[190:191], v[146:147] op_sel_hi:[1,0,1]
	v_add_f32_dpp v150, v150, v150 quad_perm:[2,3,0,1] row_mask:0xf bank_mask:0xf bound_ctrl:1
	v_add_f32_dpp v151, v151, v151 quad_perm:[2,3,0,1] row_mask:0xf bank_mask:0xf bound_ctrl:1
	v_pk_fma_f32 v[148:149], v[250:251], v[190:191], v[148:149] op_sel:[0,1,0]
	v_add_f32_dpp v150, v150, v150 row_half_mirror row_mask:0xf bank_mask:0xf bound_ctrl:1
	v_add_f32_dpp v151, v151, v151 row_half_mirror row_mask:0xf bank_mask:0xf bound_ctrl:1
	s_nop 0
	v_add_f32_dpp v150, v150, v150 row_mirror row_mask:0xf bank_mask:0xf bound_ctrl:1
	v_add_f32_dpp v151, v151, v151 row_mirror row_mask:0xf bank_mask:0xf bound_ctrl:1
	s_waitcnt lgkmcnt(0)
; #define LAS __attribute__((address_space(3)))
; #define ROW16_SUM4(x, y, z, w) do { DPP4(x, y, z, w, "quad_perm:[1,0,3,2]", "s_nop 1"); DPP4(x, y, z, w, "quad_perm:[2,3,0,1]", ""); DPP4(x, y, z, w, "row_half_mirror", ""); DPP4(x, y, z, w, "row_mirror", ""); } while (0)
; template <bool SAMPLE>
; __device__ __forceinline__ void rwkv_unit(PR P, LAS float* lds, const int b, const int h, const int half, const int wv) {
;     ...
;                 for (int tt = 0; tt < GS; ++tt) {
;                     const LAS float* qn = q0 + (tt + 1 < GS ? tt + 1 : tt) * 384;
;                     const f32x4 nr4 = *(const LAS f32x4*)(qn + j0), no4 = *(const LAS f32x4*)(qn + 64 + j0), nk4 = *(const LAS f32x4*)(qn + 128 + j0), na4 = *(const LAS f32x4*)(qn + 192 + j0), nb4 = *(const LAS f32x4*)(qn + 256 + j0);
;                     const f32x2 nv2 = *(const LAS f32x2*)(qn + 320 + row0);
;                     f32x2 sa = (S[0] * a4[0] + S[1] * a4[1]) + (S[2] * a4[2] + S[3] * a4[3]);
;                     float sx = sa.x, sy = sa.y; ROW16_SUM4(sx, sy, py0, py1); sa = (f32x2){sx, sy};
;                     if (tt > 0) { yk0 = cgl == tt - 1 ? py0 : yk0; yk1 = cgl == tt - 1 ? py1 : yk1; }
; #pragma unroll
;                     for (int c = 0; c < 4; ++c) { f32x2 t = S[c] - S[c] * o4[c]; t = t + sa * b4[c]; S[c] = t + v2 * k4[c]; }
;                     const f32x2 y = (S[0] * r4[0] + S[1] * r4[1]) + (S[2] * r4[2] + S[3] * r4[3]);
;                     py0 = y.x; py1 = y.y;
;                     r4 = nr4; o4 = no4; k4 = nk4; a4 = na4; b4 = nb4; v2 = nv2;
	v_pk_fma_f32 v[66:67], v[150:151], v[196:197], v[142:143] op_sel_hi:[1,0,1]
	v_pk_fma_f32 v[20:21], v[150:151], v[196:197], v[144:145] op_sel:[0,1,0]
	v_pk_fma_f32 v[68:69], v[150:151], v[198:199], v[146:147] op_sel_hi:[1,0,1]
	v_pk_fma_f32 v[70:71], v[150:151], v[198:199], v[148:149] op_sel:[0,1,0]
	v_pk_mul_f32 v[88:89], v[66:67], v[180:181] op_sel_hi:[1,0]
	v_pk_mul_f32 v[150:151], v[66:67], v[212:213] op_sel_hi:[1,0]
	v_pk_fma_f32 v[142:143], v[66:67], v[204:205], v[66:67] op_sel_hi:[1,0,1] neg_lo:[1,0,0] neg_hi:[1,0,0]
	ds_read_b128 v[172:175], v152 offset:13056
	v_pk_fma_f32 v[88:89], v[20:21], v[180:181], v[88:89] op_sel:[0,1,0]
	v_pk_fma_f32 v[150:151], v[20:21], v[212:213], v[150:151] op_sel:[0,1,0]
	v_pk_fma_f32 v[144:145], v[20:21], v[204:205], v[20:21] op_sel:[0,1,0] neg_lo:[1,0,0] neg_hi:[1,0,0]
	ds_read_b128 v[164:167], v152 offset:12544
	v_pk_fma_f32 v[88:89], v[68:69], v[182:183], v[88:89] op_sel_hi:[1,0,1]
	v_pk_fma_f32 v[150:151], v[68:69], v[214:215], v[150:151] op_sel_hi:[1,0,1]
	v_pk_fma_f32 v[146:147], v[68:69], v[206:207], v[68:69] op_sel_hi:[1,0,1] neg_lo:[1,0,0] neg_hi:[1,0,0]
	ds_read2st64_b64 v[244:247], v153 offset0:26 offset1:29
	v_pk_fma_f32 v[88:89], v[70:71], v[182:183], v[88:89] op_sel:[0,1,0]
	v_pk_fma_f32 v[150:151], v[70:71], v[214:215], v[150:151] op_sel:[0,1,0]
	v_pk_fma_f32 v[148:149], v[70:71], v[206:207], v[70:71] op_sel:[0,1,0] neg_lo:[1,0,0] neg_hi:[1,0,0]
	ds_read_b128 v[168:171], v152 offset:12800
	v_pk_fma_f32 v[142:143], v[240:241], v[208:209], v[142:143] op_sel_hi:[1,0,1]
	v_pk_fma_f32 v[144:145], v[240:241], v[208:209], v[144:145] op_sel:[0,1,0]
	v_add_f32_dpp v150, v150, v150 quad_perm:[1,0,3,2] row_mask:0xf bank_mask:0xf bound_ctrl:1
	v_add_f32_dpp v151, v151, v151 quad_perm:[1,0,3,2] row_mask:0xf bank_mask:0xf bound_ctrl:1
	v_pk_fma_f32 v[146:147], v[240:241], v[210:211], v[146:147] op_sel_hi:[1,0,1]
	v_add_f32_dpp v150, v150, v150 quad_perm:[2,3,0,1] row_mask:0xf bank_mask:0xf bound_ctrl:1
	v_add_f32_dpp v151, v151, v151 quad_perm:[2,3,0,1] row_mask:0xf bank_mask:0xf bound_ctrl:1
	v_pk_fma_f32 v[148:149], v[240:241], v[210:211], v[148:149] op_sel:[0,1,0]
	v_add_f32_dpp v150, v150, v150 row_half_mirror row_mask:0xf bank_mask:0xf bound_ctrl:1
	v_add_f32_dpp v151, v151, v151 row_half_mirror row_mask:0xf bank_mask:0xf bound_ctrl:1
	ds_read_b128 v[192:195], v152 offset:14592
	v_add_f32_dpp v150, v150, v150 row_mirror row_mask:0xf bank_mask:0xf bound_ctrl:1
	v_add_f32_dpp v151, v151, v151 row_mirror row_mask:0xf bank_mask:0xf bound_ctrl:1
	ds_read_b128 v[184:187], v152 offset:14080
	ds_read_b128 v[176:179], v152 offset:13312
	ds_read_b128 v[188:191], v152 offset:14336
	ds_read_b128 v[196:199], v152 offset:14848
	ds_read_b128 v[160:163], v152 offset:12288
	ds_read_b128 v[180:183], v152 offset:13824
	v_pk_fma_f32 v[66:67], v[150:151], v[216:217], v[142:143] op_sel_hi:[1,0,1]
	v_pk_fma_f32 v[20:21], v[150:151], v[216:217], v[144:145] op_sel:[0,1,0]
	v_pk_fma_f32 v[68:69], v[150:151], v[218:219], v[146:147] op_sel_hi:[1,0,1]
	v_pk_fma_f32 v[70:71], v[150:151], v[218:219], v[148:149] op_sel:[0,1,0]
	v_pk_mul_f32 v[90:91], v[66:67], v[200:201] op_sel_hi:[1,0]
	v_pk_mul_f32 v[150:151], v[66:67], v[232:233] op_sel_hi:[1,0]
	v_pk_fma_f32 v[142:143], v[66:67], v[224:225], v[66:67] op_sel_hi:[1,0,1] neg_lo:[1,0,0] neg_hi:[1,0,0]
	v_pk_fma_f32 v[90:91], v[20:21], v[200:201], v[90:91] op_sel:[0,1,0]
	v_pk_fma_f32 v[150:151], v[20:21], v[232:233], v[150:151] op_sel:[0,1,0]
	v_pk_fma_f32 v[144:145], v[20:21], v[224:225], v[20:21] op_sel:[0,1,0] neg_lo:[1,0,0] neg_hi:[1,0,0]
	v_pk_fma_f32 v[90:91], v[68:69], v[202:203], v[90:91] op_sel_hi:[1,0,1]
	v_pk_fma_f32 v[150:151], v[68:69], v[234:235], v[150:151] op_sel_hi:[1,0,1]
	v_pk_fma_f32 v[146:147], v[68:69], v[226:227], v[68:69] op_sel_hi:[1,0,1] neg_lo:[1,0,0] neg_hi:[1,0,0]
	v_pk_fma_f32 v[90:91], v[70:71], v[202:203], v[90:91] op_sel:[0,1,0]
	v_pk_fma_f32 v[150:151], v[70:71], v[234:235], v[150:151] op_sel:[0,1,0]
	v_pk_fma_f32 v[148:149], v[70:71], v[226:227], v[70:71] op_sel:[0,1,0] neg_lo:[1,0,0] neg_hi:[1,0,0]
	v_pk_fma_f32 v[142:143], v[242:243], v[228:229], v[142:143] op_sel_hi:[1,0,1]
	v_pk_fma_f32 v[144:145], v[242:243], v[228:229], v[144:145] op_sel:[0,1,0]
	v_add_f32_dpp v150, v150, v150 quad_perm:[1,0,3,2] row_mask:0xf bank_mask:0xf bound_ctrl:1
	v_add_f32_dpp v151, v151, v151 quad_perm:[1,0,3,2] row_mask:0xf bank_mask:0xf bound_ctrl:1
	v_pk_fma_f32 v[146:147], v[242:243], v[230:231], v[146:147] op_sel_hi:[1,0,1]
	v_add_f32_dpp v150, v150, v150 quad_perm:[2,3,0,1] row_mask:0xf bank_mask:0xf bound_ctrl:1
	v_add_f32_dpp v151, v151, v151 quad_perm:[2,3,0,1] row_mask:0xf bank_mask:0xf bound_ctrl:1
	v_pk_fma_f32 v[148:149], v[242:243], v[230:231], v[148:149] op_sel:[0,1,0]
	v_add_f32_dpp v150, v150, v150 row_half_mirror row_mask:0xf bank_mask:0xf bound_ctrl:1
	v_add_f32_dpp v151, v151, v151 row_half_mirror row_mask:0xf bank_mask:0xf bound_ctrl:1
	s_nop 0
	v_add_f32_dpp v150, v150, v150 row_mirror row_mask:0xf bank_mask:0xf bound_ctrl:1
	v_add_f32_dpp v151, v151, v151 row_mirror row_mask:0xf bank_mask:0xf bound_ctrl:1
	s_waitcnt lgkmcnt(0)
; #define LAS __attribute__((address_space(3)))
; #define ROW16_SUM4(x, y, z, w) do { DPP4(x, y, z, w, "quad_perm:[1,0,3,2]", "s_nop 1"); DPP4(x, y, z, w, "quad_perm:[2,3,0,1]", ""); DPP4(x, y, z, w, "row_half_mirror", ""); DPP4(x, y, z, w, "row_mirror", ""); } while (0)
; template <bool SAMPLE>
; __device__ __forceinline__ void rwkv_unit(PR P, LAS float* lds, const int b, const int h, const int half, const int wv) {
;     ...
;                 for (int tt = 0; tt < GS; ++tt) {
;                     const LAS float* qn = q0 + (tt + 1 < GS ? tt + 1 : tt) * 384;
;                     const f32x4 nr4 = *(const LAS f32x4*)(qn + j0), no4 = *(const LAS f32x4*)(qn + 64 + j0), nk4 = *(const LAS f32x4*)(qn + 128 + j0), na4 = *(const LAS f32x4*)(qn + 192 + j0), nb4 = *(const LAS f32x4*)(qn + 256 + j0);
;                     const f32x2 nv2 = *(const LAS f32x2*)(qn + 320 + row0);
;                     f32x2 sa = (S[0] * a4[0] + S[1] * a4[1]) + (S[2] * a4[2] + S[3] * a4[3]);
;                     float sx = sa.x, sy = sa.y; ROW16_SUM4(sx, sy, py0, py1); sa = (f32x2){sx, sy};
;                     if (tt > 0) { yk0 = cgl == tt - 1 ? py0 : yk0; yk1 = cgl == tt - 1 ? py1 : yk1; }
; #pragma unroll
;                     for (int c = 0; c < 4; ++c) { f32x2 t = S[c] - S[c] * o4[c]; t = t + sa * b4[c]; S[c] = t + v2 * k4[c]; }
;                     const f32x2 y = (S[0] * r4[0] + S[1] * r4[1]) + (S[2] * r4[2] + S[3] * r4[3]);
;                     py0 = y.x; py1 = y.y;
;                     r4 = nr4; o4 = no4; k4 = nk4; a4 = na4; b4 = nb4; v2 = nv2;
	v_pk_fma_f32 v[66:67], v[150:151], v[236:237], v[142:143] op_sel_hi:[1,0,1]
	v_pk_fma_f32 v[20:21], v[150:151], v[236:237], v[144:145] op_sel:[0,1,0]
	v_pk_fma_f32 v[68:69], v[150:151], v[238:239], v[146:147] op_sel_hi:[1,0,1]
	v_pk_fma_f32 v[70:71], v[150:151], v[238:239], v[148:149] op_sel:[0,1,0]
	v_pk_mul_f32 v[92:93], v[66:67], v[220:221] op_sel_hi:[1,0]
	v_pk_mul_f32 v[150:151], v[66:67], v[172:173] op_sel_hi:[1,0]
	v_pk_fma_f32 v[142:143], v[66:67], v[164:165], v[66:67] op_sel_hi:[1,0,1] neg_lo:[1,0,0] neg_hi:[1,0,0]
	ds_read_b128 v[212:215], v152 offset:16128
	v_pk_fma_f32 v[92:93], v[20:21], v[220:221], v[92:93] op_sel:[0,1,0]
	v_pk_fma_f32 v[150:151], v[20:21], v[172:173], v[150:151] op_sel:[0,1,0]
	v_pk_fma_f32 v[144:145], v[20:21], v[164:165], v[20:21] op_sel:[0,1,0] neg_lo:[1,0,0] neg_hi:[1,0,0]
	ds_read_b128 v[204:207], v152 offset:15616
	v_pk_fma_f32 v[92:93], v[68:69], v[222:223], v[92:93] op_sel_hi:[1,0,1]
	v_pk_fma_f32 v[150:151], v[68:69], v[174:175], v[150:151] op_sel_hi:[1,0,1]
	v_pk_fma_f32 v[146:147], v[68:69], v[166:167], v[68:69] op_sel_hi:[1,0,1] neg_lo:[1,0,0] neg_hi:[1,0,0]
	ds_read2st64_b64 v[248:251], v153 offset0:32 offset1:35
	v_pk_fma_f32 v[92:93], v[70:71], v[222:223], v[92:93] op_sel:[0,1,0]
	v_pk_fma_f32 v[150:151], v[70:71], v[174:175], v[150:151] op_sel:[0,1,0]
	v_pk_fma_f32 v[148:149], v[70:71], v[166:167], v[70:71] op_sel:[0,1,0] neg_lo:[1,0,0] neg_hi:[1,0,0]
	ds_read_b128 v[208:211], v152 offset:15872
	v_pk_fma_f32 v[142:143], v[244:245], v[168:169], v[142:143] op_sel_hi:[1,0,1]
	v_pk_fma_f32 v[144:145], v[244:245], v[168:169], v[144:145] op_sel:[0,1,0]
	v_add_f32_dpp v150, v150, v150 quad_perm:[1,0,3,2] row_mask:0xf bank_mask:0xf bound_ctrl:1
	v_add_f32_dpp v151, v151, v151 quad_perm:[1,0,3,2] row_mask:0xf bank_mask:0xf bound_ctrl:1
	v_pk_fma_f32 v[146:147], v[244:245], v[170:171], v[146:147] op_sel_hi:[1,0,1]
	v_add_f32_dpp v150, v150, v150 quad_perm:[2,3,0,1] row_mask:0xf bank_mask:0xf bound_ctrl:1
	v_add_f32_dpp v151, v151, v151 quad_perm:[2,3,0,1] row_mask:0xf bank_mask:0xf bound_ctrl:1
	v_pk_fma_f32 v[148:149], v[244:245], v[170:171], v[148:149] op_sel:[0,1,0]
	v_add_f32_dpp v150, v150, v150 row_half_mirror row_mask:0xf bank_mask:0xf bound_ctrl:1
	v_add_f32_dpp v151, v151, v151 row_half_mirror row_mask:0xf bank_mask:0xf bound_ctrl:1
	ds_read_b128 v[232:235], v152 offset:17664
	v_add_f32_dpp v150, v150, v150 row_mirror row_mask:0xf bank_mask:0xf bound_ctrl:1
	v_add_f32_dpp v151, v151, v151 row_mirror row_mask:0xf bank_mask:0xf bound_ctrl:1
	ds_read_b128 v[224:227], v152 offset:17152
	ds_read_b128 v[216:219], v152 offset:16384
	ds_read_b128 v[228:231], v152 offset:17408
	ds_read_b128 v[236:239], v152 offset:17920
	ds_read_b128 v[200:203], v152 offset:15360
	ds_read_b128 v[220:223], v152 offset:16896
	v_pk_fma_f32 v[66:67], v[150:151], v[176:177], v[142:143] op_sel_hi:[1,0,1]
	v_pk_fma_f32 v[20:21], v[150:151], v[176:177], v[144:145] op_sel:[0,1,0]
	v_pk_fma_f32 v[68:69], v[150:151], v[178:179], v[146:147] op_sel_hi:[1,0,1]
	v_pk_fma_f32 v[70:71], v[150:151], v[178:179], v[148:149] op_sel:[0,1,0]
	v_pk_mul_f32 v[94:95], v[66:67], v[160:161] op_sel_hi:[1,0]
	v_pk_mul_f32 v[150:151], v[66:67], v[192:193] op_sel_hi:[1,0]
	v_pk_fma_f32 v[142:143], v[66:67], v[184:185], v[66:67] op_sel_hi:[1,0,1] neg_lo:[1,0,0] neg_hi:[1,0,0]
	v_pk_fma_f32 v[94:95], v[20:21], v[160:161], v[94:95] op_sel:[0,1,0]
	v_pk_fma_f32 v[150:151], v[20:21], v[192:193], v[150:151] op_sel:[0,1,0]
	v_pk_fma_f32 v[144:145], v[20:21], v[184:185], v[20:21] op_sel:[0,1,0] neg_lo:[1,0,0] neg_hi:[1,0,0]
	v_pk_fma_f32 v[94:95], v[68:69], v[162:163], v[94:95] op_sel_hi:[1,0,1]
	v_pk_fma_f32 v[150:151], v[68:69], v[194:195], v[150:151] op_sel_hi:[1,0,1]
	v_pk_fma_f32 v[146:147], v[68:69], v[186:187], v[68:69] op_sel_hi:[1,0,1] neg_lo:[1,0,0] neg_hi:[1,0,0]
	v_pk_fma_f32 v[94:95], v[70:71], v[162:163], v[94:95] op_sel:[0,1,0]
	v_pk_fma_f32 v[150:151], v[70:71], v[194:195], v[150:151] op_sel:[0,1,0]
	v_pk_fma_f32 v[148:149], v[70:71], v[186:187], v[70:71] op_sel:[0,1,0] neg_lo:[1,0,0] neg_hi:[1,0,0]
	v_pk_fma_f32 v[142:143], v[246:247], v[188:189], v[142:143] op_sel_hi:[1,0,1]
	v_pk_fma_f32 v[144:145], v[246:247], v[188:189], v[144:145] op_sel:[0,1,0]
	v_add_f32_dpp v150, v150, v150 quad_perm:[1,0,3,2] row_mask:0xf bank_mask:0xf bound_ctrl:1
	v_add_f32_dpp v151, v151, v151 quad_perm:[1,0,3,2] row_mask:0xf bank_mask:0xf bound_ctrl:1
	v_pk_fma_f32 v[146:147], v[246:247], v[190:191], v[146:147] op_sel_hi:[1,0,1]
	v_add_f32_dpp v150, v150, v150 quad_perm:[2,3,0,1] row_mask:0xf bank_mask:0xf bound_ctrl:1
	v_add_f32_dpp v151, v151, v151 quad_perm:[2,3,0,1] row_mask:0xf bank_mask:0xf bound_ctrl:1
	v_pk_fma_f32 v[148:149], v[246:247], v[190:191], v[148:149] op_sel:[0,1,0]
	v_add_f32_dpp v150, v150, v150 row_half_mirror row_mask:0xf bank_mask:0xf bound_ctrl:1
	v_add_f32_dpp v151, v151, v151 row_half_mirror row_mask:0xf bank_mask:0xf bound_ctrl:1
	s_nop 0
	v_add_f32_dpp v150, v150, v150 row_mirror row_mask:0xf bank_mask:0xf bound_ctrl:1
	v_add_f32_dpp v151, v151, v151 row_mirror row_mask:0xf bank_mask:0xf bound_ctrl:1
	s_waitcnt lgkmcnt(0)
; #define LAS __attribute__((address_space(3)))
; #define ROW16_SUM4(x, y, z, w) do { DPP4(x, y, z, w, "quad_perm:[1,0,3,2]", "s_nop 1"); DPP4(x, y, z, w, "quad_perm:[2,3,0,1]", ""); DPP4(x, y, z, w, "row_half_mirror", ""); DPP4(x, y, z, w, "row_mirror", ""); } while (0)
; template <bool SAMPLE>
; __device__ __forceinline__ void rwkv_unit(PR P, LAS float* lds, const int b, const int h, const int half, const int wv) {
;     ...
;                 for (int tt = 0; tt < GS; ++tt) {
;                     const LAS float* qn = q0 + (tt + 1 < GS ? tt + 1 : tt) * 384;
;                     const f32x4 nr4 = *(const LAS f32x4*)(qn + j0), no4 = *(const LAS f32x4*)(qn + 64 + j0), nk4 = *(const LAS f32x4*)(qn + 128 + j0), na4 = *(const LAS f32x4*)(qn + 192 + j0), nb4 = *(const LAS f32x4*)(qn + 256 + j0);
;                     const f32x2 nv2 = *(const LAS f32x2*)(qn + 320 + row0);
;                     f32x2 sa = (S[0] * a4[0] + S[1] * a4[1]) + (S[2] * a4[2] + S[3] * a4[3]);
;                     float sx = sa.x, sy = sa.y; ROW16_SUM4(sx, sy, py0, py1); sa = (f32x2){sx, sy};
;                     if (tt > 0) { yk0 = cgl == tt - 1 ? py0 : yk0; yk1 = cgl == tt - 1 ? py1 : yk1; }
; #pragma unroll
;                     for (int c = 0; c < 4; ++c) { f32x2 t = S[c] - S[c] * o4[c]; t = t + sa * b4[c]; S[c] = t + v2 * k4[c]; }
;                     const f32x2 y = (S[0] * r4[0] + S[1] * r4[1]) + (S[2] * r4[2] + S[3] * r4[3]);
;                     py0 = y.x; py1 = y.y;
;                     r4 = nr4; o4 = no4; k4 = nk4; a4 = na4; b4 = nb4; v2 = nv2;
	v_pk_fma_f32 v[66:67], v[150:151], v[196:197], v[142:143] op_sel_hi:[1,0,1]
	v_pk_fma_f32 v[20:21], v[150:151], v[196:197], v[144:145] op_sel:[0,1,0]
	v_pk_fma_f32 v[68:69], v[150:151], v[198:199], v[146:147] op_sel_hi:[1,0,1]
	v_pk_fma_f32 v[70:71], v[150:151], v[198:199], v[148:149] op_sel:[0,1,0]
	v_pk_mul_f32 v[96:97], v[66:67], v[180:181] op_sel_hi:[1,0]
	v_pk_mul_f32 v[150:151], v[66:67], v[212:213] op_sel_hi:[1,0]
	v_pk_fma_f32 v[142:143], v[66:67], v[204:205], v[66:67] op_sel_hi:[1,0,1] neg_lo:[1,0,0] neg_hi:[1,0,0]
	ds_read_b128 v[172:175], v152 offset:19200
	v_pk_fma_f32 v[96:97], v[20:21], v[180:181], v[96:97] op_sel:[0,1,0]
	v_pk_fma_f32 v[150:151], v[20:21], v[212:213], v[150:151] op_sel:[0,1,0]
	v_pk_fma_f32 v[144:145], v[20:21], v[204:205], v[20:21] op_sel:[0,1,0] neg_lo:[1,0,0] neg_hi:[1,0,0]
	ds_read_b128 v[164:167], v152 offset:18688
	v_pk_fma_f32 v[96:97], v[68:69], v[182:183], v[96:97] op_sel_hi:[1,0,1]
	v_pk_fma_f32 v[150:151], v[68:69], v[214:215], v[150:151] op_sel_hi:[1,0,1]
	v_pk_fma_f32 v[146:147], v[68:69], v[206:207], v[68:69] op_sel_hi:[1,0,1] neg_lo:[1,0,0] neg_hi:[1,0,0]
	ds_read2st64_b64 v[240:243], v153 offset0:38 offset1:41
	v_pk_fma_f32 v[96:97], v[70:71], v[182:183], v[96:97] op_sel:[0,1,0]
	v_pk_fma_f32 v[150:151], v[70:71], v[214:215], v[150:151] op_sel:[0,1,0]
	v_pk_fma_f32 v[148:149], v[70:71], v[206:207], v[70:71] op_sel:[0,1,0] neg_lo:[1,0,0] neg_hi:[1,0,0]
	ds_read_b128 v[168:171], v152 offset:18944
	v_pk_fma_f32 v[142:143], v[248:249], v[208:209], v[142:143] op_sel_hi:[1,0,1]
	v_pk_fma_f32 v[144:145], v[248:249], v[208:209], v[144:145] op_sel:[0,1,0]
	v_add_f32_dpp v150, v150, v150 quad_perm:[1,0,3,2] row_mask:0xf bank_mask:0xf bound_ctrl:1
	v_add_f32_dpp v151, v151, v151 quad_perm:[1,0,3,2] row_mask:0xf bank_mask:0xf bound_ctrl:1
	v_pk_fma_f32 v[146:147], v[248:249], v[210:211], v[146:147] op_sel_hi:[1,0,1]
	v_add_f32_dpp v150, v150, v150 quad_perm:[2,3,0,1] row_mask:0xf bank_mask:0xf bound_ctrl:1
	v_add_f32_dpp v151, v151, v151 quad_perm:[2,3,0,1] row_mask:0xf bank_mask:0xf bound_ctrl:1
	v_pk_fma_f32 v[148:149], v[248:249], v[210:211], v[148:149] op_sel:[0,1,0]
	v_add_f32_dpp v150, v150, v150 row_half_mirror row_mask:0xf bank_mask:0xf bound_ctrl:1
	v_add_f32_dpp v151, v151, v151 row_half_mirror row_mask:0xf bank_mask:0xf bound_ctrl:1
	ds_read_b128 v[192:195], v152 offset:20736
	v_add_f32_dpp v150, v150, v150 row_mirror row_mask:0xf bank_mask:0xf bound_ctrl:1
	v_add_f32_dpp v151, v151, v151 row_mirror row_mask:0xf bank_mask:0xf bound_ctrl:1
	ds_read_b128 v[184:187], v152 offset:20224
	ds_read_b128 v[176:179], v152 offset:19456
	ds_read_b128 v[188:191], v152 offset:20480
	ds_read_b128 v[196:199], v152 offset:20992
	ds_read_b128 v[160:163], v152 offset:18432
	ds_read_b128 v[180:183], v152 offset:19968
	v_pk_fma_f32 v[66:67], v[150:151], v[216:217], v[142:143] op_sel_hi:[1,0,1]
	v_pk_fma_f32 v[20:21], v[150:151], v[216:217], v[144:145] op_sel:[0,1,0]
	v_pk_fma_f32 v[68:69], v[150:151], v[218:219], v[146:147] op_sel_hi:[1,0,1]
	v_pk_fma_f32 v[70:71], v[150:151], v[218:219], v[148:149] op_sel:[0,1,0]
	v_pk_mul_f32 v[98:99], v[66:67], v[200:201] op_sel_hi:[1,0]
	v_pk_mul_f32 v[150:151], v[66:67], v[232:233] op_sel_hi:[1,0]
	v_pk_fma_f32 v[142:143], v[66:67], v[224:225], v[66:67] op_sel_hi:[1,0,1] neg_lo:[1,0,0] neg_hi:[1,0,0]
	v_pk_fma_f32 v[98:99], v[20:21], v[200:201], v[98:99] op_sel:[0,1,0]
	v_pk_fma_f32 v[150:151], v[20:21], v[232:233], v[150:151] op_sel:[0,1,0]
	v_pk_fma_f32 v[144:145], v[20:21], v[224:225], v[20:21] op_sel:[0,1,0] neg_lo:[1,0,0] neg_hi:[1,0,0]
	v_pk_fma_f32 v[98:99], v[68:69], v[202:203], v[98:99] op_sel_hi:[1,0,1]
	v_pk_fma_f32 v[150:151], v[68:69], v[234:235], v[150:151] op_sel_hi:[1,0,1]
	v_pk_fma_f32 v[146:147], v[68:69], v[226:227], v[68:69] op_sel_hi:[1,0,1] neg_lo:[1,0,0] neg_hi:[1,0,0]
	v_pk_fma_f32 v[98:99], v[70:71], v[202:203], v[98:99] op_sel:[0,1,0]
	v_pk_fma_f32 v[150:151], v[70:71], v[234:235], v[150:151] op_sel:[0,1,0]
	v_pk_fma_f32 v[148:149], v[70:71], v[226:227], v[70:71] op_sel:[0,1,0] neg_lo:[1,0,0] neg_hi:[1,0,0]
	v_pk_fma_f32 v[142:143], v[250:251], v[228:229], v[142:143] op_sel_hi:[1,0,1]
	v_pk_fma_f32 v[144:145], v[250:251], v[228:229], v[144:145] op_sel:[0,1,0]
	v_add_f32_dpp v150, v150, v150 quad_perm:[1,0,3,2] row_mask:0xf bank_mask:0xf bound_ctrl:1
	v_add_f32_dpp v151, v151, v151 quad_perm:[1,0,3,2] row_mask:0xf bank_mask:0xf bound_ctrl:1
	v_pk_fma_f32 v[146:147], v[250:251], v[230:231], v[146:147] op_sel_hi:[1,0,1]
	v_add_f32_dpp v150, v150, v150 quad_perm:[2,3,0,1] row_mask:0xf bank_mask:0xf bound_ctrl:1
	v_add_f32_dpp v151, v151, v151 quad_perm:[2,3,0,1] row_mask:0xf bank_mask:0xf bound_ctrl:1
	v_pk_fma_f32 v[148:149], v[250:251], v[230:231], v[148:149] op_sel:[0,1,0]
	v_add_f32_dpp v150, v150, v150 row_half_mirror row_mask:0xf bank_mask:0xf bound_ctrl:1
	v_add_f32_dpp v151, v151, v151 row_half_mirror row_mask:0xf bank_mask:0xf bound_ctrl:1
	s_nop 0
	v_add_f32_dpp v150, v150, v150 row_mirror row_mask:0xf bank_mask:0xf bound_ctrl:1
	v_add_f32_dpp v151, v151, v151 row_mirror row_mask:0xf bank_mask:0xf bound_ctrl:1
	s_waitcnt lgkmcnt(0)
; #define LAS __attribute__((address_space(3)))
; #define ROW16_SUM4(x, y, z, w) do { DPP4(x, y, z, w, "quad_perm:[1,0,3,2]", "s_nop 1"); DPP4(x, y, z, w, "quad_perm:[2,3,0,1]", ""); DPP4(x, y, z, w, "row_half_mirror", ""); DPP4(x, y, z, w, "row_mirror", ""); } while (0)
; template <bool SAMPLE>
; __device__ __forceinline__ void rwkv_unit(PR P, LAS float* lds, const int b, const int h, const int half, const int wv) {
;     ...
;                 for (int tt = 0; tt < GS; ++tt) {
;                     const LAS float* qn = q0 + (tt + 1 < GS ? tt + 1 : tt) * 384;
;                     const f32x4 nr4 = *(const LAS f32x4*)(qn + j0), no4 = *(const LAS f32x4*)(qn + 64 + j0), nk4 = *(const LAS f32x4*)(qn + 128 + j0), na4 = *(const LAS f32x4*)(qn + 192 + j0), nb4 = *(const LAS f32x4*)(qn + 256 + j0);
;                     const f32x2 nv2 = *(const LAS f32x2*)(qn + 320 + row0);
;                     f32x2 sa = (S[0] * a4[0] + S[1] * a4[1]) + (S[2] * a4[2] + S[3] * a4[3]);
;                     float sx = sa.x, sy = sa.y; ROW16_SUM4(sx, sy, py0, py1); sa = (f32x2){sx, sy};
;                     if (tt > 0) { yk0 = cgl == tt - 1 ? py0 : yk0; yk1 = cgl == tt - 1 ? py1 : yk1; }
; #pragma unroll
;                     for (int c = 0; c < 4; ++c) { f32x2 t = S[c] - S[c] * o4[c]; t = t + sa * b4[c]; S[c] = t + v2 * k4[c]; }
;                     const f32x2 y = (S[0] * r4[0] + S[1] * r4[1]) + (S[2] * r4[2] + S[3] * r4[3]);
;                     py0 = y.x; py1 = y.y;
;                     r4 = nr4; o4 = no4; k4 = nk4; a4 = na4; b4 = nb4; v2 = nv2;
	v_pk_fma_f32 v[66:67], v[150:151], v[236:237], v[142:143] op_sel_hi:[1,0,1]
	v_pk_fma_f32 v[20:21], v[150:151], v[236:237], v[144:145] op_sel:[0,1,0]
	v_pk_fma_f32 v[68:69], v[150:151], v[238:239], v[146:147] op_sel_hi:[1,0,1]
	v_pk_fma_f32 v[70:71], v[150:151], v[238:239], v[148:149] op_sel:[0,1,0]
	v_pk_mul_f32 v[100:101], v[66:67], v[220:221] op_sel_hi:[1,0]
	v_pk_mul_f32 v[150:151], v[66:67], v[172:173] op_sel_hi:[1,0]
	v_pk_fma_f32 v[142:143], v[66:67], v[164:165], v[66:67] op_sel_hi:[1,0,1] neg_lo:[1,0,0] neg_hi:[1,0,0]
	ds_read_b128 v[212:215], v152 offset:22272
	v_pk_fma_f32 v[100:101], v[20:21], v[220:221], v[100:101] op_sel:[0,1,0]
	v_pk_fma_f32 v[150:151], v[20:21], v[172:173], v[150:151] op_sel:[0,1,0]
	v_pk_fma_f32 v[144:145], v[20:21], v[164:165], v[20:21] op_sel:[0,1,0] neg_lo:[1,0,0] neg_hi:[1,0,0]
	ds_read_b128 v[204:207], v152 offset:21760
	v_pk_fma_f32 v[100:101], v[68:69], v[222:223], v[100:101] op_sel_hi:[1,0,1]
	v_pk_fma_f32 v[150:151], v[68:69], v[174:175], v[150:151] op_sel_hi:[1,0,1]
	v_pk_fma_f32 v[146:147], v[68:69], v[166:167], v[68:69] op_sel_hi:[1,0,1] neg_lo:[1,0,0] neg_hi:[1,0,0]
	ds_read2st64_b64 v[244:247], v153 offset0:44 offset1:47
	v_pk_fma_f32 v[100:101], v[70:71], v[222:223], v[100:101] op_sel:[0,1,0]
	v_pk_fma_f32 v[150:151], v[70:71], v[174:175], v[150:151] op_sel:[0,1,0]
	v_pk_fma_f32 v[148:149], v[70:71], v[166:167], v[70:71] op_sel:[0,1,0] neg_lo:[1,0,0] neg_hi:[1,0,0]
	ds_read_b128 v[208:211], v152 offset:22016
	v_pk_fma_f32 v[142:143], v[240:241], v[168:169], v[142:143] op_sel_hi:[1,0,1]
	v_pk_fma_f32 v[144:145], v[240:241], v[168:169], v[144:145] op_sel:[0,1,0]
	v_add_f32_dpp v150, v150, v150 quad_perm:[1,0,3,2] row_mask:0xf bank_mask:0xf bound_ctrl:1
	v_add_f32_dpp v151, v151, v151 quad_perm:[1,0,3,2] row_mask:0xf bank_mask:0xf bound_ctrl:1
	v_pk_fma_f32 v[146:147], v[240:241], v[170:171], v[146:147] op_sel_hi:[1,0,1]
	v_add_f32_dpp v150, v150, v150 quad_perm:[2,3,0,1] row_mask:0xf bank_mask:0xf bound_ctrl:1
	v_add_f32_dpp v151, v151, v151 quad_perm:[2,3,0,1] row_mask:0xf bank_mask:0xf bound_ctrl:1
	v_pk_fma_f32 v[148:149], v[240:241], v[170:171], v[148:149] op_sel:[0,1,0]
	v_add_f32_dpp v150, v150, v150 row_half_mirror row_mask:0xf bank_mask:0xf bound_ctrl:1
	v_add_f32_dpp v151, v151, v151 row_half_mirror row_mask:0xf bank_mask:0xf bound_ctrl:1
	ds_read_b128 v[232:235], v152 offset:23808
	v_add_f32_dpp v150, v150, v150 row_mirror row_mask:0xf bank_mask:0xf bound_ctrl:1
	v_add_f32_dpp v151, v151, v151 row_mirror row_mask:0xf bank_mask:0xf bound_ctrl:1
	ds_read_b128 v[224:227], v152 offset:23296
	ds_read_b128 v[216:219], v152 offset:22528
	ds_read_b128 v[228:231], v152 offset:23552
	ds_read_b128 v[236:239], v152 offset:24064
	ds_read_b128 v[200:203], v152 offset:21504
	ds_read_b128 v[220:223], v152 offset:23040
	v_pk_fma_f32 v[66:67], v[150:151], v[176:177], v[142:143] op_sel_hi:[1,0,1]
	v_pk_fma_f32 v[20:21], v[150:151], v[176:177], v[144:145] op_sel:[0,1,0]
	v_pk_fma_f32 v[68:69], v[150:151], v[178:179], v[146:147] op_sel_hi:[1,0,1]
	v_pk_fma_f32 v[70:71], v[150:151], v[178:179], v[148:149] op_sel:[0,1,0]
	v_pk_mul_f32 v[102:103], v[66:67], v[160:161] op_sel_hi:[1,0]
	v_pk_mul_f32 v[150:151], v[66:67], v[192:193] op_sel_hi:[1,0]
	v_pk_fma_f32 v[142:143], v[66:67], v[184:185], v[66:67] op_sel_hi:[1,0,1] neg_lo:[1,0,0] neg_hi:[1,0,0]
	v_pk_fma_f32 v[102:103], v[20:21], v[160:161], v[102:103] op_sel:[0,1,0]
	v_pk_fma_f32 v[150:151], v[20:21], v[192:193], v[150:151] op_sel:[0,1,0]
	v_pk_fma_f32 v[144:145], v[20:21], v[184:185], v[20:21] op_sel:[0,1,0] neg_lo:[1,0,0] neg_hi:[1,0,0]
	v_pk_fma_f32 v[102:103], v[68:69], v[162:163], v[102:103] op_sel_hi:[1,0,1]
	v_pk_fma_f32 v[150:151], v[68:69], v[194:195], v[150:151] op_sel_hi:[1,0,1]
	v_pk_fma_f32 v[146:147], v[68:69], v[186:187], v[68:69] op_sel_hi:[1,0,1] neg_lo:[1,0,0] neg_hi:[1,0,0]
	v_pk_fma_f32 v[102:103], v[70:71], v[162:163], v[102:103] op_sel:[0,1,0]
	v_pk_fma_f32 v[150:151], v[70:71], v[194:195], v[150:151] op_sel:[0,1,0]
	v_pk_fma_f32 v[148:149], v[70:71], v[186:187], v[70:71] op_sel:[0,1,0] neg_lo:[1,0,0] neg_hi:[1,0,0]
	v_pk_fma_f32 v[142:143], v[242:243], v[188:189], v[142:143] op_sel_hi:[1,0,1]
	v_pk_fma_f32 v[144:145], v[242:243], v[188:189], v[144:145] op_sel:[0,1,0]
	v_add_f32_dpp v150, v150, v150 quad_perm:[1,0,3,2] row_mask:0xf bank_mask:0xf bound_ctrl:1
	v_add_f32_dpp v151, v151, v151 quad_perm:[1,0,3,2] row_mask:0xf bank_mask:0xf bound_ctrl:1
	v_pk_fma_f32 v[146:147], v[242:243], v[190:191], v[146:147] op_sel_hi:[1,0,1]
	v_add_f32_dpp v150, v150, v150 quad_perm:[2,3,0,1] row_mask:0xf bank_mask:0xf bound_ctrl:1
	v_add_f32_dpp v151, v151, v151 quad_perm:[2,3,0,1] row_mask:0xf bank_mask:0xf bound_ctrl:1
	v_pk_fma_f32 v[148:149], v[242:243], v[190:191], v[148:149] op_sel:[0,1,0]
	v_add_f32_dpp v150, v150, v150 row_half_mirror row_mask:0xf bank_mask:0xf bound_ctrl:1
	v_add_f32_dpp v151, v151, v151 row_half_mirror row_mask:0xf bank_mask:0xf bound_ctrl:1
	s_nop 0
	v_add_f32_dpp v150, v150, v150 row_mirror row_mask:0xf bank_mask:0xf bound_ctrl:1
	v_add_f32_dpp v151, v151, v151 row_mirror row_mask:0xf bank_mask:0xf bound_ctrl:1
	s_waitcnt lgkmcnt(0)
; #define LAS __attribute__((address_space(3)))
; #define ROW16_SUM4(x, y, z, w) do { DPP4(x, y, z, w, "quad_perm:[1,0,3,2]", "s_nop 1"); DPP4(x, y, z, w, "quad_perm:[2,3,0,1]", ""); DPP4(x, y, z, w, "row_half_mirror", ""); DPP4(x, y, z, w, "row_mirror", ""); } while (0)
; template <bool SAMPLE>
; __device__ __forceinline__ void rwkv_unit(PR P, LAS float* lds, const int b, const int h, const int half, const int wv) {
;     ...
;                 for (int tt = 0; tt < GS; ++tt) {
;                     const LAS float* qn = q0 + (tt + 1 < GS ? tt + 1 : tt) * 384;
;                     const f32x4 nr4 = *(const LAS f32x4*)(qn + j0), no4 = *(const LAS f32x4*)(qn + 64 + j0), nk4 = *(const LAS f32x4*)(qn + 128 + j0), na4 = *(const LAS f32x4*)(qn + 192 + j0), nb4 = *(const LAS f32x4*)(qn + 256 + j0);
;                     const f32x2 nv2 = *(const LAS f32x2*)(qn + 320 + row0);
;                     f32x2 sa = (S[0] * a4[0] + S[1] * a4[1]) + (S[2] * a4[2] + S[3] * a4[3]);
;                     float sx = sa.x, sy = sa.y; ROW16_SUM4(sx, sy, py0, py1); sa = (f32x2){sx, sy};
;                     if (tt > 0) { yk0 = cgl == tt - 1 ? py0 : yk0; yk1 = cgl == tt - 1 ? py1 : yk1; }
; #pragma unroll
;                     for (int c = 0; c < 4; ++c) { f32x2 t = S[c] - S[c] * o4[c]; t = t + sa * b4[c]; S[c] = t + v2 * k4[c]; }
;                     const f32x2 y = (S[0] * r4[0] + S[1] * r4[1]) + (S[2] * r4[2] + S[3] * r4[3]);
;                     py0 = y.x; py1 = y.y;
;                     r4 = nr4; o4 = no4; k4 = nk4; a4 = na4; b4 = nb4; v2 = nv2;
	v_pk_fma_f32 v[66:67], v[150:151], v[196:197], v[142:143] op_sel_hi:[1,0,1]
	v_pk_fma_f32 v[20:21], v[150:151], v[196:197], v[144:145] op_sel:[0,1,0]
	v_pk_fma_f32 v[68:69], v[150:151], v[198:199], v[146:147] op_sel_hi:[1,0,1]
	v_pk_fma_f32 v[70:71], v[150:151], v[198:199], v[148:149] op_sel:[0,1,0]
	v_pk_mul_f32 v[104:105], v[66:67], v[180:181] op_sel_hi:[1,0]
	v_pk_mul_f32 v[150:151], v[66:67], v[212:213] op_sel_hi:[1,0]
	v_pk_fma_f32 v[142:143], v[66:67], v[204:205], v[66:67] op_sel_hi:[1,0,1] neg_lo:[1,0,0] neg_hi:[1,0,0]
	ds_read_b128 v[172:175], v152 offset:25344
	v_pk_fma_f32 v[104:105], v[20:21], v[180:181], v[104:105] op_sel:[0,1,0]
	v_pk_fma_f32 v[150:151], v[20:21], v[212:213], v[150:151] op_sel:[0,1,0]
	v_pk_fma_f32 v[144:145], v[20:21], v[204:205], v[20:21] op_sel:[0,1,0] neg_lo:[1,0,0] neg_hi:[1,0,0]
	ds_read_b128 v[164:167], v152 offset:24832
	v_pk_fma_f32 v[104:105], v[68:69], v[182:183], v[104:105] op_sel_hi:[1,0,1]
	v_pk_fma_f32 v[150:151], v[68:69], v[214:215], v[150:151] op_sel_hi:[1,0,1]
	v_pk_fma_f32 v[146:147], v[68:69], v[206:207], v[68:69] op_sel_hi:[1,0,1] neg_lo:[1,0,0] neg_hi:[1,0,0]
	ds_read2st64_b64 v[248:251], v153 offset0:50 offset1:53
	v_pk_fma_f32 v[104:105], v[70:71], v[182:183], v[104:105] op_sel:[0,1,0]
	v_pk_fma_f32 v[150:151], v[70:71], v[214:215], v[150:151] op_sel:[0,1,0]
	v_pk_fma_f32 v[148:149], v[70:71], v[206:207], v[70:71] op_sel:[0,1,0] neg_lo:[1,0,0] neg_hi:[1,0,0]
	ds_read_b128 v[168:171], v152 offset:25088
	v_pk_fma_f32 v[142:143], v[244:245], v[208:209], v[142:143] op_sel_hi:[1,0,1]
	v_pk_fma_f32 v[144:145], v[244:245], v[208:209], v[144:145] op_sel:[0,1,0]
	v_add_f32_dpp v150, v150, v150 quad_perm:[1,0,3,2] row_mask:0xf bank_mask:0xf bound_ctrl:1
	v_add_f32_dpp v151, v151, v151 quad_perm:[1,0,3,2] row_mask:0xf bank_mask:0xf bound_ctrl:1
	v_pk_fma_f32 v[146:147], v[244:245], v[210:211], v[146:147] op_sel_hi:[1,0,1]
	v_add_f32_dpp v150, v150, v150 quad_perm:[2,3,0,1] row_mask:0xf bank_mask:0xf bound_ctrl:1
	v_add_f32_dpp v151, v151, v151 quad_perm:[2,3,0,1] row_mask:0xf bank_mask:0xf bound_ctrl:1
	v_pk_fma_f32 v[148:149], v[244:245], v[210:211], v[148:149] op_sel:[0,1,0]
	v_add_f32_dpp v150, v150, v150 row_half_mirror row_mask:0xf bank_mask:0xf bound_ctrl:1
	v_add_f32_dpp v151, v151, v151 row_half_mirror row_mask:0xf bank_mask:0xf bound_ctrl:1
	ds_read_b128 v[192:195], v152 offset:26880
	v_add_f32_dpp v150, v150, v150 row_mirror row_mask:0xf bank_mask:0xf bound_ctrl:1
	v_add_f32_dpp v151, v151, v151 row_mirror row_mask:0xf bank_mask:0xf bound_ctrl:1
	ds_read_b128 v[184:187], v152 offset:26368
	ds_read_b128 v[176:179], v152 offset:25600
	ds_read_b128 v[188:191], v152 offset:26624
	ds_read_b128 v[196:199], v152 offset:27136
	ds_read_b128 v[160:163], v152 offset:24576
	ds_read_b128 v[180:183], v152 offset:26112
	v_pk_fma_f32 v[66:67], v[150:151], v[216:217], v[142:143] op_sel_hi:[1,0,1]
	v_pk_fma_f32 v[20:21], v[150:151], v[216:217], v[144:145] op_sel:[0,1,0]
	v_pk_fma_f32 v[68:69], v[150:151], v[218:219], v[146:147] op_sel_hi:[1,0,1]
	v_pk_fma_f32 v[70:71], v[150:151], v[218:219], v[148:149] op_sel:[0,1,0]
	v_pk_mul_f32 v[106:107], v[66:67], v[200:201] op_sel_hi:[1,0]
	v_pk_mul_f32 v[150:151], v[66:67], v[232:233] op_sel_hi:[1,0]
	v_pk_fma_f32 v[142:143], v[66:67], v[224:225], v[66:67] op_sel_hi:[1,0,1] neg_lo:[1,0,0] neg_hi:[1,0,0]
	v_pk_fma_f32 v[106:107], v[20:21], v[200:201], v[106:107] op_sel:[0,1,0]
	v_pk_fma_f32 v[150:151], v[20:21], v[232:233], v[150:151] op_sel:[0,1,0]
	v_pk_fma_f32 v[144:145], v[20:21], v[224:225], v[20:21] op_sel:[0,1,0] neg_lo:[1,0,0] neg_hi:[1,0,0]
	v_pk_fma_f32 v[106:107], v[68:69], v[202:203], v[106:107] op_sel_hi:[1,0,1]
	v_pk_fma_f32 v[150:151], v[68:69], v[234:235], v[150:151] op_sel_hi:[1,0,1]
	v_pk_fma_f32 v[146:147], v[68:69], v[226:227], v[68:69] op_sel_hi:[1,0,1] neg_lo:[1,0,0] neg_hi:[1,0,0]
	v_pk_fma_f32 v[106:107], v[70:71], v[202:203], v[106:107] op_sel:[0,1,0]
	v_pk_fma_f32 v[150:151], v[70:71], v[234:235], v[150:151] op_sel:[0,1,0]
	v_pk_fma_f32 v[148:149], v[70:71], v[226:227], v[70:71] op_sel:[0,1,0] neg_lo:[1,0,0] neg_hi:[1,0,0]
	v_pk_fma_f32 v[142:143], v[246:247], v[228:229], v[142:143] op_sel_hi:[1,0,1]
	v_pk_fma_f32 v[144:145], v[246:247], v[228:229], v[144:145] op_sel:[0,1,0]
	v_add_f32_dpp v150, v150, v150 quad_perm:[1,0,3,2] row_mask:0xf bank_mask:0xf bound_ctrl:1
	v_add_f32_dpp v151, v151, v151 quad_perm:[1,0,3,2] row_mask:0xf bank_mask:0xf bound_ctrl:1
	v_pk_fma_f32 v[146:147], v[246:247], v[230:231], v[146:147] op_sel_hi:[1,0,1]
	v_add_f32_dpp v150, v150, v150 quad_perm:[2,3,0,1] row_mask:0xf bank_mask:0xf bound_ctrl:1
	v_add_f32_dpp v151, v151, v151 quad_perm:[2,3,0,1] row_mask:0xf bank_mask:0xf bound_ctrl:1
	v_pk_fma_f32 v[148:149], v[246:247], v[230:231], v[148:149] op_sel:[0,1,0]
	v_add_f32_dpp v150, v150, v150 row_half_mirror row_mask:0xf bank_mask:0xf bound_ctrl:1
	v_add_f32_dpp v151, v151, v151 row_half_mirror row_mask:0xf bank_mask:0xf bound_ctrl:1
	s_nop 0
	v_add_f32_dpp v150, v150, v150 row_mirror row_mask:0xf bank_mask:0xf bound_ctrl:1
	v_add_f32_dpp v151, v151, v151 row_mirror row_mask:0xf bank_mask:0xf bound_ctrl:1
	s_waitcnt lgkmcnt(0)
; #define LAS __attribute__((address_space(3)))
; #define ROW16_SUM4(x, y, z, w) do { DPP4(x, y, z, w, "quad_perm:[1,0,3,2]", "s_nop 1"); DPP4(x, y, z, w, "quad_perm:[2,3,0,1]", ""); DPP4(x, y, z, w, "row_half_mirror", ""); DPP4(x, y, z, w, "row_mirror", ""); } while (0)
; #define ROW16_SUM2(x, y) do { DPP2(x, y, "quad_perm:[1,0,3,2]", "s_nop 1"); DPP2(x, y, "quad_perm:[2,3,0,1]", "s_nop 0"); DPP2(x, y, "row_half_mirror", "s_nop 0"); DPP2(x, y, "row_mirror", "s_nop 0"); } while (0)
; template <bool SAMPLE>
; __device__ __forceinline__ void rwkv_unit(PR P, LAS float* lds, const int b, const int h, const int half, const int wv) {
;     ...
;                 for (int tt = 0; tt < GS; ++tt) {
;                     const LAS float* qn = q0 + (tt + 1 < GS ? tt + 1 : tt) * 384;
;                     const f32x4 nr4 = *(const LAS f32x4*)(qn + j0), no4 = *(const LAS f32x4*)(qn + 64 + j0), nk4 = *(const LAS f32x4*)(qn + 128 + j0), na4 = *(const LAS f32x4*)(qn + 192 + j0), nb4 = *(const LAS f32x4*)(qn + 256 + j0);
;                     const f32x2 nv2 = *(const LAS f32x2*)(qn + 320 + row0);
;                     f32x2 sa = (S[0] * a4[0] + S[1] * a4[1]) + (S[2] * a4[2] + S[3] * a4[3]);
;                     float sx = sa.x, sy = sa.y; ROW16_SUM4(sx, sy, py0, py1); sa = (f32x2){sx, sy};
;                     if (tt > 0) { yk0 = cgl == tt - 1 ? py0 : yk0; yk1 = cgl == tt - 1 ? py1 : yk1; }
; #pragma unroll
;                     for (int c = 0; c < 4; ++c) { f32x2 t = S[c] - S[c] * o4[c]; t = t + sa * b4[c]; S[c] = t + v2 * k4[c]; }
;                     const f32x2 y = (S[0] * r4[0] + S[1] * r4[1]) + (S[2] * r4[2] + S[3] * r4[3]);
;                     py0 = y.x; py1 = y.y;
;                     r4 = nr4; o4 = no4; k4 = nk4; a4 = na4; b4 = nb4; v2 = nv2;
;                 }
;                 ROW16_SUM2(py0, py1); yk0 = cgl == GS - 1 ? py0 : yk0; yk1 = cgl == GS - 1 ? py1 : yk1;
	v_pk_fma_f32 v[66:67], v[150:151], v[236:237], v[142:143] op_sel_hi:[1,0,1]
	v_pk_fma_f32 v[20:21], v[150:151], v[236:237], v[144:145] op_sel:[0,1,0]
	v_pk_fma_f32 v[68:69], v[150:151], v[238:239], v[146:147] op_sel_hi:[1,0,1]
	v_pk_fma_f32 v[70:71], v[150:151], v[238:239], v[148:149] op_sel:[0,1,0]
	v_pk_mul_f32 v[108:109], v[66:67], v[220:221] op_sel_hi:[1,0]
	v_pk_mul_f32 v[150:151], v[66:67], v[172:173] op_sel_hi:[1,0]
	v_pk_fma_f32 v[142:143], v[66:67], v[164:165], v[66:67] op_sel_hi:[1,0,1] neg_lo:[1,0,0] neg_hi:[1,0,0]
	ds_read_b128 v[212:215], v152 offset:28416
	v_pk_fma_f32 v[108:109], v[20:21], v[220:221], v[108:109] op_sel:[0,1,0]
	v_pk_fma_f32 v[150:151], v[20:21], v[172:173], v[150:151] op_sel:[0,1,0]
	v_pk_fma_f32 v[144:145], v[20:21], v[164:165], v[20:21] op_sel:[0,1,0] neg_lo:[1,0,0] neg_hi:[1,0,0]
	ds_read_b128 v[204:207], v152 offset:27904
	v_pk_fma_f32 v[108:109], v[68:69], v[222:223], v[108:109] op_sel_hi:[1,0,1]
	v_pk_fma_f32 v[150:151], v[68:69], v[174:175], v[150:151] op_sel_hi:[1,0,1]
	v_pk_fma_f32 v[146:147], v[68:69], v[166:167], v[68:69] op_sel_hi:[1,0,1] neg_lo:[1,0,0] neg_hi:[1,0,0]
	ds_read2st64_b64 v[240:243], v153 offset0:56 offset1:59
	v_pk_fma_f32 v[108:109], v[70:71], v[222:223], v[108:109] op_sel:[0,1,0]
	v_pk_fma_f32 v[150:151], v[70:71], v[174:175], v[150:151] op_sel:[0,1,0]
	v_pk_fma_f32 v[148:149], v[70:71], v[166:167], v[70:71] op_sel:[0,1,0] neg_lo:[1,0,0] neg_hi:[1,0,0]
	ds_read_b128 v[208:211], v152 offset:28160
	v_pk_fma_f32 v[142:143], v[248:249], v[168:169], v[142:143] op_sel_hi:[1,0,1]
	v_pk_fma_f32 v[144:145], v[248:249], v[168:169], v[144:145] op_sel:[0,1,0]
	v_add_f32_dpp v150, v150, v150 quad_perm:[1,0,3,2] row_mask:0xf bank_mask:0xf bound_ctrl:1
	v_add_f32_dpp v151, v151, v151 quad_perm:[1,0,3,2] row_mask:0xf bank_mask:0xf bound_ctrl:1
	v_pk_fma_f32 v[146:147], v[248:249], v[170:171], v[146:147] op_sel_hi:[1,0,1]
	v_add_f32_dpp v150, v150, v150 quad_perm:[2,3,0,1] row_mask:0xf bank_mask:0xf bound_ctrl:1
	v_add_f32_dpp v151, v151, v151 quad_perm:[2,3,0,1] row_mask:0xf bank_mask:0xf bound_ctrl:1
	v_pk_fma_f32 v[148:149], v[248:249], v[170:171], v[148:149] op_sel:[0,1,0]
	v_add_f32_dpp v150, v150, v150 row_half_mirror row_mask:0xf bank_mask:0xf bound_ctrl:1
	v_add_f32_dpp v151, v151, v151 row_half_mirror row_mask:0xf bank_mask:0xf bound_ctrl:1
	ds_read_b128 v[232:235], v152 offset:29952
	v_add_f32_dpp v150, v150, v150 row_mirror row_mask:0xf bank_mask:0xf bound_ctrl:1
	v_add_f32_dpp v151, v151, v151 row_mirror row_mask:0xf bank_mask:0xf bound_ctrl:1
	ds_read_b128 v[224:227], v152 offset:29440
	ds_read_b128 v[216:219], v152 offset:28672
	ds_read_b128 v[228:231], v152 offset:29696
	ds_read_b128 v[236:239], v152 offset:30208
	ds_read_b128 v[200:203], v152 offset:27648
	ds_read_b128 v[220:223], v152 offset:29184
	v_pk_fma_f32 v[66:67], v[150:151], v[176:177], v[142:143] op_sel_hi:[1,0,1]
	v_pk_fma_f32 v[20:21], v[150:151], v[176:177], v[144:145] op_sel:[0,1,0]
	v_pk_fma_f32 v[68:69], v[150:151], v[178:179], v[146:147] op_sel_hi:[1,0,1]
	v_pk_fma_f32 v[70:71], v[150:151], v[178:179], v[148:149] op_sel:[0,1,0]
	v_add_f32_dpp v78, v78, v78 row_ror:8 row_mask:0xf bank_mask:0x3 bound_ctrl:1
	v_add_f32_dpp v78, v94, v94 row_ror:8 row_mask:0xf bank_mask:0xc bound_ctrl:1
	v_add_f32_dpp v80, v80, v80 row_ror:8 row_mask:0xf bank_mask:0x3 bound_ctrl:1
	v_add_f32_dpp v80, v96, v96 row_ror:8 row_mask:0xf bank_mask:0xc bound_ctrl:1
	v_add_f32_dpp v82, v82, v82 row_ror:8 row_mask:0xf bank_mask:0x3 bound_ctrl:1
	v_add_f32_dpp v82, v98, v98 row_ror:8 row_mask:0xf bank_mask:0xc bound_ctrl:1
	v_add_f32_dpp v84, v84, v84 row_ror:8 row_mask:0xf bank_mask:0x3 bound_ctrl:1
	v_add_f32_dpp v84, v100, v100 row_ror:8 row_mask:0xf bank_mask:0xc bound_ctrl:1
	v_add_f32_dpp v86, v86, v86 row_ror:8 row_mask:0xf bank_mask:0x3 bound_ctrl:1
	v_add_f32_dpp v86, v102, v102 row_ror:8 row_mask:0xf bank_mask:0xc bound_ctrl:1
	v_add_f32_dpp v88, v88, v88 row_ror:8 row_mask:0xf bank_mask:0x3 bound_ctrl:1
	v_add_f32_dpp v88, v104, v104 row_ror:8 row_mask:0xf bank_mask:0xc bound_ctrl:1
	v_add_f32_dpp v90, v90, v90 row_ror:8 row_mask:0xf bank_mask:0x3 bound_ctrl:1
	v_add_f32_dpp v90, v106, v106 row_ror:8 row_mask:0xf bank_mask:0xc bound_ctrl:1
	v_add_f32_dpp v92, v92, v92 row_ror:8 row_mask:0xf bank_mask:0x3 bound_ctrl:1
	v_add_f32_dpp v92, v108, v108 row_ror:8 row_mask:0xf bank_mask:0xc bound_ctrl:1
	v_add_f32_dpp v79, v79, v79 row_ror:8 row_mask:0xf bank_mask:0x3 bound_ctrl:1
	v_add_f32_dpp v79, v95, v95 row_ror:8 row_mask:0xf bank_mask:0xc bound_ctrl:1
	v_add_f32_dpp v81, v81, v81 row_ror:8 row_mask:0xf bank_mask:0x3 bound_ctrl:1
	v_add_f32_dpp v81, v97, v97 row_ror:8 row_mask:0xf bank_mask:0xc bound_ctrl:1
	v_add_f32_dpp v83, v83, v83 row_ror:8 row_mask:0xf bank_mask:0x3 bound_ctrl:1
	v_add_f32_dpp v83, v99, v99 row_ror:8 row_mask:0xf bank_mask:0xc bound_ctrl:1
	v_add_f32_dpp v85, v85, v85 row_ror:8 row_mask:0xf bank_mask:0x3 bound_ctrl:1
	v_add_f32_dpp v85, v101, v101 row_ror:8 row_mask:0xf bank_mask:0xc bound_ctrl:1
	v_add_f32_dpp v87, v87, v87 row_ror:8 row_mask:0xf bank_mask:0x3 bound_ctrl:1
	v_add_f32_dpp v87, v103, v103 row_ror:8 row_mask:0xf bank_mask:0xc bound_ctrl:1
	v_add_f32_dpp v89, v89, v89 row_ror:8 row_mask:0xf bank_mask:0x3 bound_ctrl:1
	v_add_f32_dpp v89, v105, v105 row_ror:8 row_mask:0xf bank_mask:0xc bound_ctrl:1
	v_add_f32_dpp v91, v91, v91 row_ror:8 row_mask:0xf bank_mask:0x3 bound_ctrl:1
	v_add_f32_dpp v91, v107, v107 row_ror:8 row_mask:0xf bank_mask:0xc bound_ctrl:1
	v_add_f32_dpp v93, v93, v93 row_ror:8 row_mask:0xf bank_mask:0x3 bound_ctrl:1
	v_add_f32_dpp v93, v109, v109 row_ror:8 row_mask:0xf bank_mask:0xc bound_ctrl:1
; __device__ __forceinline__ unsigned cvt_pk_bf16(float lo, float hi) { const f32x2_t v = {lo, hi}; const bf16x2_t b = __builtin_convertvector(v, bf16x2_t); return __builtin_bit_cast(unsigned, b); }
; #define LAS __attribute__((address_space(3)))
; #define ROW16_SUM4(x, y, z, w) do { DPP4(x, y, z, w, "quad_perm:[1,0,3,2]", "s_nop 1"); DPP4(x, y, z, w, "quad_perm:[2,3,0,1]", ""); DPP4(x, y, z, w, "row_half_mirror", ""); DPP4(x, y, z, w, "row_mirror", ""); } while (0)
; #define ROW16_SUM2(x, y) do { DPP2(x, y, "quad_perm:[1,0,3,2]", "s_nop 1"); DPP2(x, y, "quad_perm:[2,3,0,1]", "s_nop 0"); DPP2(x, y, "row_half_mirror", "s_nop 0"); DPP2(x, y, "row_mirror", "s_nop 0"); } while (0)
; template <bool SAMPLE>
; __device__ __forceinline__ void rwkv_unit(PR P, LAS float* lds, const int b, const int h, const int half, const int wv) {
;     ...
;                 for (int tt = 0; tt < GS; ++tt) {
;                     const LAS float* qn = q0 + (tt + 1 < GS ? tt + 1 : tt) * 384;
;                     const f32x4 nr4 = *(const LAS f32x4*)(qn + j0), no4 = *(const LAS f32x4*)(qn + 64 + j0), nk4 = *(const LAS f32x4*)(qn + 128 + j0), na4 = *(const LAS f32x4*)(qn + 192 + j0), nb4 = *(const LAS f32x4*)(qn + 256 + j0);
;                     const f32x2 nv2 = *(const LAS f32x2*)(qn + 320 + row0);
;                     f32x2 sa = (S[0] * a4[0] + S[1] * a4[1]) + (S[2] * a4[2] + S[3] * a4[3]);
;                     float sx = sa.x, sy = sa.y; ROW16_SUM4(sx, sy, py0, py1); sa = (f32x2){sx, sy};
;                     if (tt > 0) { yk0 = cgl == tt - 1 ? py0 : yk0; yk1 = cgl == tt - 1 ? py1 : yk1; }
; #pragma unroll
;                     for (int c = 0; c < 4; ++c) { f32x2 t = S[c] - S[c] * o4[c]; t = t + sa * b4[c]; S[c] = t + v2 * k4[c]; }
;                     const f32x2 y = (S[0] * r4[0] + S[1] * r4[1]) + (S[2] * r4[2] + S[3] * r4[3]);
;                     py0 = y.x; py1 = y.y;
;                     r4 = nr4; o4 = no4; k4 = nk4; a4 = na4; b4 = nb4; v2 = nv2;
;     ...
;                 ROW16_SUM2(py0, py1); yk0 = cgl == GS - 1 ? py0 : yk0; yk1 = cgl == GS - 1 ? py1 : yk1;
;                 if (cgl < GS) *(unsigned*)(YS + (size_t)(row_base + c * TC + g * GS + cgl) * 512 + h * 64 + row0) = pg8::cvt_pk_bf16(yk0, yk1);
	v_add_f32_dpp v78, v78, v78 row_shl:4 row_mask:0xf bank_mask:0x5 bound_ctrl:1
	v_add_f32_dpp v78, v86, v86 row_shr:4 row_mask:0xf bank_mask:0xa bound_ctrl:1
	v_add_f32_dpp v80, v80, v80 row_shl:4 row_mask:0xf bank_mask:0x5 bound_ctrl:1
	v_add_f32_dpp v80, v88, v88 row_shr:4 row_mask:0xf bank_mask:0xa bound_ctrl:1
	v_add_f32_dpp v82, v82, v82 row_shl:4 row_mask:0xf bank_mask:0x5 bound_ctrl:1
	v_add_f32_dpp v82, v90, v90 row_shr:4 row_mask:0xf bank_mask:0xa bound_ctrl:1
	v_add_f32_dpp v84, v84, v84 row_shl:4 row_mask:0xf bank_mask:0x5 bound_ctrl:1
	v_add_f32_dpp v84, v92, v92 row_shr:4 row_mask:0xf bank_mask:0xa bound_ctrl:1
	v_add_f32_dpp v79, v79, v79 row_shl:4 row_mask:0xf bank_mask:0x5 bound_ctrl:1
	v_add_f32_dpp v79, v87, v87 row_shr:4 row_mask:0xf bank_mask:0xa bound_ctrl:1
	v_add_f32_dpp v81, v81, v81 row_shl:4 row_mask:0xf bank_mask:0x5 bound_ctrl:1
	v_add_f32_dpp v81, v89, v89 row_shr:4 row_mask:0xf bank_mask:0xa bound_ctrl:1
	v_add_f32_dpp v83, v83, v83 row_shl:4 row_mask:0xf bank_mask:0x5 bound_ctrl:1
	v_add_f32_dpp v83, v91, v91 row_shr:4 row_mask:0xf bank_mask:0xa bound_ctrl:1
	v_add_f32_dpp v85, v85, v85 row_shl:4 row_mask:0xf bank_mask:0x5 bound_ctrl:1
	v_add_f32_dpp v85, v93, v93 row_shr:4 row_mask:0xf bank_mask:0xa bound_ctrl:1
	v_add_f32_dpp v78, v78, v78 quad_perm:[1,0,3,2] row_mask:0xf bank_mask:0xf bound_ctrl:1
	v_add_f32_dpp v80, v80, v80 quad_perm:[1,0,3,2] row_mask:0xf bank_mask:0xf bound_ctrl:1
	v_add_f32_dpp v82, v82, v82 quad_perm:[1,0,3,2] row_mask:0xf bank_mask:0xf bound_ctrl:1
	v_add_f32_dpp v84, v84, v84 quad_perm:[1,0,3,2] row_mask:0xf bank_mask:0xf bound_ctrl:1
	v_add_f32_dpp v79, v79, v79 quad_perm:[1,0,3,2] row_mask:0xf bank_mask:0xf bound_ctrl:1
	v_add_f32_dpp v81, v81, v81 quad_perm:[1,0,3,2] row_mask:0xf bank_mask:0xf bound_ctrl:1
	v_add_f32_dpp v83, v83, v83 quad_perm:[1,0,3,2] row_mask:0xf bank_mask:0xf bound_ctrl:1
	v_add_f32_dpp v85, v85, v85 quad_perm:[1,0,3,2] row_mask:0xf bank_mask:0xf bound_ctrl:1
	v_add_f32_dpp v78, v78, v78 quad_perm:[2,3,0,1] row_mask:0xf bank_mask:0xf bound_ctrl:1
	v_add_f32_dpp v80, v80, v80 quad_perm:[2,3,0,1] row_mask:0xf bank_mask:0xf bound_ctrl:1
	v_add_f32_dpp v82, v82, v82 quad_perm:[2,3,0,1] row_mask:0xf bank_mask:0xf bound_ctrl:1
	v_add_f32_dpp v84, v84, v84 quad_perm:[2,3,0,1] row_mask:0xf bank_mask:0xf bound_ctrl:1
	v_add_f32_dpp v79, v79, v79 quad_perm:[2,3,0,1] row_mask:0xf bank_mask:0xf bound_ctrl:1
	v_add_f32_dpp v81, v81, v81 quad_perm:[2,3,0,1] row_mask:0xf bank_mask:0xf bound_ctrl:1
	v_add_f32_dpp v83, v83, v83 quad_perm:[2,3,0,1] row_mask:0xf bank_mask:0xf bound_ctrl:1
	v_add_f32_dpp v85, v85, v85 quad_perm:[2,3,0,1] row_mask:0xf bank_mask:0xf bound_ctrl:1
	v_add_u32_e32 v72, 0, v57
	v_ashrrev_i32_e32 v73, 31, v72
	v_lshlrev_b64 v[72:73], 10, v[72:73]
	v_lshl_add_u64 v[72:73], v[64:65], 0, v[72:73]
	v_cndmask_b32_e64 v154, v84, v82, s[16:17]
	v_cndmask_b32_e64 v155, v85, v83, s[16:17]
	v_cndmask_b32_e64 v154, v154, v80, s[14:15]
	v_cndmask_b32_e64 v155, v155, v81, s[14:15]
	v_cndmask_b32_e64 v154, v154, v78, s[12:13]
	v_cndmask_b32_e64 v155, v155, v79, s[12:13]
	v_cvt_pk_bf16_f32 v154, v154, v155
	global_store_dword v[72:73], v154, off
	v_pk_mul_f32 v[110:111], v[66:67], v[160:161] op_sel_hi:[1,0]
	v_pk_mul_f32 v[150:151], v[66:67], v[192:193] op_sel_hi:[1,0]
	v_pk_fma_f32 v[142:143], v[66:67], v[184:185], v[66:67] op_sel_hi:[1,0,1] neg_lo:[1,0,0] neg_hi:[1,0,0]
	v_pk_fma_f32 v[110:111], v[20:21], v[160:161], v[110:111] op_sel:[0,1,0]
	v_pk_fma_f32 v[150:151], v[20:21], v[192:193], v[150:151] op_sel:[0,1,0]
	v_pk_fma_f32 v[144:145], v[20:21], v[184:185], v[20:21] op_sel:[0,1,0] neg_lo:[1,0,0] neg_hi:[1,0,0]
	v_pk_fma_f32 v[110:111], v[68:69], v[162:163], v[110:111] op_sel_hi:[1,0,1]
	v_pk_fma_f32 v[150:151], v[68:69], v[194:195], v[150:151] op_sel_hi:[1,0,1]
	v_pk_fma_f32 v[146:147], v[68:69], v[186:187], v[68:69] op_sel_hi:[1,0,1] neg_lo:[1,0,0] neg_hi:[1,0,0]
	v_pk_fma_f32 v[110:111], v[70:71], v[162:163], v[110:111] op_sel:[0,1,0]
	v_pk_fma_f32 v[150:151], v[70:71], v[194:195], v[150:151] op_sel:[0,1,0]
	v_pk_fma_f32 v[148:149], v[70:71], v[186:187], v[70:71] op_sel:[0,1,0] neg_lo:[1,0,0] neg_hi:[1,0,0]
	v_pk_fma_f32 v[142:143], v[250:251], v[188:189], v[142:143] op_sel_hi:[1,0,1]
	v_pk_fma_f32 v[144:145], v[250:251], v[188:189], v[144:145] op_sel:[0,1,0]
	v_add_f32_dpp v150, v150, v150 quad_perm:[1,0,3,2] row_mask:0xf bank_mask:0xf bound_ctrl:1
	v_add_f32_dpp v151, v151, v151 quad_perm:[1,0,3,2] row_mask:0xf bank_mask:0xf bound_ctrl:1
	v_pk_fma_f32 v[146:147], v[250:251], v[190:191], v[146:147] op_sel_hi:[1,0,1]
	v_add_f32_dpp v150, v150, v150 quad_perm:[2,3,0,1] row_mask:0xf bank_mask:0xf bound_ctrl:1
	v_add_f32_dpp v151, v151, v151 quad_perm:[2,3,0,1] row_mask:0xf bank_mask:0xf bound_ctrl:1
	v_pk_fma_f32 v[148:149], v[250:251], v[190:191], v[148:149] op_sel:[0,1,0]
	v_add_f32_dpp v150, v150, v150 row_half_mirror row_mask:0xf bank_mask:0xf bound_ctrl:1
	v_add_f32_dpp v151, v151, v151 row_half_mirror row_mask:0xf bank_mask:0xf bound_ctrl:1
	s_nop 0
	v_add_f32_dpp v150, v150, v150 row_mirror row_mask:0xf bank_mask:0xf bound_ctrl:1
	v_add_f32_dpp v151, v151, v151 row_mirror row_mask:0xf bank_mask:0xf bound_ctrl:1
	s_waitcnt lgkmcnt(0)
; #define LAS __attribute__((address_space(3)))
; #define ROW16_SUM4(x, y, z, w) do { DPP4(x, y, z, w, "quad_perm:[1,0,3,2]", "s_nop 1"); DPP4(x, y, z, w, "quad_perm:[2,3,0,1]", ""); DPP4(x, y, z, w, "row_half_mirror", ""); DPP4(x, y, z, w, "row_mirror", ""); } while (0)
; template <bool SAMPLE>
; __device__ __forceinline__ void rwkv_unit(PR P, LAS float* lds, const int b, const int h, const int half, const int wv) {
;     ...
;                 for (int tt = 0; tt < GS; ++tt) {
;                     const LAS float* qn = q0 + (tt + 1 < GS ? tt + 1 : tt) * 384;
;                     const f32x4 nr4 = *(const LAS f32x4*)(qn + j0), no4 = *(const LAS f32x4*)(qn + 64 + j0), nk4 = *(const LAS f32x4*)(qn + 128 + j0), na4 = *(const LAS f32x4*)(qn + 192 + j0), nb4 = *(const LAS f32x4*)(qn + 256 + j0);
;                     const f32x2 nv2 = *(const LAS f32x2*)(qn + 320 + row0);
;                     f32x2 sa = (S[0] * a4[0] + S[1] * a4[1]) + (S[2] * a4[2] + S[3] * a4[3]);
;                     float sx = sa.x, sy = sa.y; ROW16_SUM4(sx, sy, py0, py1); sa = (f32x2){sx, sy};
;                     if (tt > 0) { yk0 = cgl == tt - 1 ? py0 : yk0; yk1 = cgl == tt - 1 ? py1 : yk1; }
; #pragma unroll
;                     for (int c = 0; c < 4; ++c) { f32x2 t = S[c] - S[c] * o4[c]; t = t + sa * b4[c]; S[c] = t + v2 * k4[c]; }
;                     const f32x2 y = (S[0] * r4[0] + S[1] * r4[1]) + (S[2] * r4[2] + S[3] * r4[3]);
;                     py0 = y.x; py1 = y.y;
;                     r4 = nr4; o4 = no4; k4 = nk4; a4 = na4; b4 = nb4; v2 = nv2;
	v_pk_fma_f32 v[66:67], v[150:151], v[196:197], v[142:143] op_sel_hi:[1,0,1]
	v_pk_fma_f32 v[20:21], v[150:151], v[196:197], v[144:145] op_sel:[0,1,0]
	v_pk_fma_f32 v[68:69], v[150:151], v[198:199], v[146:147] op_sel_hi:[1,0,1]
	v_pk_fma_f32 v[70:71], v[150:151], v[198:199], v[148:149] op_sel:[0,1,0]
	v_pk_mul_f32 v[112:113], v[66:67], v[180:181] op_sel_hi:[1,0]
	v_pk_mul_f32 v[150:151], v[66:67], v[212:213] op_sel_hi:[1,0]
	v_pk_fma_f32 v[142:143], v[66:67], v[204:205], v[66:67] op_sel_hi:[1,0,1] neg_lo:[1,0,0] neg_hi:[1,0,0]
	ds_read_b128 v[172:175], v152 offset:31488
	v_pk_fma_f32 v[112:113], v[20:21], v[180:181], v[112:113] op_sel:[0,1,0]
	v_pk_fma_f32 v[150:151], v[20:21], v[212:213], v[150:151] op_sel:[0,1,0]
	v_pk_fma_f32 v[144:145], v[20:21], v[204:205], v[20:21] op_sel:[0,1,0] neg_lo:[1,0,0] neg_hi:[1,0,0]
	ds_read_b128 v[164:167], v152 offset:30976
	v_pk_fma_f32 v[112:113], v[68:69], v[182:183], v[112:113] op_sel_hi:[1,0,1]
	v_pk_fma_f32 v[150:151], v[68:69], v[214:215], v[150:151] op_sel_hi:[1,0,1]
	v_pk_fma_f32 v[146:147], v[68:69], v[206:207], v[68:69] op_sel_hi:[1,0,1] neg_lo:[1,0,0] neg_hi:[1,0,0]
	ds_read2st64_b64 v[244:247], v153 offset0:62 offset1:65
	v_pk_fma_f32 v[112:113], v[70:71], v[182:183], v[112:113] op_sel:[0,1,0]
	v_pk_fma_f32 v[150:151], v[70:71], v[214:215], v[150:151] op_sel:[0,1,0]
	v_pk_fma_f32 v[148:149], v[70:71], v[206:207], v[70:71] op_sel:[0,1,0] neg_lo:[1,0,0] neg_hi:[1,0,0]
	ds_read_b128 v[168:171], v152 offset:31232
	v_pk_fma_f32 v[142:143], v[240:241], v[208:209], v[142:143] op_sel_hi:[1,0,1]
	v_pk_fma_f32 v[144:145], v[240:241], v[208:209], v[144:145] op_sel:[0,1,0]
	v_add_f32_dpp v150, v150, v150 quad_perm:[1,0,3,2] row_mask:0xf bank_mask:0xf bound_ctrl:1
	v_add_f32_dpp v151, v151, v151 quad_perm:[1,0,3,2] row_mask:0xf bank_mask:0xf bound_ctrl:1
	v_pk_fma_f32 v[146:147], v[240:241], v[210:211], v[146:147] op_sel_hi:[1,0,1]
	v_add_f32_dpp v150, v150, v150 quad_perm:[2,3,0,1] row_mask:0xf bank_mask:0xf bound_ctrl:1
	v_add_f32_dpp v151, v151, v151 quad_perm:[2,3,0,1] row_mask:0xf bank_mask:0xf bound_ctrl:1
	v_pk_fma_f32 v[148:149], v[240:241], v[210:211], v[148:149] op_sel:[0,1,0]
	v_add_f32_dpp v150, v150, v150 row_half_mirror row_mask:0xf bank_mask:0xf bound_ctrl:1
	v_add_f32_dpp v151, v151, v151 row_half_mirror row_mask:0xf bank_mask:0xf bound_ctrl:1
	ds_read_b128 v[192:195], v152 offset:33024
	v_add_f32_dpp v150, v150, v150 row_mirror row_mask:0xf bank_mask:0xf bound_ctrl:1
	v_add_f32_dpp v151, v151, v151 row_mirror row_mask:0xf bank_mask:0xf bound_ctrl:1
	ds_read_b128 v[184:187], v152 offset:32512
	ds_read_b128 v[176:179], v152 offset:31744
	ds_read_b128 v[188:191], v152 offset:32768
	ds_read_b128 v[196:199], v152 offset:33280
	ds_read_b128 v[160:163], v152 offset:30720
	ds_read_b128 v[180:183], v152 offset:32256
	v_pk_fma_f32 v[66:67], v[150:151], v[216:217], v[142:143] op_sel_hi:[1,0,1]
	v_pk_fma_f32 v[20:21], v[150:151], v[216:217], v[144:145] op_sel:[0,1,0]
	v_pk_fma_f32 v[68:69], v[150:151], v[218:219], v[146:147] op_sel_hi:[1,0,1]
	v_pk_fma_f32 v[70:71], v[150:151], v[218:219], v[148:149] op_sel:[0,1,0]
	v_pk_mul_f32 v[114:115], v[66:67], v[200:201] op_sel_hi:[1,0]
	v_pk_mul_f32 v[150:151], v[66:67], v[232:233] op_sel_hi:[1,0]
	v_pk_fma_f32 v[142:143], v[66:67], v[224:225], v[66:67] op_sel_hi:[1,0,1] neg_lo:[1,0,0] neg_hi:[1,0,0]
	v_pk_fma_f32 v[114:115], v[20:21], v[200:201], v[114:115] op_sel:[0,1,0]
	v_pk_fma_f32 v[150:151], v[20:21], v[232:233], v[150:151] op_sel:[0,1,0]
	v_pk_fma_f32 v[144:145], v[20:21], v[224:225], v[20:21] op_sel:[0,1,0] neg_lo:[1,0,0] neg_hi:[1,0,0]
	v_pk_fma_f32 v[114:115], v[68:69], v[202:203], v[114:115] op_sel_hi:[1,0,1]
	v_pk_fma_f32 v[150:151], v[68:69], v[234:235], v[150:151] op_sel_hi:[1,0,1]
	v_pk_fma_f32 v[146:147], v[68:69], v[226:227], v[68:69] op_sel_hi:[1,0,1] neg_lo:[1,0,0] neg_hi:[1,0,0]
	v_pk_fma_f32 v[114:115], v[70:71], v[202:203], v[114:115] op_sel:[0,1,0]
	v_pk_fma_f32 v[150:151], v[70:71], v[234:235], v[150:151] op_sel:[0,1,0]
	v_pk_fma_f32 v[148:149], v[70:71], v[226:227], v[70:71] op_sel:[0,1,0] neg_lo:[1,0,0] neg_hi:[1,0,0]
	v_pk_fma_f32 v[142:143], v[242:243], v[228:229], v[142:143] op_sel_hi:[1,0,1]
	v_pk_fma_f32 v[144:145], v[242:243], v[228:229], v[144:145] op_sel:[0,1,0]
	v_add_f32_dpp v150, v150, v150 quad_perm:[1,0,3,2] row_mask:0xf bank_mask:0xf bound_ctrl:1
	v_add_f32_dpp v151, v151, v151 quad_perm:[1,0,3,2] row_mask:0xf bank_mask:0xf bound_ctrl:1
	v_pk_fma_f32 v[146:147], v[242:243], v[230:231], v[146:147] op_sel_hi:[1,0,1]
	v_add_f32_dpp v150, v150, v150 quad_perm:[2,3,0,1] row_mask:0xf bank_mask:0xf bound_ctrl:1
	v_add_f32_dpp v151, v151, v151 quad_perm:[2,3,0,1] row_mask:0xf bank_mask:0xf bound_ctrl:1
	v_pk_fma_f32 v[148:149], v[242:243], v[230:231], v[148:149] op_sel:[0,1,0]
	v_add_f32_dpp v150, v150, v150 row_half_mirror row_mask:0xf bank_mask:0xf bound_ctrl:1
	v_add_f32_dpp v151, v151, v151 row_half_mirror row_mask:0xf bank_mask:0xf bound_ctrl:1
	s_nop 0
	v_add_f32_dpp v150, v150, v150 row_mirror row_mask:0xf bank_mask:0xf bound_ctrl:1
	v_add_f32_dpp v151, v151, v151 row_mirror row_mask:0xf bank_mask:0xf bound_ctrl:1
	s_waitcnt lgkmcnt(0)
; #define LAS __attribute__((address_space(3)))
; #define ROW16_SUM4(x, y, z, w) do { DPP4(x, y, z, w, "quad_perm:[1,0,3,2]", "s_nop 1"); DPP4(x, y, z, w, "quad_perm:[2,3,0,1]", ""); DPP4(x, y, z, w, "row_half_mirror", ""); DPP4(x, y, z, w, "row_mirror", ""); } while (0)
; template <bool SAMPLE>
; __device__ __forceinline__ void rwkv_unit(PR P, LAS float* lds, const int b, const int h, const int half, const int wv) {
;     ...
;                 for (int tt = 0; tt < GS; ++tt) {
;                     const LAS float* qn = q0 + (tt + 1 < GS ? tt + 1 : tt) * 384;
;                     const f32x4 nr4 = *(const LAS f32x4*)(qn + j0), no4 = *(const LAS f32x4*)(qn + 64 + j0), nk4 = *(const LAS f32x4*)(qn + 128 + j0), na4 = *(const LAS f32x4*)(qn + 192 + j0), nb4 = *(const LAS f32x4*)(qn + 256 + j0);
;                     const f32x2 nv2 = *(const LAS f32x2*)(qn + 320 + row0);
;                     f32x2 sa = (S[0] * a4[0] + S[1] * a4[1]) + (S[2] * a4[2] + S[3] * a4[3]);
;                     float sx = sa.x, sy = sa.y; ROW16_SUM4(sx, sy, py0, py1); sa = (f32x2){sx, sy};
;                     if (tt > 0) { yk0 = cgl == tt - 1 ? py0 : yk0; yk1 = cgl == tt - 1 ? py1 : yk1; }
; #pragma unroll
;                     for (int c = 0; c < 4; ++c) { f32x2 t = S[c] - S[c] * o4[c]; t = t + sa * b4[c]; S[c] = t + v2 * k4[c]; }
;                     const f32x2 y = (S[0] * r4[0] + S[1] * r4[1]) + (S[2] * r4[2] + S[3] * r4[3]);
;                     py0 = y.x; py1 = y.y;
;                     r4 = nr4; o4 = no4; k4 = nk4; a4 = na4; b4 = nb4; v2 = nv2;
	v_pk_fma_f32 v[66:67], v[150:151], v[236:237], v[142:143] op_sel_hi:[1,0,1]
	v_pk_fma_f32 v[20:21], v[150:151], v[236:237], v[144:145] op_sel:[0,1,0]
	v_pk_fma_f32 v[68:69], v[150:151], v[238:239], v[146:147] op_sel_hi:[1,0,1]
	v_pk_fma_f32 v[70:71], v[150:151], v[238:239], v[148:149] op_sel:[0,1,0]
	v_pk_mul_f32 v[116:117], v[66:67], v[220:221] op_sel_hi:[1,0]
	v_pk_mul_f32 v[150:151], v[66:67], v[172:173] op_sel_hi:[1,0]
	v_pk_fma_f32 v[142:143], v[66:67], v[164:165], v[66:67] op_sel_hi:[1,0,1] neg_lo:[1,0,0] neg_hi:[1,0,0]
	ds_read_b128 v[212:215], v152 offset:34560
	v_pk_fma_f32 v[116:117], v[20:21], v[220:221], v[116:117] op_sel:[0,1,0]
	v_pk_fma_f32 v[150:151], v[20:21], v[172:173], v[150:151] op_sel:[0,1,0]
	v_pk_fma_f32 v[144:145], v[20:21], v[164:165], v[20:21] op_sel:[0,1,0] neg_lo:[1,0,0] neg_hi:[1,0,0]
	ds_read_b128 v[204:207], v152 offset:34048
	v_pk_fma_f32 v[116:117], v[68:69], v[222:223], v[116:117] op_sel_hi:[1,0,1]
	v_pk_fma_f32 v[150:151], v[68:69], v[174:175], v[150:151] op_sel_hi:[1,0,1]
	v_pk_fma_f32 v[146:147], v[68:69], v[166:167], v[68:69] op_sel_hi:[1,0,1] neg_lo:[1,0,0] neg_hi:[1,0,0]
	ds_read2st64_b64 v[248:251], v153 offset0:68 offset1:71
	v_pk_fma_f32 v[116:117], v[70:71], v[222:223], v[116:117] op_sel:[0,1,0]
	v_pk_fma_f32 v[150:151], v[70:71], v[174:175], v[150:151] op_sel:[0,1,0]
	v_pk_fma_f32 v[148:149], v[70:71], v[166:167], v[70:71] op_sel:[0,1,0] neg_lo:[1,0,0] neg_hi:[1,0,0]
	ds_read_b128 v[208:211], v152 offset:34304
	v_pk_fma_f32 v[142:143], v[244:245], v[168:169], v[142:143] op_sel_hi:[1,0,1]
	v_pk_fma_f32 v[144:145], v[244:245], v[168:169], v[144:145] op_sel:[0,1,0]
	v_add_f32_dpp v150, v150, v150 quad_perm:[1,0,3,2] row_mask:0xf bank_mask:0xf bound_ctrl:1
	v_add_f32_dpp v151, v151, v151 quad_perm:[1,0,3,2] row_mask:0xf bank_mask:0xf bound_ctrl:1
	v_pk_fma_f32 v[146:147], v[244:245], v[170:171], v[146:147] op_sel_hi:[1,0,1]
	v_add_f32_dpp v150, v150, v150 quad_perm:[2,3,0,1] row_mask:0xf bank_mask:0xf bound_ctrl:1
	v_add_f32_dpp v151, v151, v151 quad_perm:[2,3,0,1] row_mask:0xf bank_mask:0xf bound_ctrl:1
	v_pk_fma_f32 v[148:149], v[244:245], v[170:171], v[148:149] op_sel:[0,1,0]
	v_add_f32_dpp v150, v150, v150 row_half_mirror row_mask:0xf bank_mask:0xf bound_ctrl:1
	v_add_f32_dpp v151, v151, v151 row_half_mirror row_mask:0xf bank_mask:0xf bound_ctrl:1
	ds_read_b128 v[232:235], v152 offset:36096
	v_add_f32_dpp v150, v150, v150 row_mirror row_mask:0xf bank_mask:0xf bound_ctrl:1
	v_add_f32_dpp v151, v151, v151 row_mirror row_mask:0xf bank_mask:0xf bound_ctrl:1
	ds_read_b128 v[224:227], v152 offset:35584
	ds_read_b128 v[216:219], v152 offset:34816
	ds_read_b128 v[228:231], v152 offset:35840
	ds_read_b128 v[236:239], v152 offset:36352
	ds_read_b128 v[200:203], v152 offset:33792
	ds_read_b128 v[220:223], v152 offset:35328
	v_pk_fma_f32 v[66:67], v[150:151], v[176:177], v[142:143] op_sel_hi:[1,0,1]
	v_pk_fma_f32 v[20:21], v[150:151], v[176:177], v[144:145] op_sel:[0,1,0]
	v_pk_fma_f32 v[68:69], v[150:151], v[178:179], v[146:147] op_sel_hi:[1,0,1]
	v_pk_fma_f32 v[70:71], v[150:151], v[178:179], v[148:149] op_sel:[0,1,0]
	v_pk_mul_f32 v[118:119], v[66:67], v[160:161] op_sel_hi:[1,0]
	v_pk_mul_f32 v[150:151], v[66:67], v[192:193] op_sel_hi:[1,0]
	v_pk_fma_f32 v[142:143], v[66:67], v[184:185], v[66:67] op_sel_hi:[1,0,1] neg_lo:[1,0,0] neg_hi:[1,0,0]
	v_pk_fma_f32 v[118:119], v[20:21], v[160:161], v[118:119] op_sel:[0,1,0]
	v_pk_fma_f32 v[150:151], v[20:21], v[192:193], v[150:151] op_sel:[0,1,0]
	v_pk_fma_f32 v[144:145], v[20:21], v[184:185], v[20:21] op_sel:[0,1,0] neg_lo:[1,0,0] neg_hi:[1,0,0]
	v_pk_fma_f32 v[118:119], v[68:69], v[162:163], v[118:119] op_sel_hi:[1,0,1]
	v_pk_fma_f32 v[150:151], v[68:69], v[194:195], v[150:151] op_sel_hi:[1,0,1]
	v_pk_fma_f32 v[146:147], v[68:69], v[186:187], v[68:69] op_sel_hi:[1,0,1] neg_lo:[1,0,0] neg_hi:[1,0,0]
	v_pk_fma_f32 v[118:119], v[70:71], v[162:163], v[118:119] op_sel:[0,1,0]
	v_pk_fma_f32 v[150:151], v[70:71], v[194:195], v[150:151] op_sel:[0,1,0]
	v_pk_fma_f32 v[148:149], v[70:71], v[186:187], v[70:71] op_sel:[0,1,0] neg_lo:[1,0,0] neg_hi:[1,0,0]
	v_pk_fma_f32 v[142:143], v[246:247], v[188:189], v[142:143] op_sel_hi:[1,0,1]
	v_pk_fma_f32 v[144:145], v[246:247], v[188:189], v[144:145] op_sel:[0,1,0]
	v_add_f32_dpp v150, v150, v150 quad_perm:[1,0,3,2] row_mask:0xf bank_mask:0xf bound_ctrl:1
	v_add_f32_dpp v151, v151, v151 quad_perm:[1,0,3,2] row_mask:0xf bank_mask:0xf bound_ctrl:1
	v_pk_fma_f32 v[146:147], v[246:247], v[190:191], v[146:147] op_sel_hi:[1,0,1]
	v_add_f32_dpp v150, v150, v150 quad_perm:[2,3,0,1] row_mask:0xf bank_mask:0xf bound_ctrl:1
	v_add_f32_dpp v151, v151, v151 quad_perm:[2,3,0,1] row_mask:0xf bank_mask:0xf bound_ctrl:1
	v_pk_fma_f32 v[148:149], v[246:247], v[190:191], v[148:149] op_sel:[0,1,0]
	v_add_f32_dpp v150, v150, v150 row_half_mirror row_mask:0xf bank_mask:0xf bound_ctrl:1
	v_add_f32_dpp v151, v151, v151 row_half_mirror row_mask:0xf bank_mask:0xf bound_ctrl:1
	s_nop 0
	v_add_f32_dpp v150, v150, v150 row_mirror row_mask:0xf bank_mask:0xf bound_ctrl:1
	v_add_f32_dpp v151, v151, v151 row_mirror row_mask:0xf bank_mask:0xf bound_ctrl:1
	s_waitcnt lgkmcnt(0)
; #define LAS __attribute__((address_space(3)))
; #define ROW16_SUM4(x, y, z, w) do { DPP4(x, y, z, w, "quad_perm:[1,0,3,2]", "s_nop 1"); DPP4(x, y, z, w, "quad_perm:[2,3,0,1]", ""); DPP4(x, y, z, w, "row_half_mirror", ""); DPP4(x, y, z, w, "row_mirror", ""); } while (0)
; template <bool SAMPLE>
; __device__ __forceinline__ void rwkv_unit(PR P, LAS float* lds, const int b, const int h, const int half, const int wv) {
;     ...
;                 for (int tt = 0; tt < GS; ++tt) {
;                     const LAS float* qn = q0 + (tt + 1 < GS ? tt + 1 : tt) * 384;
;                     const f32x4 nr4 = *(const LAS f32x4*)(qn + j0), no4 = *(const LAS f32x4*)(qn + 64 + j0), nk4 = *(const LAS f32x4*)(qn + 128 + j0), na4 = *(const LAS f32x4*)(qn + 192 + j0), nb4 = *(const LAS f32x4*)(qn + 256 + j0);
;                     const f32x2 nv2 = *(const LAS f32x2*)(qn + 320 + row0);
;                     f32x2 sa = (S[0] * a4[0] + S[1] * a4[1]) + (S[2] * a4[2] + S[3] * a4[3]);
;                     float sx = sa.x, sy = sa.y; ROW16_SUM4(sx, sy, py0, py1); sa = (f32x2){sx, sy};
;                     if (tt > 0) { yk0 = cgl == tt - 1 ? py0 : yk0; yk1 = cgl == tt - 1 ? py1 : yk1; }
; #pragma unroll
;                     for (int c = 0; c < 4; ++c) { f32x2 t = S[c] - S[c] * o4[c]; t = t + sa * b4[c]; S[c] = t + v2 * k4[c]; }
;                     const f32x2 y = (S[0] * r4[0] + S[1] * r4[1]) + (S[2] * r4[2] + S[3] * r4[3]);
;                     py0 = y.x; py1 = y.y;
;                     r4 = nr4; o4 = no4; k4 = nk4; a4 = na4; b4 = nb4; v2 = nv2;
	v_pk_fma_f32 v[66:67], v[150:151], v[196:197], v[142:143] op_sel_hi:[1,0,1]
	v_pk_fma_f32 v[20:21], v[150:151], v[196:197], v[144:145] op_sel:[0,1,0]
	v_pk_fma_f32 v[68:69], v[150:151], v[198:199], v[146:147] op_sel_hi:[1,0,1]
	v_pk_fma_f32 v[70:71], v[150:151], v[198:199], v[148:149] op_sel:[0,1,0]
	v_pk_mul_f32 v[120:121], v[66:67], v[180:181] op_sel_hi:[1,0]
	v_pk_mul_f32 v[150:151], v[66:67], v[212:213] op_sel_hi:[1,0]
	v_pk_fma_f32 v[142:143], v[66:67], v[204:205], v[66:67] op_sel_hi:[1,0,1] neg_lo:[1,0,0] neg_hi:[1,0,0]
	ds_read_b128 v[172:175], v152 offset:37632
	v_pk_fma_f32 v[120:121], v[20:21], v[180:181], v[120:121] op_sel:[0,1,0]
	v_pk_fma_f32 v[150:151], v[20:21], v[212:213], v[150:151] op_sel:[0,1,0]
	v_pk_fma_f32 v[144:145], v[20:21], v[204:205], v[20:21] op_sel:[0,1,0] neg_lo:[1,0,0] neg_hi:[1,0,0]
	ds_read_b128 v[164:167], v152 offset:37120
	v_pk_fma_f32 v[120:121], v[68:69], v[182:183], v[120:121] op_sel_hi:[1,0,1]
	v_pk_fma_f32 v[150:151], v[68:69], v[214:215], v[150:151] op_sel_hi:[1,0,1]
	v_pk_fma_f32 v[146:147], v[68:69], v[206:207], v[68:69] op_sel_hi:[1,0,1] neg_lo:[1,0,0] neg_hi:[1,0,0]
	ds_read2st64_b64 v[240:243], v153 offset0:74 offset1:77
	v_pk_fma_f32 v[120:121], v[70:71], v[182:183], v[120:121] op_sel:[0,1,0]
	v_pk_fma_f32 v[150:151], v[70:71], v[214:215], v[150:151] op_sel:[0,1,0]
	v_pk_fma_f32 v[148:149], v[70:71], v[206:207], v[70:71] op_sel:[0,1,0] neg_lo:[1,0,0] neg_hi:[1,0,0]
	ds_read_b128 v[168:171], v152 offset:37376
	v_pk_fma_f32 v[142:143], v[248:249], v[208:209], v[142:143] op_sel_hi:[1,0,1]
	v_pk_fma_f32 v[144:145], v[248:249], v[208:209], v[144:145] op_sel:[0,1,0]
	v_add_f32_dpp v150, v150, v150 quad_perm:[1,0,3,2] row_mask:0xf bank_mask:0xf bound_ctrl:1
	v_add_f32_dpp v151, v151, v151 quad_perm:[1,0,3,2] row_mask:0xf bank_mask:0xf bound_ctrl:1
	v_pk_fma_f32 v[146:147], v[248:249], v[210:211], v[146:147] op_sel_hi:[1,0,1]
	v_add_f32_dpp v150, v150, v150 quad_perm:[2,3,0,1] row_mask:0xf bank_mask:0xf bound_ctrl:1
	v_add_f32_dpp v151, v151, v151 quad_perm:[2,3,0,1] row_mask:0xf bank_mask:0xf bound_ctrl:1
	v_pk_fma_f32 v[148:149], v[248:249], v[210:211], v[148:149] op_sel:[0,1,0]
	v_add_f32_dpp v150, v150, v150 row_half_mirror row_mask:0xf bank_mask:0xf bound_ctrl:1
	v_add_f32_dpp v151, v151, v151 row_half_mirror row_mask:0xf bank_mask:0xf bound_ctrl:1
	ds_read_b128 v[192:195], v152 offset:39168
	v_add_f32_dpp v150, v150, v150 row_mirror row_mask:0xf bank_mask:0xf bound_ctrl:1
	v_add_f32_dpp v151, v151, v151 row_mirror row_mask:0xf bank_mask:0xf bound_ctrl:1
	ds_read_b128 v[184:187], v152 offset:38656
	ds_read_b128 v[176:179], v152 offset:37888
	ds_read_b128 v[188:191], v152 offset:38912
	ds_read_b128 v[196:199], v152 offset:39424
	ds_read_b128 v[160:163], v152 offset:36864
	ds_read_b128 v[180:183], v152 offset:38400
	v_pk_fma_f32 v[66:67], v[150:151], v[216:217], v[142:143] op_sel_hi:[1,0,1]
	v_pk_fma_f32 v[20:21], v[150:151], v[216:217], v[144:145] op_sel:[0,1,0]
	v_pk_fma_f32 v[68:69], v[150:151], v[218:219], v[146:147] op_sel_hi:[1,0,1]
	v_pk_fma_f32 v[70:71], v[150:151], v[218:219], v[148:149] op_sel:[0,1,0]
	v_pk_mul_f32 v[122:123], v[66:67], v[200:201] op_sel_hi:[1,0]
	v_pk_mul_f32 v[150:151], v[66:67], v[232:233] op_sel_hi:[1,0]
	v_pk_fma_f32 v[142:143], v[66:67], v[224:225], v[66:67] op_sel_hi:[1,0,1] neg_lo:[1,0,0] neg_hi:[1,0,0]
	v_pk_fma_f32 v[122:123], v[20:21], v[200:201], v[122:123] op_sel:[0,1,0]
	v_pk_fma_f32 v[150:151], v[20:21], v[232:233], v[150:151] op_sel:[0,1,0]
	v_pk_fma_f32 v[144:145], v[20:21], v[224:225], v[20:21] op_sel:[0,1,0] neg_lo:[1,0,0] neg_hi:[1,0,0]
	v_pk_fma_f32 v[122:123], v[68:69], v[202:203], v[122:123] op_sel_hi:[1,0,1]
	v_pk_fma_f32 v[150:151], v[68:69], v[234:235], v[150:151] op_sel_hi:[1,0,1]
	v_pk_fma_f32 v[146:147], v[68:69], v[226:227], v[68:69] op_sel_hi:[1,0,1] neg_lo:[1,0,0] neg_hi:[1,0,0]
	v_pk_fma_f32 v[122:123], v[70:71], v[202:203], v[122:123] op_sel:[0,1,0]
	v_pk_fma_f32 v[150:151], v[70:71], v[234:235], v[150:151] op_sel:[0,1,0]
	v_pk_fma_f32 v[148:149], v[70:71], v[226:227], v[70:71] op_sel:[0,1,0] neg_lo:[1,0,0] neg_hi:[1,0,0]
	v_pk_fma_f32 v[142:143], v[250:251], v[228:229], v[142:143] op_sel_hi:[1,0,1]
	v_pk_fma_f32 v[144:145], v[250:251], v[228:229], v[144:145] op_sel:[0,1,0]
	v_add_f32_dpp v150, v150, v150 quad_perm:[1,0,3,2] row_mask:0xf bank_mask:0xf bound_ctrl:1
	v_add_f32_dpp v151, v151, v151 quad_perm:[1,0,3,2] row_mask:0xf bank_mask:0xf bound_ctrl:1
	v_pk_fma_f32 v[146:147], v[250:251], v[230:231], v[146:147] op_sel_hi:[1,0,1]
	v_add_f32_dpp v150, v150, v150 quad_perm:[2,3,0,1] row_mask:0xf bank_mask:0xf bound_ctrl:1
	v_add_f32_dpp v151, v151, v151 quad_perm:[2,3,0,1] row_mask:0xf bank_mask:0xf bound_ctrl:1
	v_pk_fma_f32 v[148:149], v[250:251], v[230:231], v[148:149] op_sel:[0,1,0]
	v_add_f32_dpp v150, v150, v150 row_half_mirror row_mask:0xf bank_mask:0xf bound_ctrl:1
	v_add_f32_dpp v151, v151, v151 row_half_mirror row_mask:0xf bank_mask:0xf bound_ctrl:1
	s_nop 0
	v_add_f32_dpp v150, v150, v150 row_mirror row_mask:0xf bank_mask:0xf bound_ctrl:1
	v_add_f32_dpp v151, v151, v151 row_mirror row_mask:0xf bank_mask:0xf bound_ctrl:1
	s_waitcnt lgkmcnt(0)
; #define LAS __attribute__((address_space(3)))
; #define ROW16_SUM4(x, y, z, w) do { DPP4(x, y, z, w, "quad_perm:[1,0,3,2]", "s_nop 1"); DPP4(x, y, z, w, "quad_perm:[2,3,0,1]", ""); DPP4(x, y, z, w, "row_half_mirror", ""); DPP4(x, y, z, w, "row_mirror", ""); } while (0)
; template <bool SAMPLE>
; __device__ __forceinline__ void rwkv_unit(PR P, LAS float* lds, const int b, const int h, const int half, const int wv) {
;     ...
;                 for (int tt = 0; tt < GS; ++tt) {
;                     const LAS float* qn = q0 + (tt + 1 < GS ? tt + 1 : tt) * 384;
;                     const f32x4 nr4 = *(const LAS f32x4*)(qn + j0), no4 = *(const LAS f32x4*)(qn + 64 + j0), nk4 = *(const LAS f32x4*)(qn + 128 + j0), na4 = *(const LAS f32x4*)(qn + 192 + j0), nb4 = *(const LAS f32x4*)(qn + 256 + j0);
;                     const f32x2 nv2 = *(const LAS f32x2*)(qn + 320 + row0);
;                     f32x2 sa = (S[0] * a4[0] + S[1] * a4[1]) + (S[2] * a4[2] + S[3] * a4[3]);
;                     float sx = sa.x, sy = sa.y; ROW16_SUM4(sx, sy, py0, py1); sa = (f32x2){sx, sy};
;                     if (tt > 0) { yk0 = cgl == tt - 1 ? py0 : yk0; yk1 = cgl == tt - 1 ? py1 : yk1; }
; #pragma unroll
;                     for (int c = 0; c < 4; ++c) { f32x2 t = S[c] - S[c] * o4[c]; t = t + sa * b4[c]; S[c] = t + v2 * k4[c]; }
;                     const f32x2 y = (S[0] * r4[0] + S[1] * r4[1]) + (S[2] * r4[2] + S[3] * r4[3]);
;                     py0 = y.x; py1 = y.y;
;                     r4 = nr4; o4 = no4; k4 = nk4; a4 = na4; b4 = nb4; v2 = nv2;
	v_pk_fma_f32 v[66:67], v[150:151], v[236:237], v[142:143] op_sel_hi:[1,0,1]
	v_pk_fma_f32 v[20:21], v[150:151], v[236:237], v[144:145] op_sel:[0,1,0]
	v_pk_fma_f32 v[68:69], v[150:151], v[238:239], v[146:147] op_sel_hi:[1,0,1]
	v_pk_fma_f32 v[70:71], v[150:151], v[238:239], v[148:149] op_sel:[0,1,0]
	v_pk_mul_f32 v[124:125], v[66:67], v[220:221] op_sel_hi:[1,0]
	v_pk_mul_f32 v[150:151], v[66:67], v[172:173] op_sel_hi:[1,0]
	v_pk_fma_f32 v[142:143], v[66:67], v[164:165], v[66:67] op_sel_hi:[1,0,1] neg_lo:[1,0,0] neg_hi:[1,0,0]
	ds_read_b128 v[212:215], v152 offset:40704
	v_pk_fma_f32 v[124:125], v[20:21], v[220:221], v[124:125] op_sel:[0,1,0]
	v_pk_fma_f32 v[150:151], v[20:21], v[172:173], v[150:151] op_sel:[0,1,0]
	v_pk_fma_f32 v[144:145], v[20:21], v[164:165], v[20:21] op_sel:[0,1,0] neg_lo:[1,0,0] neg_hi:[1,0,0]
	ds_read_b128 v[204:207], v152 offset:40192
	v_pk_fma_f32 v[124:125], v[68:69], v[222:223], v[124:125] op_sel_hi:[1,0,1]
	v_pk_fma_f32 v[150:151], v[68:69], v[174:175], v[150:151] op_sel_hi:[1,0,1]
	v_pk_fma_f32 v[146:147], v[68:69], v[166:167], v[68:69] op_sel_hi:[1,0,1] neg_lo:[1,0,0] neg_hi:[1,0,0]
	ds_read2st64_b64 v[244:247], v153 offset0:80 offset1:83
	v_pk_fma_f32 v[124:125], v[70:71], v[222:223], v[124:125] op_sel:[0,1,0]
	v_pk_fma_f32 v[150:151], v[70:71], v[174:175], v[150:151] op_sel:[0,1,0]
	v_pk_fma_f32 v[148:149], v[70:71], v[166:167], v[70:71] op_sel:[0,1,0] neg_lo:[1,0,0] neg_hi:[1,0,0]
	ds_read_b128 v[208:211], v152 offset:40448
	v_pk_fma_f32 v[142:143], v[240:241], v[168:169], v[142:143] op_sel_hi:[1,0,1]
	v_pk_fma_f32 v[144:145], v[240:241], v[168:169], v[144:145] op_sel:[0,1,0]
	v_add_f32_dpp v150, v150, v150 quad_perm:[1,0,3,2] row_mask:0xf bank_mask:0xf bound_ctrl:1
	v_add_f32_dpp v151, v151, v151 quad_perm:[1,0,3,2] row_mask:0xf bank_mask:0xf bound_ctrl:1
	v_pk_fma_f32 v[146:147], v[240:241], v[170:171], v[146:147] op_sel_hi:[1,0,1]
	v_add_f32_dpp v150, v150, v150 quad_perm:[2,3,0,1] row_mask:0xf bank_mask:0xf bound_ctrl:1
	v_add_f32_dpp v151, v151, v151 quad_perm:[2,3,0,1] row_mask:0xf bank_mask:0xf bound_ctrl:1
	v_pk_fma_f32 v[148:149], v[240:241], v[170:171], v[148:149] op_sel:[0,1,0]
	v_add_f32_dpp v150, v150, v150 row_half_mirror row_mask:0xf bank_mask:0xf bound_ctrl:1
	v_add_f32_dpp v151, v151, v151 row_half_mirror row_mask:0xf bank_mask:0xf bound_ctrl:1
	ds_read_b128 v[232:235], v152 offset:42240
	v_add_f32_dpp v150, v150, v150 row_mirror row_mask:0xf bank_mask:0xf bound_ctrl:1
	v_add_f32_dpp v151, v151, v151 row_mirror row_mask:0xf bank_mask:0xf bound_ctrl:1
	ds_read_b128 v[224:227], v152 offset:41728
	ds_read_b128 v[216:219], v152 offset:40960
	ds_read_b128 v[228:231], v152 offset:41984
	ds_read_b128 v[236:239], v152 offset:42496
	ds_read_b128 v[200:203], v152 offset:39936
	ds_read_b128 v[220:223], v152 offset:41472
	v_pk_fma_f32 v[66:67], v[150:151], v[176:177], v[142:143] op_sel_hi:[1,0,1]
	v_pk_fma_f32 v[20:21], v[150:151], v[176:177], v[144:145] op_sel:[0,1,0]
	v_pk_fma_f32 v[68:69], v[150:151], v[178:179], v[146:147] op_sel_hi:[1,0,1]
	v_pk_fma_f32 v[70:71], v[150:151], v[178:179], v[148:149] op_sel:[0,1,0]
	v_pk_mul_f32 v[126:127], v[66:67], v[160:161] op_sel_hi:[1,0]
	v_pk_mul_f32 v[150:151], v[66:67], v[192:193] op_sel_hi:[1,0]
	v_pk_fma_f32 v[142:143], v[66:67], v[184:185], v[66:67] op_sel_hi:[1,0,1] neg_lo:[1,0,0] neg_hi:[1,0,0]
	v_pk_fma_f32 v[126:127], v[20:21], v[160:161], v[126:127] op_sel:[0,1,0]
	v_pk_fma_f32 v[150:151], v[20:21], v[192:193], v[150:151] op_sel:[0,1,0]
	v_pk_fma_f32 v[144:145], v[20:21], v[184:185], v[20:21] op_sel:[0,1,0] neg_lo:[1,0,0] neg_hi:[1,0,0]
	v_pk_fma_f32 v[126:127], v[68:69], v[162:163], v[126:127] op_sel_hi:[1,0,1]
	v_pk_fma_f32 v[150:151], v[68:69], v[194:195], v[150:151] op_sel_hi:[1,0,1]
	v_pk_fma_f32 v[146:147], v[68:69], v[186:187], v[68:69] op_sel_hi:[1,0,1] neg_lo:[1,0,0] neg_hi:[1,0,0]
	v_pk_fma_f32 v[126:127], v[70:71], v[162:163], v[126:127] op_sel:[0,1,0]
	v_pk_fma_f32 v[150:151], v[70:71], v[194:195], v[150:151] op_sel:[0,1,0]
	v_pk_fma_f32 v[148:149], v[70:71], v[186:187], v[70:71] op_sel:[0,1,0] neg_lo:[1,0,0] neg_hi:[1,0,0]
	v_pk_fma_f32 v[142:143], v[242:243], v[188:189], v[142:143] op_sel_hi:[1,0,1]
	v_pk_fma_f32 v[144:145], v[242:243], v[188:189], v[144:145] op_sel:[0,1,0]
	v_add_f32_dpp v150, v150, v150 quad_perm:[1,0,3,2] row_mask:0xf bank_mask:0xf bound_ctrl:1
	v_add_f32_dpp v151, v151, v151 quad_perm:[1,0,3,2] row_mask:0xf bank_mask:0xf bound_ctrl:1
	v_pk_fma_f32 v[146:147], v[242:243], v[190:191], v[146:147] op_sel_hi:[1,0,1]
	v_add_f32_dpp v150, v150, v150 quad_perm:[2,3,0,1] row_mask:0xf bank_mask:0xf bound_ctrl:1
	v_add_f32_dpp v151, v151, v151 quad_perm:[2,3,0,1] row_mask:0xf bank_mask:0xf bound_ctrl:1
	v_pk_fma_f32 v[148:149], v[242:243], v[190:191], v[148:149] op_sel:[0,1,0]
	v_add_f32_dpp v150, v150, v150 row_half_mirror row_mask:0xf bank_mask:0xf bound_ctrl:1
	v_add_f32_dpp v151, v151, v151 row_half_mirror row_mask:0xf bank_mask:0xf bound_ctrl:1
	s_nop 0
	v_add_f32_dpp v150, v150, v150 row_mirror row_mask:0xf bank_mask:0xf bound_ctrl:1
	v_add_f32_dpp v151, v151, v151 row_mirror row_mask:0xf bank_mask:0xf bound_ctrl:1
	s_waitcnt lgkmcnt(0)
; #define LAS __attribute__((address_space(3)))
; #define ROW16_SUM4(x, y, z, w) do { DPP4(x, y, z, w, "quad_perm:[1,0,3,2]", "s_nop 1"); DPP4(x, y, z, w, "quad_perm:[2,3,0,1]", ""); DPP4(x, y, z, w, "row_half_mirror", ""); DPP4(x, y, z, w, "row_mirror", ""); } while (0)
; template <bool SAMPLE>
; __device__ __forceinline__ void rwkv_unit(PR P, LAS float* lds, const int b, const int h, const int half, const int wv) {
;     ...
;                 for (int tt = 0; tt < GS; ++tt) {
;                     const LAS float* qn = q0 + (tt + 1 < GS ? tt + 1 : tt) * 384;
;                     const f32x4 nr4 = *(const LAS f32x4*)(qn + j0), no4 = *(const LAS f32x4*)(qn + 64 + j0), nk4 = *(const LAS f32x4*)(qn + 128 + j0), na4 = *(const LAS f32x4*)(qn + 192 + j0), nb4 = *(const LAS f32x4*)(qn + 256 + j0);
;                     const f32x2 nv2 = *(const LAS f32x2*)(qn + 320 + row0);
;                     f32x2 sa = (S[0] * a4[0] + S[1] * a4[1]) + (S[2] * a4[2] + S[3] * a4[3]);
;                     float sx = sa.x, sy = sa.y; ROW16_SUM4(sx, sy, py0, py1); sa = (f32x2){sx, sy};
;                     if (tt > 0) { yk0 = cgl == tt - 1 ? py0 : yk0; yk1 = cgl == tt - 1 ? py1 : yk1; }
; #pragma unroll
;                     for (int c = 0; c < 4; ++c) { f32x2 t = S[c] - S[c] * o4[c]; t = t + sa * b4[c]; S[c] = t + v2 * k4[c]; }
;                     const f32x2 y = (S[0] * r4[0] + S[1] * r4[1]) + (S[2] * r4[2] + S[3] * r4[3]);
;                     py0 = y.x; py1 = y.y;
;                     r4 = nr4; o4 = no4; k4 = nk4; a4 = na4; b4 = nb4; v2 = nv2;
	v_pk_fma_f32 v[66:67], v[150:151], v[196:197], v[142:143] op_sel_hi:[1,0,1]
	v_pk_fma_f32 v[20:21], v[150:151], v[196:197], v[144:145] op_sel:[0,1,0]
	v_pk_fma_f32 v[68:69], v[150:151], v[198:199], v[146:147] op_sel_hi:[1,0,1]
	v_pk_fma_f32 v[70:71], v[150:151], v[198:199], v[148:149] op_sel:[0,1,0]
	v_pk_mul_f32 v[128:129], v[66:67], v[180:181] op_sel_hi:[1,0]
	v_pk_mul_f32 v[150:151], v[66:67], v[212:213] op_sel_hi:[1,0]
	v_pk_fma_f32 v[142:143], v[66:67], v[204:205], v[66:67] op_sel_hi:[1,0,1] neg_lo:[1,0,0] neg_hi:[1,0,0]
	ds_read_b128 v[172:175], v152 offset:43776
	v_pk_fma_f32 v[128:129], v[20:21], v[180:181], v[128:129] op_sel:[0,1,0]
	v_pk_fma_f32 v[150:151], v[20:21], v[212:213], v[150:151] op_sel:[0,1,0]
	v_pk_fma_f32 v[144:145], v[20:21], v[204:205], v[20:21] op_sel:[0,1,0] neg_lo:[1,0,0] neg_hi:[1,0,0]
	ds_read_b128 v[164:167], v152 offset:43264
	v_pk_fma_f32 v[128:129], v[68:69], v[182:183], v[128:129] op_sel_hi:[1,0,1]
	v_pk_fma_f32 v[150:151], v[68:69], v[214:215], v[150:151] op_sel_hi:[1,0,1]
	v_pk_fma_f32 v[146:147], v[68:69], v[206:207], v[68:69] op_sel_hi:[1,0,1] neg_lo:[1,0,0] neg_hi:[1,0,0]
	ds_read2st64_b64 v[248:251], v153 offset0:86 offset1:89
	v_pk_fma_f32 v[128:129], v[70:71], v[182:183], v[128:129] op_sel:[0,1,0]
	v_pk_fma_f32 v[150:151], v[70:71], v[214:215], v[150:151] op_sel:[0,1,0]
	v_pk_fma_f32 v[148:149], v[70:71], v[206:207], v[70:71] op_sel:[0,1,0] neg_lo:[1,0,0] neg_hi:[1,0,0]
	ds_read_b128 v[168:171], v152 offset:43520
	v_pk_fma_f32 v[142:143], v[244:245], v[208:209], v[142:143] op_sel_hi:[1,0,1]
	v_pk_fma_f32 v[144:145], v[244:245], v[208:209], v[144:145] op_sel:[0,1,0]
	v_add_f32_dpp v150, v150, v150 quad_perm:[1,0,3,2] row_mask:0xf bank_mask:0xf bound_ctrl:1
	v_add_f32_dpp v151, v151, v151 quad_perm:[1,0,3,2] row_mask:0xf bank_mask:0xf bound_ctrl:1
	v_pk_fma_f32 v[146:147], v[244:245], v[210:211], v[146:147] op_sel_hi:[1,0,1]
	v_add_f32_dpp v150, v150, v150 quad_perm:[2,3,0,1] row_mask:0xf bank_mask:0xf bound_ctrl:1
	v_add_f32_dpp v151, v151, v151 quad_perm:[2,3,0,1] row_mask:0xf bank_mask:0xf bound_ctrl:1
	v_pk_fma_f32 v[148:149], v[244:245], v[210:211], v[148:149] op_sel:[0,1,0]
	v_add_f32_dpp v150, v150, v150 row_half_mirror row_mask:0xf bank_mask:0xf bound_ctrl:1
	v_add_f32_dpp v151, v151, v151 row_half_mirror row_mask:0xf bank_mask:0xf bound_ctrl:1
	ds_read_b128 v[192:195], v152 offset:45312
	v_add_f32_dpp v150, v150, v150 row_mirror row_mask:0xf bank_mask:0xf bound_ctrl:1
	v_add_f32_dpp v151, v151, v151 row_mirror row_mask:0xf bank_mask:0xf bound_ctrl:1
	ds_read_b128 v[184:187], v152 offset:44800
	ds_read_b128 v[176:179], v152 offset:44032
	ds_read_b128 v[188:191], v152 offset:45056
	ds_read_b128 v[196:199], v152 offset:45568
	ds_read_b128 v[160:163], v152 offset:43008
	ds_read_b128 v[180:183], v152 offset:44544
	v_pk_fma_f32 v[66:67], v[150:151], v[216:217], v[142:143] op_sel_hi:[1,0,1]
	v_pk_fma_f32 v[20:21], v[150:151], v[216:217], v[144:145] op_sel:[0,1,0]
	v_pk_fma_f32 v[68:69], v[150:151], v[218:219], v[146:147] op_sel_hi:[1,0,1]
	v_pk_fma_f32 v[70:71], v[150:151], v[218:219], v[148:149] op_sel:[0,1,0]
	v_pk_mul_f32 v[130:131], v[66:67], v[200:201] op_sel_hi:[1,0]
	v_pk_mul_f32 v[150:151], v[66:67], v[232:233] op_sel_hi:[1,0]
	v_pk_fma_f32 v[142:143], v[66:67], v[224:225], v[66:67] op_sel_hi:[1,0,1] neg_lo:[1,0,0] neg_hi:[1,0,0]
	v_pk_fma_f32 v[130:131], v[20:21], v[200:201], v[130:131] op_sel:[0,1,0]
	v_pk_fma_f32 v[150:151], v[20:21], v[232:233], v[150:151] op_sel:[0,1,0]
	v_pk_fma_f32 v[144:145], v[20:21], v[224:225], v[20:21] op_sel:[0,1,0] neg_lo:[1,0,0] neg_hi:[1,0,0]
	v_pk_fma_f32 v[130:131], v[68:69], v[202:203], v[130:131] op_sel_hi:[1,0,1]
	v_pk_fma_f32 v[150:151], v[68:69], v[234:235], v[150:151] op_sel_hi:[1,0,1]
	v_pk_fma_f32 v[146:147], v[68:69], v[226:227], v[68:69] op_sel_hi:[1,0,1] neg_lo:[1,0,0] neg_hi:[1,0,0]
	v_pk_fma_f32 v[130:131], v[70:71], v[202:203], v[130:131] op_sel:[0,1,0]
	v_pk_fma_f32 v[150:151], v[70:71], v[234:235], v[150:151] op_sel:[0,1,0]
	v_pk_fma_f32 v[148:149], v[70:71], v[226:227], v[70:71] op_sel:[0,1,0] neg_lo:[1,0,0] neg_hi:[1,0,0]
	v_pk_fma_f32 v[142:143], v[246:247], v[228:229], v[142:143] op_sel_hi:[1,0,1]
	v_pk_fma_f32 v[144:145], v[246:247], v[228:229], v[144:145] op_sel:[0,1,0]
	v_add_f32_dpp v150, v150, v150 quad_perm:[1,0,3,2] row_mask:0xf bank_mask:0xf bound_ctrl:1
	v_add_f32_dpp v151, v151, v151 quad_perm:[1,0,3,2] row_mask:0xf bank_mask:0xf bound_ctrl:1
	v_pk_fma_f32 v[146:147], v[246:247], v[230:231], v[146:147] op_sel_hi:[1,0,1]
	v_add_f32_dpp v150, v150, v150 quad_perm:[2,3,0,1] row_mask:0xf bank_mask:0xf bound_ctrl:1
	v_add_f32_dpp v151, v151, v151 quad_perm:[2,3,0,1] row_mask:0xf bank_mask:0xf bound_ctrl:1
	v_pk_fma_f32 v[148:149], v[246:247], v[230:231], v[148:149] op_sel:[0,1,0]
	v_add_f32_dpp v150, v150, v150 row_half_mirror row_mask:0xf bank_mask:0xf bound_ctrl:1
	v_add_f32_dpp v151, v151, v151 row_half_mirror row_mask:0xf bank_mask:0xf bound_ctrl:1
	s_nop 0
	v_add_f32_dpp v150, v150, v150 row_mirror row_mask:0xf bank_mask:0xf bound_ctrl:1
	v_add_f32_dpp v151, v151, v151 row_mirror row_mask:0xf bank_mask:0xf bound_ctrl:1
	s_waitcnt lgkmcnt(0)
; #define LAS __attribute__((address_space(3)))
; #define ROW16_SUM4(x, y, z, w) do { DPP4(x, y, z, w, "quad_perm:[1,0,3,2]", "s_nop 1"); DPP4(x, y, z, w, "quad_perm:[2,3,0,1]", ""); DPP4(x, y, z, w, "row_half_mirror", ""); DPP4(x, y, z, w, "row_mirror", ""); } while (0)
; template <bool SAMPLE>
; __device__ __forceinline__ void rwkv_unit(PR P, LAS float* lds, const int b, const int h, const int half, const int wv) {
;     ...
;                 for (int tt = 0; tt < GS; ++tt) {
;                     const LAS float* qn = q0 + (tt + 1 < GS ? tt + 1 : tt) * 384;
;                     const f32x4 nr4 = *(const LAS f32x4*)(qn + j0), no4 = *(const LAS f32x4*)(qn + 64 + j0), nk4 = *(const LAS f32x4*)(qn + 128 + j0), na4 = *(const LAS f32x4*)(qn + 192 + j0), nb4 = *(const LAS f32x4*)(qn + 256 + j0);
;                     const f32x2 nv2 = *(const LAS f32x2*)(qn + 320 + row0);
;                     f32x2 sa = (S[0] * a4[0] + S[1] * a4[1]) + (S[2] * a4[2] + S[3] * a4[3]);
;                     float sx = sa.x, sy = sa.y; ROW16_SUM4(sx, sy, py0, py1); sa = (f32x2){sx, sy};
;                     if (tt > 0) { yk0 = cgl == tt - 1 ? py0 : yk0; yk1 = cgl == tt - 1 ? py1 : yk1; }
; #pragma unroll
;                     for (int c = 0; c < 4; ++c) { f32x2 t = S[c] - S[c] * o4[c]; t = t + sa * b4[c]; S[c] = t + v2 * k4[c]; }
;                     const f32x2 y = (S[0] * r4[0] + S[1] * r4[1]) + (S[2] * r4[2] + S[3] * r4[3]);
;                     py0 = y.x; py1 = y.y;
;                     r4 = nr4; o4 = no4; k4 = nk4; a4 = na4; b4 = nb4; v2 = nv2;
	v_pk_fma_f32 v[66:67], v[150:151], v[236:237], v[142:143] op_sel_hi:[1,0,1]
	v_pk_fma_f32 v[20:21], v[150:151], v[236:237], v[144:145] op_sel:[0,1,0]
	v_pk_fma_f32 v[68:69], v[150:151], v[238:239], v[146:147] op_sel_hi:[1,0,1]
	v_pk_fma_f32 v[70:71], v[150:151], v[238:239], v[148:149] op_sel:[0,1,0]
	v_pk_mul_f32 v[132:133], v[66:67], v[220:221] op_sel_hi:[1,0]
	v_pk_mul_f32 v[150:151], v[66:67], v[172:173] op_sel_hi:[1,0]
	v_pk_fma_f32 v[142:143], v[66:67], v[164:165], v[66:67] op_sel_hi:[1,0,1] neg_lo:[1,0,0] neg_hi:[1,0,0]
	ds_read_b128 v[212:215], v152 offset:46848
	v_pk_fma_f32 v[132:133], v[20:21], v[220:221], v[132:133] op_sel:[0,1,0]
	v_pk_fma_f32 v[150:151], v[20:21], v[172:173], v[150:151] op_sel:[0,1,0]
	v_pk_fma_f32 v[144:145], v[20:21], v[164:165], v[20:21] op_sel:[0,1,0] neg_lo:[1,0,0] neg_hi:[1,0,0]
	ds_read_b128 v[204:207], v152 offset:46336
	v_pk_fma_f32 v[132:133], v[68:69], v[222:223], v[132:133] op_sel_hi:[1,0,1]
	v_pk_fma_f32 v[150:151], v[68:69], v[174:175], v[150:151] op_sel_hi:[1,0,1]
	v_pk_fma_f32 v[146:147], v[68:69], v[166:167], v[68:69] op_sel_hi:[1,0,1] neg_lo:[1,0,0] neg_hi:[1,0,0]
	ds_read2st64_b64 v[240:243], v153 offset0:92 offset1:95
	v_pk_fma_f32 v[132:133], v[70:71], v[222:223], v[132:133] op_sel:[0,1,0]
	v_pk_fma_f32 v[150:151], v[70:71], v[174:175], v[150:151] op_sel:[0,1,0]
	v_pk_fma_f32 v[148:149], v[70:71], v[166:167], v[70:71] op_sel:[0,1,0] neg_lo:[1,0,0] neg_hi:[1,0,0]
	ds_read_b128 v[208:211], v152 offset:46592
	v_pk_fma_f32 v[142:143], v[248:249], v[168:169], v[142:143] op_sel_hi:[1,0,1]
	v_pk_fma_f32 v[144:145], v[248:249], v[168:169], v[144:145] op_sel:[0,1,0]
	v_add_f32_dpp v150, v150, v150 quad_perm:[1,0,3,2] row_mask:0xf bank_mask:0xf bound_ctrl:1
	v_add_f32_dpp v151, v151, v151 quad_perm:[1,0,3,2] row_mask:0xf bank_mask:0xf bound_ctrl:1
	v_pk_fma_f32 v[146:147], v[248:249], v[170:171], v[146:147] op_sel_hi:[1,0,1]
	v_add_f32_dpp v150, v150, v150 quad_perm:[2,3,0,1] row_mask:0xf bank_mask:0xf bound_ctrl:1
	v_add_f32_dpp v151, v151, v151 quad_perm:[2,3,0,1] row_mask:0xf bank_mask:0xf bound_ctrl:1
	v_pk_fma_f32 v[148:149], v[248:249], v[170:171], v[148:149] op_sel:[0,1,0]
	v_add_f32_dpp v150, v150, v150 row_half_mirror row_mask:0xf bank_mask:0xf bound_ctrl:1
	v_add_f32_dpp v151, v151, v151 row_half_mirror row_mask:0xf bank_mask:0xf bound_ctrl:1
	ds_read_b128 v[232:235], v152 offset:48384
	v_add_f32_dpp v150, v150, v150 row_mirror row_mask:0xf bank_mask:0xf bound_ctrl:1
	v_add_f32_dpp v151, v151, v151 row_mirror row_mask:0xf bank_mask:0xf bound_ctrl:1
	ds_read_b128 v[224:227], v152 offset:47872
	ds_read_b128 v[216:219], v152 offset:47104
	ds_read_b128 v[228:231], v152 offset:48128
	ds_read_b128 v[236:239], v152 offset:48640
	ds_read_b128 v[200:203], v152 offset:46080
	ds_read_b128 v[220:223], v152 offset:47616
	v_pk_fma_f32 v[66:67], v[150:151], v[176:177], v[142:143] op_sel_hi:[1,0,1]
	v_pk_fma_f32 v[20:21], v[150:151], v[176:177], v[144:145] op_sel:[0,1,0]
	v_pk_fma_f32 v[68:69], v[150:151], v[178:179], v[146:147] op_sel_hi:[1,0,1]
	v_pk_fma_f32 v[70:71], v[150:151], v[178:179], v[148:149] op_sel:[0,1,0]
	v_pk_mul_f32 v[134:135], v[66:67], v[160:161] op_sel_hi:[1,0]
	v_pk_mul_f32 v[150:151], v[66:67], v[192:193] op_sel_hi:[1,0]
	v_pk_fma_f32 v[142:143], v[66:67], v[184:185], v[66:67] op_sel_hi:[1,0,1] neg_lo:[1,0,0] neg_hi:[1,0,0]
	v_pk_fma_f32 v[134:135], v[20:21], v[160:161], v[134:135] op_sel:[0,1,0]
	v_pk_fma_f32 v[150:151], v[20:21], v[192:193], v[150:151] op_sel:[0,1,0]
	v_pk_fma_f32 v[144:145], v[20:21], v[184:185], v[20:21] op_sel:[0,1,0] neg_lo:[1,0,0] neg_hi:[1,0,0]
	v_pk_fma_f32 v[134:135], v[68:69], v[162:163], v[134:135] op_sel_hi:[1,0,1]
	v_pk_fma_f32 v[150:151], v[68:69], v[194:195], v[150:151] op_sel_hi:[1,0,1]
	v_pk_fma_f32 v[146:147], v[68:69], v[186:187], v[68:69] op_sel_hi:[1,0,1] neg_lo:[1,0,0] neg_hi:[1,0,0]
	v_pk_fma_f32 v[134:135], v[70:71], v[162:163], v[134:135] op_sel:[0,1,0]
	v_pk_fma_f32 v[150:151], v[70:71], v[194:195], v[150:151] op_sel:[0,1,0]
	v_pk_fma_f32 v[148:149], v[70:71], v[186:187], v[70:71] op_sel:[0,1,0] neg_lo:[1,0,0] neg_hi:[1,0,0]
	v_pk_fma_f32 v[142:143], v[250:251], v[188:189], v[142:143] op_sel_hi:[1,0,1]
	v_pk_fma_f32 v[144:145], v[250:251], v[188:189], v[144:145] op_sel:[0,1,0]
	v_add_f32_dpp v150, v150, v150 quad_perm:[1,0,3,2] row_mask:0xf bank_mask:0xf bound_ctrl:1
	v_add_f32_dpp v151, v151, v151 quad_perm:[1,0,3,2] row_mask:0xf bank_mask:0xf bound_ctrl:1
	v_pk_fma_f32 v[146:147], v[250:251], v[190:191], v[146:147] op_sel_hi:[1,0,1]
	v_add_f32_dpp v150, v150, v150 quad_perm:[2,3,0,1] row_mask:0xf bank_mask:0xf bound_ctrl:1
	v_add_f32_dpp v151, v151, v151 quad_perm:[2,3,0,1] row_mask:0xf bank_mask:0xf bound_ctrl:1
	v_pk_fma_f32 v[148:149], v[250:251], v[190:191], v[148:149] op_sel:[0,1,0]
	v_add_f32_dpp v150, v150, v150 row_half_mirror row_mask:0xf bank_mask:0xf bound_ctrl:1
	v_add_f32_dpp v151, v151, v151 row_half_mirror row_mask:0xf bank_mask:0xf bound_ctrl:1
	s_nop 0
	v_add_f32_dpp v150, v150, v150 row_mirror row_mask:0xf bank_mask:0xf bound_ctrl:1
	v_add_f32_dpp v151, v151, v151 row_mirror row_mask:0xf bank_mask:0xf bound_ctrl:1
	s_waitcnt lgkmcnt(0)
; #define LAS __attribute__((address_space(3)))
; #define ROW16_SUM4(x, y, z, w) do { DPP4(x, y, z, w, "quad_perm:[1,0,3,2]", "s_nop 1"); DPP4(x, y, z, w, "quad_perm:[2,3,0,1]", ""); DPP4(x, y, z, w, "row_half_mirror", ""); DPP4(x, y, z, w, "row_mirror", ""); } while (0)
; template <bool SAMPLE>
; __device__ __forceinline__ void rwkv_unit(PR P, LAS float* lds, const int b, const int h, const int half, const int wv) {
;     ...
;                 for (int tt = 0; tt < GS; ++tt) {
;                     const LAS float* qn = q0 + (tt + 1 < GS ? tt + 1 : tt) * 384;
;                     const f32x4 nr4 = *(const LAS f32x4*)(qn + j0), no4 = *(const LAS f32x4*)(qn + 64 + j0), nk4 = *(const LAS f32x4*)(qn + 128 + j0), na4 = *(const LAS f32x4*)(qn + 192 + j0), nb4 = *(const LAS f32x4*)(qn + 256 + j0);
;                     const f32x2 nv2 = *(const LAS f32x2*)(qn + 320 + row0);
;                     f32x2 sa = (S[0] * a4[0] + S[1] * a4[1]) + (S[2] * a4[2] + S[3] * a4[3]);
;                     float sx = sa.x, sy = sa.y; ROW16_SUM4(sx, sy, py0, py1); sa = (f32x2){sx, sy};
;                     if (tt > 0) { yk0 = cgl == tt - 1 ? py0 : yk0; yk1 = cgl == tt - 1 ? py1 : yk1; }
; #pragma unroll
;                     for (int c = 0; c < 4; ++c) { f32x2 t = S[c] - S[c] * o4[c]; t = t + sa * b4[c]; S[c] = t + v2 * k4[c]; }
;                     const f32x2 y = (S[0] * r4[0] + S[1] * r4[1]) + (S[2] * r4[2] + S[3] * r4[3]);
;                     py0 = y.x; py1 = y.y;
;                     r4 = nr4; o4 = no4; k4 = nk4; a4 = na4; b4 = nb4; v2 = nv2;
;                 }
	v_pk_fma_f32 v[66:67], v[150:151], v[196:197], v[142:143] op_sel_hi:[1,0,1]
	v_pk_fma_f32 v[20:21], v[150:151], v[196:197], v[144:145] op_sel:[0,1,0]
	v_pk_fma_f32 v[68:69], v[150:151], v[198:199], v[146:147] op_sel_hi:[1,0,1]
	v_pk_fma_f32 v[70:71], v[150:151], v[198:199], v[148:149] op_sel:[0,1,0]
	v_pk_mul_f32 v[136:137], v[66:67], v[180:181] op_sel_hi:[1,0]
	v_pk_mul_f32 v[150:151], v[66:67], v[212:213] op_sel_hi:[1,0]
	v_pk_fma_f32 v[142:143], v[66:67], v[204:205], v[66:67] op_sel_hi:[1,0,1] neg_lo:[1,0,0] neg_hi:[1,0,0]
	v_pk_fma_f32 v[136:137], v[20:21], v[180:181], v[136:137] op_sel:[0,1,0]
	v_pk_fma_f32 v[150:151], v[20:21], v[212:213], v[150:151] op_sel:[0,1,0]
	v_pk_fma_f32 v[144:145], v[20:21], v[204:205], v[20:21] op_sel:[0,1,0] neg_lo:[1,0,0] neg_hi:[1,0,0]
	v_pk_fma_f32 v[136:137], v[68:69], v[182:183], v[136:137] op_sel_hi:[1,0,1]
	v_pk_fma_f32 v[150:151], v[68:69], v[214:215], v[150:151] op_sel_hi:[1,0,1]
	v_pk_fma_f32 v[146:147], v[68:69], v[206:207], v[68:69] op_sel_hi:[1,0,1] neg_lo:[1,0,0] neg_hi:[1,0,0]
	v_pk_fma_f32 v[136:137], v[70:71], v[182:183], v[136:137] op_sel:[0,1,0]
	v_pk_fma_f32 v[150:151], v[70:71], v[214:215], v[150:151] op_sel:[0,1,0]
	v_pk_fma_f32 v[148:149], v[70:71], v[206:207], v[70:71] op_sel:[0,1,0] neg_lo:[1,0,0] neg_hi:[1,0,0]
	v_pk_fma_f32 v[142:143], v[240:241], v[208:209], v[142:143] op_sel_hi:[1,0,1]
	v_pk_fma_f32 v[144:145], v[240:241], v[208:209], v[144:145] op_sel:[0,1,0]
	v_add_f32_dpp v150, v150, v150 quad_perm:[1,0,3,2] row_mask:0xf bank_mask:0xf bound_ctrl:1
	v_add_f32_dpp v151, v151, v151 quad_perm:[1,0,3,2] row_mask:0xf bank_mask:0xf bound_ctrl:1
	v_pk_fma_f32 v[146:147], v[240:241], v[210:211], v[146:147] op_sel_hi:[1,0,1]
	v_add_f32_dpp v150, v150, v150 quad_perm:[2,3,0,1] row_mask:0xf bank_mask:0xf bound_ctrl:1
	v_add_f32_dpp v151, v151, v151 quad_perm:[2,3,0,1] row_mask:0xf bank_mask:0xf bound_ctrl:1
	v_pk_fma_f32 v[148:149], v[240:241], v[210:211], v[148:149] op_sel:[0,1,0]
	v_add_f32_dpp v150, v150, v150 row_half_mirror row_mask:0xf bank_mask:0xf bound_ctrl:1
	v_add_f32_dpp v151, v151, v151 row_half_mirror row_mask:0xf bank_mask:0xf bound_ctrl:1
	s_nop 0
	v_add_f32_dpp v150, v150, v150 row_mirror row_mask:0xf bank_mask:0xf bound_ctrl:1
	v_add_f32_dpp v151, v151, v151 row_mirror row_mask:0xf bank_mask:0xf bound_ctrl:1
	v_pk_fma_f32 v[66:67], v[150:151], v[216:217], v[142:143] op_sel_hi:[1,0,1]
	v_pk_fma_f32 v[20:21], v[150:151], v[216:217], v[144:145] op_sel:[0,1,0]
	v_pk_fma_f32 v[68:69], v[150:151], v[218:219], v[146:147] op_sel_hi:[1,0,1]
	v_pk_fma_f32 v[70:71], v[150:151], v[218:219], v[148:149] op_sel:[0,1,0]
	v_pk_mul_f32 v[138:139], v[66:67], v[200:201] op_sel_hi:[1,0]
	v_pk_mul_f32 v[150:151], v[66:67], v[232:233] op_sel_hi:[1,0]
	v_pk_fma_f32 v[142:143], v[66:67], v[224:225], v[66:67] op_sel_hi:[1,0,1] neg_lo:[1,0,0] neg_hi:[1,0,0]
	v_pk_fma_f32 v[138:139], v[20:21], v[200:201], v[138:139] op_sel:[0,1,0]
	v_pk_fma_f32 v[150:151], v[20:21], v[232:233], v[150:151] op_sel:[0,1,0]
	v_pk_fma_f32 v[144:145], v[20:21], v[224:225], v[20:21] op_sel:[0,1,0] neg_lo:[1,0,0] neg_hi:[1,0,0]
	v_pk_fma_f32 v[138:139], v[68:69], v[202:203], v[138:139] op_sel_hi:[1,0,1]
	v_pk_fma_f32 v[150:151], v[68:69], v[234:235], v[150:151] op_sel_hi:[1,0,1]
	v_pk_fma_f32 v[146:147], v[68:69], v[226:227], v[68:69] op_sel_hi:[1,0,1] neg_lo:[1,0,0] neg_hi:[1,0,0]
	v_pk_fma_f32 v[138:139], v[70:71], v[202:203], v[138:139] op_sel:[0,1,0]
	v_pk_fma_f32 v[150:151], v[70:71], v[234:235], v[150:151] op_sel:[0,1,0]
	v_pk_fma_f32 v[148:149], v[70:71], v[226:227], v[70:71] op_sel:[0,1,0] neg_lo:[1,0,0] neg_hi:[1,0,0]
	v_pk_fma_f32 v[142:143], v[242:243], v[228:229], v[142:143] op_sel_hi:[1,0,1]
	v_pk_fma_f32 v[144:145], v[242:243], v[228:229], v[144:145] op_sel:[0,1,0]
	v_add_f32_dpp v150, v150, v150 quad_perm:[1,0,3,2] row_mask:0xf bank_mask:0xf bound_ctrl:1
	v_add_f32_dpp v151, v151, v151 quad_perm:[1,0,3,2] row_mask:0xf bank_mask:0xf bound_ctrl:1
	v_pk_fma_f32 v[146:147], v[242:243], v[230:231], v[146:147] op_sel_hi:[1,0,1]
	v_add_f32_dpp v150, v150, v150 quad_perm:[2,3,0,1] row_mask:0xf bank_mask:0xf bound_ctrl:1
	v_add_f32_dpp v151, v151, v151 quad_perm:[2,3,0,1] row_mask:0xf bank_mask:0xf bound_ctrl:1
	v_pk_fma_f32 v[148:149], v[242:243], v[230:231], v[148:149] op_sel:[0,1,0]
	v_add_f32_dpp v150, v150, v150 row_half_mirror row_mask:0xf bank_mask:0xf bound_ctrl:1
	v_add_f32_dpp v151, v151, v151 row_half_mirror row_mask:0xf bank_mask:0xf bound_ctrl:1
	s_nop 0
	v_add_f32_dpp v150, v150, v150 row_mirror row_mask:0xf bank_mask:0xf bound_ctrl:1
	v_add_f32_dpp v151, v151, v151 row_mirror row_mask:0xf bank_mask:0xf bound_ctrl:1
	v_pk_fma_f32 v[66:67], v[150:151], v[236:237], v[142:143] op_sel_hi:[1,0,1]
	v_pk_fma_f32 v[20:21], v[150:151], v[236:237], v[144:145] op_sel:[0,1,0]
	v_pk_fma_f32 v[68:69], v[150:151], v[238:239], v[146:147] op_sel_hi:[1,0,1]
	v_pk_fma_f32 v[70:71], v[150:151], v[238:239], v[148:149] op_sel:[0,1,0]
	v_pk_mul_f32 v[140:141], v[66:67], v[220:221] op_sel_hi:[1,0]
	v_pk_fma_f32 v[140:141], v[20:21], v[220:221], v[140:141] op_sel:[0,1,0]
	v_pk_fma_f32 v[140:141], v[68:69], v[222:223], v[140:141] op_sel_hi:[1,0,1]
	v_pk_fma_f32 v[140:141], v[70:71], v[222:223], v[140:141] op_sel:[0,1,0]
	s_branch .LBB0_704

; __device__ __forceinline__ unsigned cvt_pk_bf16(float lo, float hi) { const f32x2_t v = {lo, hi}; const bf16x2_t b = __builtin_convertvector(v, bf16x2_t); return __builtin_bit_cast(unsigned, b); }
; #define ROW16_SUM2(x, y) do { DPP2(x, y, "quad_perm:[1,0,3,2]", "s_nop 1"); DPP2(x, y, "quad_perm:[2,3,0,1]", "s_nop 0"); DPP2(x, y, "row_half_mirror", "s_nop 0"); DPP2(x, y, "row_mirror", "s_nop 0"); } while (0)
; template <bool SAMPLE>
; __device__ __forceinline__ void rwkv_unit(PR P, LAS float* lds, const int b, const int h, const int half, const int wv) {
;     ...
;                 ROW16_SUM2(py0, py1); yk0 = cgl == GS - 1 ? py0 : yk0; yk1 = cgl == GS - 1 ? py1 : yk1;
;                 if (cgl < GS) *(unsigned*)(YS + (size_t)(row_base + c * TC + g * GS + cgl) * 512 + h * 64 + row0) = pg8::cvt_pk_bf16(yk0, yk1);
;     ...
;     if (wid < 4) { *(float4*)sout = make_float4(S[0].x, S[1].x, S[2].x, S[3].x); *(float4*)(sout + 64) = make_float4(S[0].y, S[1].y, S[2].y, S[3].y); }
.LBB0_723:
	s_and_saveexec_b64 s[10:11], s[8:9]
	s_cbranch_execz .LBB0_725
	v_add_f32_dpp v110, v110, v110 row_ror:8 row_mask:0xf bank_mask:0x3 bound_ctrl:1
	v_add_f32_dpp v110, v126, v126 row_ror:8 row_mask:0xf bank_mask:0xc bound_ctrl:1
	v_add_f32_dpp v112, v112, v112 row_ror:8 row_mask:0xf bank_mask:0x3 bound_ctrl:1
	v_add_f32_dpp v112, v128, v128 row_ror:8 row_mask:0xf bank_mask:0xc bound_ctrl:1
	v_add_f32_dpp v114, v114, v114 row_ror:8 row_mask:0xf bank_mask:0x3 bound_ctrl:1
	v_add_f32_dpp v114, v130, v130 row_ror:8 row_mask:0xf bank_mask:0xc bound_ctrl:1
	v_add_f32_dpp v116, v116, v116 row_ror:8 row_mask:0xf bank_mask:0x3 bound_ctrl:1
	v_add_f32_dpp v116, v132, v132 row_ror:8 row_mask:0xf bank_mask:0xc bound_ctrl:1
	v_add_f32_dpp v118, v118, v118 row_ror:8 row_mask:0xf bank_mask:0x3 bound_ctrl:1
	v_add_f32_dpp v118, v134, v134 row_ror:8 row_mask:0xf bank_mask:0xc bound_ctrl:1
	v_add_f32_dpp v120, v120, v120 row_ror:8 row_mask:0xf bank_mask:0x3 bound_ctrl:1
	v_add_f32_dpp v120, v136, v136 row_ror:8 row_mask:0xf bank_mask:0xc bound_ctrl:1
	v_add_f32_dpp v122, v122, v122 row_ror:8 row_mask:0xf bank_mask:0x3 bound_ctrl:1
	v_add_f32_dpp v122, v138, v138 row_ror:8 row_mask:0xf bank_mask:0xc bound_ctrl:1
	v_add_f32_dpp v124, v124, v124 row_ror:8 row_mask:0xf bank_mask:0x3 bound_ctrl:1
	v_add_f32_dpp v124, v140, v140 row_ror:8 row_mask:0xf bank_mask:0xc bound_ctrl:1
	v_add_f32_dpp v111, v111, v111 row_ror:8 row_mask:0xf bank_mask:0x3 bound_ctrl:1
	v_add_f32_dpp v111, v127, v127 row_ror:8 row_mask:0xf bank_mask:0xc bound_ctrl:1
	v_add_f32_dpp v113, v113, v113 row_ror:8 row_mask:0xf bank_mask:0x3 bound_ctrl:1
	v_add_f32_dpp v113, v129, v129 row_ror:8 row_mask:0xf bank_mask:0xc bound_ctrl:1
	v_add_f32_dpp v115, v115, v115 row_ror:8 row_mask:0xf bank_mask:0x3 bound_ctrl:1
	v_add_f32_dpp v115, v131, v131 row_ror:8 row_mask:0xf bank_mask:0xc bound_ctrl:1
	v_add_f32_dpp v117, v117, v117 row_ror:8 row_mask:0xf bank_mask:0x3 bound_ctrl:1
	v_add_f32_dpp v117, v133, v133 row_ror:8 row_mask:0xf bank_mask:0xc bound_ctrl:1
	v_add_f32_dpp v119, v119, v119 row_ror:8 row_mask:0xf bank_mask:0x3 bound_ctrl:1
	v_add_f32_dpp v119, v135, v135 row_ror:8 row_mask:0xf bank_mask:0xc bound_ctrl:1
	v_add_f32_dpp v121, v121, v121 row_ror:8 row_mask:0xf bank_mask:0x3 bound_ctrl:1
	v_add_f32_dpp v121, v137, v137 row_ror:8 row_mask:0xf bank_mask:0xc bound_ctrl:1
	v_add_f32_dpp v123, v123, v123 row_ror:8 row_mask:0xf bank_mask:0x3 bound_ctrl:1
	v_add_f32_dpp v123, v139, v139 row_ror:8 row_mask:0xf bank_mask:0xc bound_ctrl:1
	v_add_f32_dpp v125, v125, v125 row_ror:8 row_mask:0xf bank_mask:0x3 bound_ctrl:1
	v_add_f32_dpp v125, v141, v141 row_ror:8 row_mask:0xf bank_mask:0xc bound_ctrl:1
	v_add_f32_dpp v110, v110, v110 row_shl:4 row_mask:0xf bank_mask:0x5 bound_ctrl:1
	v_add_f32_dpp v110, v118, v118 row_shr:4 row_mask:0xf bank_mask:0xa bound_ctrl:1
	v_add_f32_dpp v112, v112, v112 row_shl:4 row_mask:0xf bank_mask:0x5 bound_ctrl:1
	v_add_f32_dpp v112, v120, v120 row_shr:4 row_mask:0xf bank_mask:0xa bound_ctrl:1
	v_add_f32_dpp v114, v114, v114 row_shl:4 row_mask:0xf bank_mask:0x5 bound_ctrl:1
	v_add_f32_dpp v114, v122, v122 row_shr:4 row_mask:0xf bank_mask:0xa bound_ctrl:1
	v_add_f32_dpp v116, v116, v116 row_shl:4 row_mask:0xf bank_mask:0x5 bound_ctrl:1
	v_add_f32_dpp v116, v124, v124 row_shr:4 row_mask:0xf bank_mask:0xa bound_ctrl:1
	v_add_f32_dpp v111, v111, v111 row_shl:4 row_mask:0xf bank_mask:0x5 bound_ctrl:1
	v_add_f32_dpp v111, v119, v119 row_shr:4 row_mask:0xf bank_mask:0xa bound_ctrl:1
	v_add_f32_dpp v113, v113, v113 row_shl:4 row_mask:0xf bank_mask:0x5 bound_ctrl:1
	v_add_f32_dpp v113, v121, v121 row_shr:4 row_mask:0xf bank_mask:0xa bound_ctrl:1
	v_add_f32_dpp v115, v115, v115 row_shl:4 row_mask:0xf bank_mask:0x5 bound_ctrl:1
	v_add_f32_dpp v115, v123, v123 row_shr:4 row_mask:0xf bank_mask:0xa bound_ctrl:1
	v_add_f32_dpp v117, v117, v117 row_shl:4 row_mask:0xf bank_mask:0x5 bound_ctrl:1
	v_add_f32_dpp v117, v125, v125 row_shr:4 row_mask:0xf bank_mask:0xa bound_ctrl:1
	v_add_f32_dpp v110, v110, v110 quad_perm:[1,0,3,2] row_mask:0xf bank_mask:0xf bound_ctrl:1
	v_add_f32_dpp v112, v112, v112 quad_perm:[1,0,3,2] row_mask:0xf bank_mask:0xf bound_ctrl:1
	v_add_f32_dpp v114, v114, v114 quad_perm:[1,0,3,2] row_mask:0xf bank_mask:0xf bound_ctrl:1
	v_add_f32_dpp v116, v116, v116 quad_perm:[1,0,3,2] row_mask:0xf bank_mask:0xf bound_ctrl:1
	v_add_f32_dpp v111, v111, v111 quad_perm:[1,0,3,2] row_mask:0xf bank_mask:0xf bound_ctrl:1
	v_add_f32_dpp v113, v113, v113 quad_perm:[1,0,3,2] row_mask:0xf bank_mask:0xf bound_ctrl:1
	v_add_f32_dpp v115, v115, v115 quad_perm:[1,0,3,2] row_mask:0xf bank_mask:0xf bound_ctrl:1
	v_add_f32_dpp v117, v117, v117 quad_perm:[1,0,3,2] row_mask:0xf bank_mask:0xf bound_ctrl:1
	v_add_f32_dpp v110, v110, v110 quad_perm:[2,3,0,1] row_mask:0xf bank_mask:0xf bound_ctrl:1
	v_add_f32_dpp v112, v112, v112 quad_perm:[2,3,0,1] row_mask:0xf bank_mask:0xf bound_ctrl:1
	v_add_f32_dpp v114, v114, v114 quad_perm:[2,3,0,1] row_mask:0xf bank_mask:0xf bound_ctrl:1
	v_add_f32_dpp v116, v116, v116 quad_perm:[2,3,0,1] row_mask:0xf bank_mask:0xf bound_ctrl:1
	v_add_f32_dpp v111, v111, v111 quad_perm:[2,3,0,1] row_mask:0xf bank_mask:0xf bound_ctrl:1
	v_add_f32_dpp v113, v113, v113 quad_perm:[2,3,0,1] row_mask:0xf bank_mask:0xf bound_ctrl:1
	v_add_f32_dpp v115, v115, v115 quad_perm:[2,3,0,1] row_mask:0xf bank_mask:0xf bound_ctrl:1
	v_add_f32_dpp v117, v117, v117 quad_perm:[2,3,0,1] row_mask:0xf bank_mask:0xf bound_ctrl:1
	v_add_u32_e32 v72, 16, v57
	v_ashrrev_i32_e32 v73, 31, v72
	v_lshlrev_b64 v[72:73], 10, v[72:73]
	v_lshl_add_u64 v[72:73], v[64:65], 0, v[72:73]
	v_cndmask_b32_e64 v154, v116, v114, s[16:17]
	v_cndmask_b32_e64 v155, v117, v115, s[16:17]
	v_cndmask_b32_e64 v154, v154, v112, s[14:15]
	v_cndmask_b32_e64 v155, v155, v113, s[14:15]
	v_cndmask_b32_e64 v154, v154, v110, s[12:13]
	v_cndmask_b32_e64 v155, v155, v111, s[12:13]
	v_cvt_pk_bf16_f32 v154, v154, v155
	global_store_dword v[72:73], v154, off
	s_lshl_b32 s5, s5, 3
	s_or_b32 s4, s5, s4
	s_ashr_i32 s5, s4, 31
	s_lshl_b64 s[4:5], s[4:5], 14
	s_add_u32 s4, s44, s4
	s_addc_u32 s5, s45, s5
	s_waitcnt vmcnt(4)
	v_lshlrev_b32_e32 v0, 8, v54
	v_mov_b32_e32 v1, 0
	v_lshl_add_u64 v[2:3], s[4:5], 0, v[0:1]
	v_lshlrev_b32_e32 v0, 2, v76
	s_waitcnt vmcnt(3)
	v_lshl_add_u64 v[4:5], v[2:3], 0, v[0:1]
	s_mov_b64 s[4:5], 0x4208000
	v_lshl_add_u64 v[6:7], v[4:5], 0, s[4:5]
	v_add_co_u32_e32 v4, vcc, 0x4208000, v4
	v_mov_b32_e32 v0, v66
	v_mov_b32_e32 v1, v20
	v_mov_b32_e32 v2, v68
	v_mov_b32_e32 v3, v70
	v_addc_co_u32_e32 v5, vcc, 0, v5, vcc
	v_mov_b32_e32 v20, v67
	v_mov_b32_e32 v22, v69
	v_mov_b32_e32 v23, v71
	global_store_dwordx4 v[4:5], v[0:3], off
	global_store_dwordx4 v[6:7], v[20:23], off offset:256

; #define PH(k) if ((PHM >> (k)) & 1)
; __device__ __forceinline__ void tconv_list(const float* wg, const float* wu, const float* wd, const float* win, const float* wout, unsigned char* ws, const int ntiles, LAS float* t, const int wv) {
;     ...
;     int i = blockIdx.x;
;     if (i < ntiles) { const TDesc d = tconv_desc(wg, wu, wd, win, wout, ws, i);
; #pragma unroll
;         for (int e = 0; e < 8; ++e) { const int idx = e * 512 + tid, r = idx >> 6, c = idx & 63; cur[e] = __builtin_nontemporal_load(d.W + (size_t)(d.k0 + r) * d.N + d.n0 + c); } }
;     for (; i < ntiles; i += G) {
; __global__ void __launch_bounds__(512, 2) hymba_mega(Params P_unused) {
;     ...
;     PH(10) { tconv_list(P.f2g, P.f2u, P.f2d, nullptr, nullptr, ws, 2112, ldsf, wv);
;     rows_phase(P, 2, ldsf, wv); }
.LBB0_899:
	s_or_b64 exec, exec, s[0:1]
	s_waitcnt lgkmcnt(0)
	s_barrier
	s_load_dwordx2 s[12:13], s[38:39], 0xd8
	s_cmpk_lt_i32 s2, 0x0
	v_mbcnt_lo_u32_b32 v2, -1, 0
	v_mbcnt_hi_u32_b32 v2, -1, v2
	s_cbranch_scc0 .LBB0_928
	s_load_dwordx4 s[8:11], s[38:39], 0xb8
	s_load_dwordx2 s[0:1], s[38:39], 0xc8
	v_readlane_b32 s4, v254, 1
	v_readlane_b32 s5, v254, 2
	s_and_b64 vcc, exec, s[4:5]
	s_cbranch_vccnz .LBB0_902
	v_readlane_b32 s4, v254, 3
	v_readlane_b32 s5, v254, 4
	s_and_b64 s[4:5], s[4:5], exec
	v_readlane_b32 s4, v254, 0
	v_readlane_b32 s5, v254, 5
	s_cselect_b32 s14, s4, s5
	s_movk_i32 s4, 0xb00
	s_waitcnt lgkmcnt(0)
	s_cselect_b32 s7, s11, s1
	s_cselect_b32 s6, s10, s0
	s_cselect_b32 s5, 16, 44
	s_cselect_b32 s4, s4, 0x400
	s_branch .LBB0_903

; __device__ __forceinline__ int fresh_tid(int wv) { int l; asm volatile("v_mbcnt_lo_u32_b32 %0, -1, 0\n\tv_mbcnt_hi_u32_b32 %0, -1, %0" : "=v"(l)); return wv * 64 + l; }
; #define PG8_LAS __attribute__((address_space(3)))
; #define PH(k) if ((PHM >> (k)) & 1)
; template <class Epi, class Sched>
; __device__ __forceinline__ void gemm_phase(PG8_LAS unsigned char* lds, const Gemm g, const Sched& S, const Epi& E, const int wv) {
;     const int tid = fresh_tid(wv), wid = __builtin_amdgcn_readfirstlane(tid >> 6), lane = tid & 63, wr = wid >> 2, wc = wid & 3, fr = lane & 15, fq = lane >> 4;
;     const int K = g.K;
; __global__ void __launch_bounds__(512, 2) hymba_mega(Params P_unused) {
;     ...
;     PH(11) { pg8::Gemm g{XN, (const bf16_t*)(ws + WS_WGU), MT, NGU, 1024}; S.init(MT, NGU, G, bx, 1024); pg8::EpiSwiGLU E{ACT, DFF}; pg8::gemm_phase(lds, g, S, E, wv); }
.LBB0_993:
	s_or_b64 exec, exec, s[0:1]
	s_waitcnt lgkmcnt(0)
	s_barrier
	s_load_dwordx2 s[8:9], s[38:39], 0xd8
	s_load_dwordx2 s[98:99], s[38:39], 0xd0
	v_mbcnt_lo_u32_b32 v8, -1, 0
	v_mbcnt_hi_u32_b32 v8, -1, v8
	s_and_b64 vcc, exec, s[96:97]
	v_add_u32_e32 v0, s33, v8
	s_nop 0
	v_readfirstlane_b32 s28, v0
	s_cbranch_vccz .LBB0_1013
	s_cmp_gt_i32 s83, 3
	s_cbranch_scc0 .LBB0_996
	s_mul_i32 s0, s83, 0xb5
	s_add_i32 s4, s0, 4
	s_cbranch_execz .LBB0_997
	s_branch .LBB0_998

; #define PG8_STAGE(bufoff, gbase, voff) do { _Pragma("unroll") for (int _i = 0; _i < 2; ++_i) \
;         __builtin_amdgcn_global_load_lds((const unsigned*)((const char*)(gbase) + (voff)[_i]), (PG8_LAS unsigned*)(lds + (bufoff) + ldsw + _i * 8192), 16, 0, 0); } while (0)
; #define PG8_WAIT_V(n) asm volatile("s_waitcnt vmcnt(" #n ")" ::: "memory")
; #define PG8_BAR __builtin_amdgcn_s_barrier()
; template <class Epi, class Sched>
; __device__ __forceinline__ void gemm_phase(PG8_LAS unsigned char* lds, const Gemm g, const Sched& S, const Epi& E, const int wv) {
;     ...
;     for (int i = 0; i < 2; ++i) { int R, C; stage_rc(tid * 16 + i * 8192, R, C); const int Rb = Epi::PERM ? ((R & ~31) + perm32(R & 31)) : R;
;         voffA[i] = (unsigned)(R * K + C) * 2u; voffB[i] = (unsigned)(Rb * K + C) * 2u; }
;     const size_t kstep = (size_t)(BK * 2);
;     const size_t hstep = (size_t)HALF * K * 2;
;     const size_t tstep = 2 * hstep;
;     const unsigned ldsw = (unsigned)wid * 1024u;
;     const int aoff = lds_byte(wr * 64 + fr, fq * 8), boff = lds_byte(wc * 32 + fr, fq * 8);
;     ...
;     const char* cA = (const char*)g.A + (size_t)cur.pm * tstep + (size_t)cur.k0 * kstep; const char* cB = (const char*)g.Bt + (size_t)cur.pn * tstep + (size_t)cur.k0 * kstep;
;     S.a_ready(cur);
;     PG8_STAGE(PG8_SB(0, 0), cB, voffB); PG8_STAGE(PG8_SA(0, 0), cA, voffA); PG8_STAGE(PG8_SB(0, 1), cB + hstep, voffB); PG8_STAGE(PG8_SA(0, 1), cA + hstep, voffA);
;     if (wr == 1) PG8_BAR;
;     PG8_WAIT_V(4); PG8_BAR;
;     PG8_STAGE(PG8_SB(1, 0), cB + kstep, voffB); PG8_STAGE(PG8_SA(1, 0), cA + kstep, voffA); PG8_STAGE(PG8_SB(1, 1), cB + hstep + kstep, voffB);
;     PG8_WAIT_V(6); PG8_BAR;
.LBB0_998:
	v_ashrrev_i32_e32 v2, 31, v0
	v_lshrrev_b32_e32 v2, 26, v2
	v_lshlrev_b32_e32 v1, 4, v0
	v_add_u32_e32 v2, v0, v2
	v_bfe_i32 v0, v0, 27, 1
	v_lshrrev_b32_e32 v0, 22, v0
	v_add_u32_e32 v0, v1, v0
	v_and_b32_e32 v0, 0xfffffc00, v0
	v_sub_u32_e32 v0, v1, v0
	v_ashrrev_i32_e32 v9, 6, v2
	v_lshrrev_b32_e32 v2, 4, v0
	v_bitop3_b32 v0, v2, v0, 32 bitop3:0x6c
	v_ashrrev_i32_e32 v3, 31, v0
	v_lshrrev_b32_e32 v3, 26, v3
	v_add_u32_e32 v3, v0, v3
	v_lshlrev_b32_e32 v2, 3, v9
	v_ashrrev_i32_e32 v10, 6, v3
	v_and_b32_e32 v3, 0xc0, v3
	v_and_b32_e32 v2, -16, v2
	v_sub_u32_e32 v0, v0, v3
	v_mov_b32_e32 v3, 1
	v_add_u32_e32 v2, v10, v2
	v_ashrrev_i16_sdwa v0, v3, sext(v0) dst_sel:DWORD dst_unused:UNUSED_PAD src0_sel:DWORD src1_sel:BYTE_0
	v_lshlrev_b32_e32 v4, 5, v9
	v_bfe_i32 v11, v0, 0, 16
	v_lshlrev_b32_e32 v0, 1, v2
	v_lshrrev_b32_e32 v5, 2, v2
	v_and_b32_e32 v6, 3, v10
	s_mov_b32 s0, 0x1fffe0
	v_and_b32_e32 v4, 32, v4
	v_and_b32_e32 v0, 24, v0
	v_and_b32_e32 v5, 4, v5
	v_and_or_b32 v6, v2, s0, v6
	v_or3_b32 v0, v6, v5, v0
	v_add_lshl_u32 v4, v4, v11, 1
	v_lshl_add_u32 v130, v0, 11, v4
	v_add_u32_e32 v0, 0x2000, v1
	v_ashrrev_i32_e32 v1, 31, v0
	v_lshrrev_b32_e32 v1, 22, v1
	v_add_u32_e32 v1, v0, v1
	v_ashrrev_i32_e32 v12, 10, v1
	v_mul_i32_i24_e32 v1, 0x400, v12
	v_sub_u32_e32 v0, v0, v1
	v_lshrrev_b32_e32 v1, 4, v0
	v_bitop3_b32 v0, v1, v0, 32 bitop3:0x6c
	v_lshl_add_u32 v128, v2, 11, v4
	v_ashrrev_i32_e32 v2, 31, v0
	v_lshrrev_b32_e32 v2, 26, v2
	v_add_u32_e32 v2, v0, v2
	s_waitcnt lgkmcnt(0)
	s_add_u32 s29, s8, 0x1bc4800
	v_lshlrev_b32_e32 v1, 3, v12
	v_ashrrev_i32_e32 v13, 6, v2
	v_and_b32_e32 v2, 0xc0, v2
	s_addc_u32 s30, s9, 0
	v_and_b32_e32 v1, -16, v1
	v_sub_u32_e32 v0, v0, v2
	s_add_u32 s31, s98, 0x2100000
	v_add_u32_e32 v1, v13, v1
	v_ashrrev_i16_sdwa v0, v3, sext(v0) dst_sel:DWORD dst_unused:UNUSED_PAD src0_sel:DWORD src1_sel:BYTE_0
	v_and_b32_e32 v3, 3, v13
	s_addc_u32 s34, s99, 0
	v_and_or_b32 v3, v1, s0, v3
	s_add_i32 s0, s4, s75
	s_mul_hi_i32 s4, s0, 0x2e8ba2e9
	s_lshr_b32 s6, s4, 31
	s_ashr_i32 s4, s4, 4
	s_add_i32 s4, s4, s6
	v_lshlrev_b32_e32 v4, 5, v12
	v_bfe_i32 v14, v0, 0, 16
	v_lshlrev_b32_e32 v0, 1, v1
	v_lshrrev_b32_e32 v2, 2, v1
	s_lshl_b32 s10, s4, 2
	v_and_b32_e32 v4, 32, v4
	v_and_b32_e32 v0, 24, v0
	v_and_b32_e32 v2, 4, v2
	s_sub_i32 s6, 0x42, s10
	v_or3_b32 v0, v3, v2, v0
	v_add_lshl_u32 v2, v4, v14, 1
	s_min_u32 s11, s6, 4
	s_mulk_i32 s4, 0x58
	v_lshl_add_u32 v132, v1, 11, v2
	s_sub_i32 s4, s0, s4
	v_cvt_f32_ubyte0_e32 v1, s11
	v_lshl_add_u32 v134, v0, 11, v2
	v_cvt_f32_i32_e32 v0, s4
	v_rcp_iflag_f32_e32 v2, v1
	s_ashr_i32 s5, s28, 6
	s_ashr_i32 s0, s4, 30
	s_ashr_i32 s1, s28, 8
	v_mul_f32_e32 v2, v0, v2
	v_trunc_f32_e32 v2, v2
	v_fma_f32 v0, -v2, v1, v0
	v_cvt_i32_f32_e32 v2, v2
	s_lshl_b32 s35, s5, 10
	s_or_b32 s0, s0, 1
	v_cmp_ge_f32_e64 s[6:7], |v0|, v1
	s_and_b64 s[6:7], s[6:7], exec
	s_cselect_b32 s0, s0, 0
	v_readfirstlane_b32 s6, v2
	s_add_i32 s0, s6, s0
	s_mul_i32 s6, s0, s11
	s_sub_i32 s4, s4, s6
	s_sext_i32_i8 s4, s4
	s_add_i32 s20, s10, s4
	s_ashr_i32 s21, s20, 31
	s_bfe_i64 s[10:11], s[0:1], 0x80000
	s_lshl_b64 s[6:7], s[20:21], 19
	s_lshl_b64 s[10:11], s[10:11], 19
	s_add_u32 s24, s31, s10
	s_addc_u32 s25, s34, s11
	s_add_i32 s21, s35, 0
	s_add_i32 m0, s21, 0x10000
	v_mov_b32_e32 v131, 0
	global_load_lds_dwordx4 v130, s[24:25]
	s_add_i32 m0, s21, 0x12000
	s_add_u32 s22, s29, s6
	global_load_lds_dwordx4 v134, s[24:25]
	s_addc_u32 s23, s30, s7
	s_mov_b32 m0, s21
	s_add_i32 s36, s21, 0x2000
	global_load_lds_dwordx4 v128, s[22:23]
	s_mov_b32 m0, s36
	s_add_u32 s6, s24, 0x40000
	global_load_lds_dwordx4 v132, s[22:23]
	s_addc_u32 s7, s25, 0
	s_add_i32 m0, s21, 0x14000
	v_mov_b32_e32 v135, v131
	global_load_lds_dwordx4 v130, s[6:7]
	s_add_i32 m0, s21, 0x16000
	v_mov_b32_e32 v129, v131
	global_load_lds_dwordx4 v134, s[6:7]
	s_add_u32 s6, s22, 0x40000
	s_addc_u32 s7, s23, 0
	s_add_i32 s37, s21, 0x4000
	s_mov_b32 m0, s37
	s_add_i32 s40, s21, 0x6000
	global_load_lds_dwordx4 v128, s[6:7]
	s_mov_b32 m0, s40
	v_mov_b32_e32 v133, v131
	global_load_lds_dwordx4 v132, s[6:7]
	s_mov_b32 s41, 0
	v_lshl_add_u64 v[6:7], s[24:25], 0, v[130:131]
	v_lshl_add_u64 v[4:5], s[24:25], 0, v[134:135]
	v_lshl_add_u64 v[2:3], s[22:23], 0, v[128:129]
	s_cmp_lg_u32 s1, 1
	v_lshl_add_u64 v[0:1], s[22:23], 0, v[132:133]
	s_cbranch_scc1 .LBB0_1000
	s_barrier

; __global__ void __launch_bounds__(512, 2) hymba_mega(Params P_unused) {
	.amdhsa_kernel _Z10hymba_mega6Params
		.amdhsa_group_segment_fixed_size 0
		.amdhsa_private_segment_fixed_size 0
		.amdhsa_kernarg_size 480
		.amdhsa_user_sgpr_count 2
		.amdhsa_user_sgpr_dispatch_ptr 0
		.amdhsa_user_sgpr_queue_ptr 0
		.amdhsa_user_sgpr_kernarg_segment_ptr 1
		.amdhsa_user_sgpr_dispatch_id 0
		.amdhsa_user_sgpr_kernarg_preload_length 0
		.amdhsa_user_sgpr_kernarg_preload_offset 0
		.amdhsa_user_sgpr_private_segment_size 0
		.amdhsa_uses_dynamic_stack 0
		.amdhsa_enable_private_segment 0
		.amdhsa_system_sgpr_workgroup_id_x 1
		.amdhsa_system_sgpr_workgroup_id_y 0
		.amdhsa_system_sgpr_workgroup_id_z 0
		.amdhsa_system_sgpr_workgroup_info 0
		.amdhsa_system_vgpr_workitem_id 2
		.amdhsa_next_free_vgpr 255
		.amdhsa_next_free_sgpr 100
		.amdhsa_accum_offset 256
		.amdhsa_reserve_vcc 1
		.amdhsa_float_round_mode_32 0
		.amdhsa_float_round_mode_16_64 0
		.amdhsa_float_denorm_mode_32 3
		.amdhsa_float_denorm_mode_16_64 3
		.amdhsa_dx10_clamp 1
		.amdhsa_ieee_mode 1
		.amdhsa_fp16_overflow 0
		.amdhsa_tg_split 0
		.amdhsa_exception_fp_ieee_invalid_op 0
		.amdhsa_exception_fp_denorm_src 0
		.amdhsa_exception_fp_ieee_div_zero 0
		.amdhsa_exception_fp_ieee_overflow 0
		.amdhsa_exception_fp_ieee_underflow 0
		.amdhsa_exception_fp_ieee_inexact 0
		.amdhsa_exception_int_div_zero 0
	.end_amdhsa_kernel

; __global__ void __launch_bounds__(512, 2) hymba_mega(Params P_unused) {
amdhsa.kernels:
  - .agpr_count:     0
    .args:
      - .offset:         0
        .size:           224
        .value_kind:     by_value
      - .offset:         224
        .size:           4
        .value_kind:     hidden_block_count_x
      - .offset:         228
        .size:           4
        .value_kind:     hidden_block_count_y
      - .offset:         232
        .size:           4
        .value_kind:     hidden_block_count_z
      - .offset:         236
        .size:           2
        .value_kind:     hidden_group_size_x
      - .offset:         238
        .size:           2
        .value_kind:     hidden_group_size_y
      - .offset:         240
        .size:           2
        .value_kind:     hidden_group_size_z
      - .offset:         242
        .size:           2
        .value_kind:     hidden_remainder_x
      - .offset:         244
        .size:           2
        .value_kind:     hidden_remainder_y
      - .offset:         246
        .size:           2
        .value_kind:     hidden_remainder_z
      - .offset:         264
        .size:           8
        .value_kind:     hidden_global_offset_x
      - .offset:         272
        .size:           8
        .value_kind:     hidden_global_offset_y
      - .offset:         280
        .size:           8
        .value_kind:     hidden_global_offset_z
      - .offset:         288
        .size:           2
        .value_kind:     hidden_grid_dims
      - .offset:         312
        .size:           8
        .value_kind:     hidden_multigrid_sync_arg
      - .offset:         344
        .size:           4
        .value_kind:     hidden_dynamic_lds_size
    .group_segment_fixed_size: 0
    .kernarg_segment_align: 8
    .kernarg_segment_size: 480
    .language:       OpenCL C
    .language_version:
      - 2
      - 0
    .max_flat_workgroup_size: 512
    .name:           _Z10hymba_mega6Params
    .private_segment_fixed_size: 0
    .sgpr_count:     106
    .sgpr_spill_count: 18
    .symbol:         _Z10hymba_mega6Params.kd
    .uniform_work_group_size: 1
    .uses_dynamic_stack: false
    .vgpr_count:     255
    .vgpr_spill_count: 0
    .wavefront_size: 64
